# GEMM K-loops: hipcc's per-phase s_setprio 1/0 flips deleted (A/B of the flips)
# speedup vs baseline: 1.0138x; 1.0132x over previous
; #define PG8_STAGE(bufoff, gbase, voff) do { _Pragma("unroll") for (int _i = 0; _i < 2; ++_i) \
;     __builtin_amdgcn_global_load_lds((const unsigned*)((const char*)(gbase) + (voff)[_i]), (PG8_LAS unsigned*)(lds + (bufoff) + ldsw + _i * 8192), 16, 0, 0); } while (0)
; #define PG8_LDA(dst, b, h) do { _Pragma("unroll") for (int m = 0; m < 4; ++m) _Pragma("unroll") for (int k = 0; k < 2; ++k) dst[m][k] = *(const PG8_LAS bf16x8*)(lds + PG8_SA(b, h) + aoff + m * 2048 + k * 1024); } while (0)
; #define PG8_LDB(dst, b, h) do { _Pragma("unroll") for (int n = 0; n < 2; ++n) _Pragma("unroll") for (int k = 0; k < 2; ++k) dst[n][k] = *(const PG8_LAS bf16x8*)(lds + PG8_SB(b, h) + boff + n * 2048 + k * 1024); } while (0)
; #define PG8_MMA(ai, bj, At, Bt) do { __builtin_amdgcn_s_setprio(1); _Pragma("unroll") for (int m = 0; m < 4; ++m) _Pragma("unroll") for (int n = 0; n < 2; ++n) _Pragma("unroll") for (int k = 0; k < 2; ++k) \
;     acc[ai][bj][m][n] = __builtin_amdgcn_mfma_f32_16x16x32_bf16(Bt[n][k], At[m][k], acc[ai][bj][m][n], 0, 0, 0); __builtin_amdgcn_s_setprio(0); } while (0)
; #define PG8_WAIT_V(n) asm volatile("s_waitcnt vmcnt(" #n ")" ::: "memory")
; #define PG8_WAIT_L(n) asm volatile("s_waitcnt lgkmcnt(" #n ")" ::: "memory")
; #define PG8_BAR __builtin_amdgcn_s_barrier()
; #define PG8_SCHED __builtin_amdgcn_sched_barrier(0)
; template <class Epi, class Sched>
; DI void gemm_phase(PG8_LAS unsigned char* lds, const Gemm g, const Sched& S, const Epi& E) {
;     ...
;       PG8_LDB(B0, 0, 0); PG8_LDB(B1, 0, 1); PG8_SCHED; PG8_LDA(At, 0, 0); PG8_STAGE(PG8_SA(1, 1), a1 + hstepA, voffA);
;       PG8_WAIT_V(8); PG8_WAIT_L(0); PG8_BAR; PG8_MMA(0, 0, At, B0); PG8_MMA(0, 1, At, B1); PG8_BAR; PG8_SCHED;
;       PG8_LDA(At, 0, 1); PG8_STAGE(PG8_SB(0, 0), b2, voffB); PG8_STAGE(PG8_SB(0, 1), b2 + hstepB, voffB); PG8_STAGE(PG8_SA(0, 0), a2, voffA);
;       PG8_WAIT_V(8); PG8_WAIT_L(0); PG8_BAR; PG8_MMA(1, 0, At, B0); PG8_MMA(1, 1, At, B1); PG8_BAR; PG8_SCHED;
.LBB0_286:
	ds_read_b128 v[146:149], v180
	ds_read_b128 v[150:153], v180 offset:1024
	ds_read_b128 v[154:157], v180 offset:2048
	ds_read_b128 v[158:161], v180 offset:3072
	ds_read_b128 v[162:165], v181
	ds_read_b128 v[166:169], v181 offset:1024
	ds_read_b128 v[170:173], v181 offset:2048
	ds_read_b128 v[174:177], v181 offset:3072
	s_add_u32 s16, s6, 0xfffc0080
	s_addc_u32 s30, s7, -1
	s_cmp_eq_u32 s69, 12
	s_cselect_b32 s35, s1, s30
	s_cselect_b32 s34, s5, s16
	s_cselect_b32 s31, s21, s68
	s_cselect_b32 s30, s23, s67
	v_lshl_add_u64 v[178:179], s[6:7], 0, v[140:141]
	s_add_i32 m0, s3, 0xc000
	ds_read_b128 v[186:189], v182
	ds_read_b128 v[190:193], v182 offset:1024
	ds_read_b128 v[194:197], v182 offset:2048
	ds_read_b128 v[198:201], v182 offset:3072
	ds_read_b128 v[202:205], v182 offset:4096
	ds_read_b128 v[206:209], v182 offset:5120
	ds_read_b128 v[214:217], v182 offset:6144
	ds_read_b128 v[218:221], v182 offset:7168
	global_load_lds_dwordx4 v[178:179], off
	v_lshl_add_u64 v[178:179], s[6:7], 0, v[142:143]
	s_add_i32 m0, s3, 0xe000
	s_nop 0
	global_load_lds_dwordx4 v[178:179], off
	s_waitcnt vmcnt(8)
	s_waitcnt lgkmcnt(0)
	s_barrier
	s_waitcnt lgkmcnt(0)
	v_mfma_f32_16x16x32_bf16 v[122:125], v[146:149], v[186:189], v[122:125]
	v_mfma_f32_16x16x32_bf16 v[126:129], v[154:157], v[186:189], v[126:129]
	v_mfma_f32_16x16x32_bf16 v[106:109], v[146:149], v[194:197], v[106:109]
	v_mfma_f32_16x16x32_bf16 v[110:113], v[154:157], v[194:197], v[110:113]
	v_mfma_f32_16x16x32_bf16 v[90:93], v[146:149], v[202:205], v[90:93]
	v_mfma_f32_16x16x32_bf16 v[94:97], v[154:157], v[202:205], v[94:97]
	v_mfma_f32_16x16x32_bf16 v[74:77], v[146:149], v[214:217], v[74:77]
	v_mfma_f32_16x16x32_bf16 v[78:81], v[154:157], v[214:217], v[78:81]
	v_mfma_f32_16x16x32_bf16 v[122:125], v[150:153], v[190:193], v[122:125]
	v_mfma_f32_16x16x32_bf16 v[126:129], v[158:161], v[190:193], v[126:129]
	v_mfma_f32_16x16x32_bf16 v[106:109], v[150:153], v[198:201], v[106:109]
	v_mfma_f32_16x16x32_bf16 v[110:113], v[158:161], v[198:201], v[110:113]
	v_mfma_f32_16x16x32_bf16 v[90:93], v[150:153], v[206:209], v[90:93]
	v_mfma_f32_16x16x32_bf16 v[94:97], v[158:161], v[206:209], v[94:97]
	v_mfma_f32_16x16x32_bf16 v[74:77], v[150:153], v[218:221], v[74:77]
	v_mfma_f32_16x16x32_bf16 v[78:81], v[158:161], v[218:221], v[78:81]
	v_mfma_f32_16x16x32_bf16 v[114:117], v[162:165], v[186:189], v[114:117]
	v_mfma_f32_16x16x32_bf16 v[118:121], v[170:173], v[186:189], v[118:121]
	v_mfma_f32_16x16x32_bf16 v[98:101], v[162:165], v[194:197], v[98:101]
	v_mfma_f32_16x16x32_bf16 v[102:105], v[170:173], v[194:197], v[102:105]
	v_mfma_f32_16x16x32_bf16 v[82:85], v[162:165], v[202:205], v[82:85]
	v_mfma_f32_16x16x32_bf16 v[86:89], v[170:173], v[202:205], v[86:89]
	v_mfma_f32_16x16x32_bf16 v[66:69], v[162:165], v[214:217], v[66:69]
	v_mfma_f32_16x16x32_bf16 v[70:73], v[170:173], v[214:217], v[70:73]
	v_mfma_f32_16x16x32_bf16 v[114:117], v[166:169], v[190:193], v[114:117]
	v_mfma_f32_16x16x32_bf16 v[118:121], v[174:177], v[190:193], v[118:121]
	v_mfma_f32_16x16x32_bf16 v[98:101], v[166:169], v[198:201], v[98:101]
	v_mfma_f32_16x16x32_bf16 v[102:105], v[174:177], v[198:201], v[102:105]
	v_mfma_f32_16x16x32_bf16 v[82:85], v[166:169], v[206:209], v[82:85]
	v_mfma_f32_16x16x32_bf16 v[86:89], v[174:177], v[206:209], v[86:89]
	v_mfma_f32_16x16x32_bf16 v[66:69], v[166:169], v[218:221], v[66:69]
	v_mfma_f32_16x16x32_bf16 v[70:73], v[174:177], v[218:221], v[70:73]
	s_barrier
	s_add_i32 s16, s40, s2
	v_lshl_add_u64 v[178:179], s[30:31], 0, v[132:133]
	s_mov_b32 m0, s16
	ds_read_b128 v[186:189], v182 offset:16384
	ds_read_b128 v[190:193], v182 offset:17408
	ds_read_b128 v[194:197], v182 offset:18432
	ds_read_b128 v[198:201], v182 offset:19456
	ds_read_b128 v[202:205], v182 offset:20480
	ds_read_b128 v[206:209], v182 offset:21504
	ds_read_b128 v[214:217], v182 offset:22528
	ds_read_b128 v[218:221], v182 offset:23552
	global_load_lds_dwordx4 v[178:179], off
	s_add_i32 m0, s16, 0x2000
	s_add_u32 s56, s30, 0x40000
	v_lshl_add_u64 v[210:211], s[30:31], 0, v[136:137]
	s_addc_u32 s57, s31, 0
	s_add_i32 s16, s41, s2
	global_load_lds_dwordx4 v[210:211], off
	v_lshl_add_u64 v[222:223], s[56:57], 0, v[132:133]
	s_mov_b32 m0, s16
	v_lshl_add_u64 v[224:225], s[34:35], 0, v[134:135]
	global_load_lds_dwordx4 v[222:223], off
	v_lshl_add_u64 v[222:223], s[56:57], 0, v[136:137]
	s_add_i32 m0, s16, 0x2000
	s_nop 0
	global_load_lds_dwordx4 v[222:223], off
	v_lshl_add_u64 v[222:223], s[34:35], 0, v[130:131]
	s_mov_b32 m0, s3
	s_nop 0
	global_load_lds_dwordx4 v[222:223], off
	s_mov_b32 m0, s17
	s_nop 0
	global_load_lds_dwordx4 v[224:225], off
	s_waitcnt vmcnt(8)
	s_waitcnt lgkmcnt(0)
	s_barrier
; #define PG8_STAGE(bufoff, gbase, voff) do { _Pragma("unroll") for (int _i = 0; _i < 2; ++_i) \
;     __builtin_amdgcn_global_load_lds((const unsigned*)((const char*)(gbase) + (voff)[_i]), (PG8_LAS unsigned*)(lds + (bufoff) + ldsw + _i * 8192), 16, 0, 0); } while (0)
; #define PG8_LDA(dst, b, h) do { _Pragma("unroll") for (int m = 0; m < 4; ++m) _Pragma("unroll") for (int k = 0; k < 2; ++k) dst[m][k] = *(const PG8_LAS bf16x8*)(lds + PG8_SA(b, h) + aoff + m * 2048 + k * 1024); } while (0)
; #define PG8_LDB(dst, b, h) do { _Pragma("unroll") for (int n = 0; n < 2; ++n) _Pragma("unroll") for (int k = 0; k < 2; ++k) dst[n][k] = *(const PG8_LAS bf16x8*)(lds + PG8_SB(b, h) + boff + n * 2048 + k * 1024); } while (0)
; #define PG8_MMA(ai, bj, At, Bt) do { __builtin_amdgcn_s_setprio(1); _Pragma("unroll") for (int m = 0; m < 4; ++m) _Pragma("unroll") for (int n = 0; n < 2; ++n) _Pragma("unroll") for (int k = 0; k < 2; ++k) \
;     acc[ai][bj][m][n] = __builtin_amdgcn_mfma_f32_16x16x32_bf16(Bt[n][k], At[m][k], acc[ai][bj][m][n], 0, 0, 0); __builtin_amdgcn_s_setprio(0); } while (0)
; #define PG8_WAIT_V(n) asm volatile("s_waitcnt vmcnt(" #n ")" ::: "memory")
; #define PG8_WAIT_L(n) asm volatile("s_waitcnt lgkmcnt(" #n ")" ::: "memory")
; #define PG8_BAR __builtin_amdgcn_s_barrier()
; #define PG8_SCHED __builtin_amdgcn_sched_barrier(0)
; template <class Epi, class Sched>
; DI void gemm_phase(PG8_LAS unsigned char* lds, const Gemm g, const Sched& S, const Epi& E) {
;     ...
;       PG8_WAIT_V(8); PG8_WAIT_L(0); PG8_BAR; PG8_MMA(1, 0, At, B0); PG8_MMA(1, 1, At, B1); PG8_BAR; PG8_SCHED;
;       PG8_LDB(B0, 1, 0); PG8_LDB(B1, 1, 1); PG8_SCHED; PG8_LDA(At, 1, 0); PG8_STAGE(PG8_SA(0, 1), a2 + hstepA, voffA);
;       PG8_WAIT_V(8); PG8_WAIT_L(0); PG8_BAR; PG8_MMA(0, 0, At, B0); PG8_MMA(0, 1, At, B1); PG8_BAR; PG8_SCHED;
;       PG8_LDA(At, 1, 1); PG8_STAGE(PG8_SB(1, 0), b3, voffB); PG8_STAGE(PG8_SB(1, 1), b3 + hstepB, voffB); PG8_STAGE(PG8_SA(1, 0), a3, voffA);
	s_waitcnt lgkmcnt(0)
	v_mfma_f32_16x16x32_bf16 v[58:61], v[146:149], v[186:189], v[58:61]
	v_mfma_f32_16x16x32_bf16 v[62:65], v[154:157], v[186:189], v[62:65]
	v_mfma_f32_16x16x32_bf16 v[42:45], v[146:149], v[194:197], v[42:45]
	v_mfma_f32_16x16x32_bf16 v[46:49], v[154:157], v[194:197], v[46:49]
	v_mfma_f32_16x16x32_bf16 v[26:29], v[146:149], v[202:205], v[26:29]
	v_mfma_f32_16x16x32_bf16 v[30:33], v[154:157], v[202:205], v[30:33]
	v_mfma_f32_16x16x32_bf16 v[10:13], v[146:149], v[214:217], v[10:13]
	v_mfma_f32_16x16x32_bf16 v[14:17], v[154:157], v[214:217], v[14:17]
	v_mfma_f32_16x16x32_bf16 v[58:61], v[150:153], v[190:193], v[58:61]
	v_mfma_f32_16x16x32_bf16 v[62:65], v[158:161], v[190:193], v[62:65]
	v_mfma_f32_16x16x32_bf16 v[42:45], v[150:153], v[198:201], v[42:45]
	v_mfma_f32_16x16x32_bf16 v[46:49], v[158:161], v[198:201], v[46:49]
	v_mfma_f32_16x16x32_bf16 v[26:29], v[150:153], v[206:209], v[26:29]
	v_mfma_f32_16x16x32_bf16 v[30:33], v[158:161], v[206:209], v[30:33]
	v_mfma_f32_16x16x32_bf16 v[10:13], v[150:153], v[218:221], v[10:13]
	v_mfma_f32_16x16x32_bf16 v[14:17], v[158:161], v[218:221], v[14:17]
	v_mfma_f32_16x16x32_bf16 v[50:53], v[162:165], v[186:189], v[50:53]
	v_mfma_f32_16x16x32_bf16 v[54:57], v[170:173], v[186:189], v[54:57]
	v_mfma_f32_16x16x32_bf16 v[34:37], v[162:165], v[194:197], v[34:37]
	v_mfma_f32_16x16x32_bf16 v[38:41], v[170:173], v[194:197], v[38:41]
	v_mfma_f32_16x16x32_bf16 v[18:21], v[162:165], v[202:205], v[18:21]
	v_mfma_f32_16x16x32_bf16 v[22:25], v[170:173], v[202:205], v[22:25]
	v_mfma_f32_16x16x32_bf16 v[6:9], v[162:165], v[214:217], v[6:9]
	v_mfma_f32_16x16x32_bf16 v[2:5], v[170:173], v[214:217], v[2:5]
	v_mfma_f32_16x16x32_bf16 v[50:53], v[166:169], v[190:193], v[50:53]
	v_mfma_f32_16x16x32_bf16 v[54:57], v[174:177], v[190:193], v[54:57]
	v_mfma_f32_16x16x32_bf16 v[34:37], v[166:169], v[198:201], v[34:37]
	v_mfma_f32_16x16x32_bf16 v[38:41], v[174:177], v[198:201], v[38:41]
	v_mfma_f32_16x16x32_bf16 v[18:21], v[166:169], v[206:209], v[18:21]
	v_mfma_f32_16x16x32_bf16 v[22:25], v[174:177], v[206:209], v[22:25]
	v_mfma_f32_16x16x32_bf16 v[6:9], v[166:169], v[218:221], v[6:9]
	v_mfma_f32_16x16x32_bf16 v[2:5], v[174:177], v[218:221], v[2:5]
	s_barrier
	ds_read_b128 v[146:149], v184
	ds_read_b128 v[150:153], v184 offset:1024
	ds_read_b128 v[154:157], v184 offset:2048
	ds_read_b128 v[158:161], v184 offset:3072
	ds_read_b128 v[162:165], v185
	ds_read_b128 v[166:169], v185 offset:1024
	ds_read_b128 v[170:173], v185 offset:2048
	ds_read_b128 v[174:177], v185 offset:3072
	s_add_u32 s34, s34, 0x40000
	s_addc_u32 s35, s35, 0
	s_mov_b32 m0, s19
	v_lshl_add_u64 v[226:227], s[34:35], 0, v[130:131]
	ds_read_b128 v[186:189], v182 offset:32768
	ds_read_b128 v[190:193], v182 offset:33792
	ds_read_b128 v[194:197], v182 offset:34816
	ds_read_b128 v[198:201], v182 offset:35840
	ds_read_b128 v[202:205], v182 offset:36864
	ds_read_b128 v[206:209], v182 offset:37888
	ds_read_b128 v[214:217], v182 offset:38912
	ds_read_b128 v[218:221], v182 offset:39936
	global_load_lds_dwordx4 v[226:227], off
	v_lshl_add_u64 v[226:227], s[34:35], 0, v[134:135]
	s_mov_b32 m0, s33
	s_nop 0
	global_load_lds_dwordx4 v[226:227], off
	s_waitcnt vmcnt(8)
	s_waitcnt lgkmcnt(0)
	s_barrier
	s_waitcnt lgkmcnt(0)
	v_mfma_f32_16x16x32_bf16 v[122:125], v[146:149], v[186:189], v[122:125]
	v_mfma_f32_16x16x32_bf16 v[126:129], v[154:157], v[186:189], v[126:129]
	v_mfma_f32_16x16x32_bf16 v[106:109], v[146:149], v[194:197], v[106:109]
	v_mfma_f32_16x16x32_bf16 v[110:113], v[154:157], v[194:197], v[110:113]
	v_mfma_f32_16x16x32_bf16 v[90:93], v[146:149], v[202:205], v[90:93]
	v_mfma_f32_16x16x32_bf16 v[94:97], v[154:157], v[202:205], v[94:97]
	v_mfma_f32_16x16x32_bf16 v[74:77], v[146:149], v[214:217], v[74:77]
	v_mfma_f32_16x16x32_bf16 v[78:81], v[154:157], v[214:217], v[78:81]
	v_mfma_f32_16x16x32_bf16 v[122:125], v[150:153], v[190:193], v[122:125]
	v_mfma_f32_16x16x32_bf16 v[126:129], v[158:161], v[190:193], v[126:129]
	v_mfma_f32_16x16x32_bf16 v[106:109], v[150:153], v[198:201], v[106:109]
	v_mfma_f32_16x16x32_bf16 v[110:113], v[158:161], v[198:201], v[110:113]
	v_mfma_f32_16x16x32_bf16 v[90:93], v[150:153], v[206:209], v[90:93]
	v_mfma_f32_16x16x32_bf16 v[94:97], v[158:161], v[206:209], v[94:97]
	v_mfma_f32_16x16x32_bf16 v[74:77], v[150:153], v[218:221], v[74:77]
	v_mfma_f32_16x16x32_bf16 v[78:81], v[158:161], v[218:221], v[78:81]
	v_mfma_f32_16x16x32_bf16 v[114:117], v[162:165], v[186:189], v[114:117]
	v_mfma_f32_16x16x32_bf16 v[118:121], v[170:173], v[186:189], v[118:121]
	v_mfma_f32_16x16x32_bf16 v[98:101], v[162:165], v[194:197], v[98:101]
	v_mfma_f32_16x16x32_bf16 v[102:105], v[170:173], v[194:197], v[102:105]
	v_mfma_f32_16x16x32_bf16 v[82:85], v[162:165], v[202:205], v[82:85]
	v_mfma_f32_16x16x32_bf16 v[86:89], v[170:173], v[202:205], v[86:89]
	v_mfma_f32_16x16x32_bf16 v[66:69], v[162:165], v[214:217], v[66:69]
	v_mfma_f32_16x16x32_bf16 v[70:73], v[170:173], v[214:217], v[70:73]
	v_mfma_f32_16x16x32_bf16 v[114:117], v[166:169], v[190:193], v[114:117]
	v_mfma_f32_16x16x32_bf16 v[118:121], v[174:177], v[190:193], v[118:121]
	v_mfma_f32_16x16x32_bf16 v[98:101], v[166:169], v[198:201], v[98:101]
	v_mfma_f32_16x16x32_bf16 v[102:105], v[174:177], v[198:201], v[102:105]
	v_mfma_f32_16x16x32_bf16 v[82:85], v[166:169], v[206:209], v[82:85]
	v_mfma_f32_16x16x32_bf16 v[86:89], v[174:177], v[206:209], v[86:89]
	v_mfma_f32_16x16x32_bf16 v[66:69], v[166:169], v[218:221], v[66:69]
	v_mfma_f32_16x16x32_bf16 v[70:73], v[174:177], v[218:221], v[70:73]
	s_barrier
; #define PG8_STAGE(bufoff, gbase, voff) do { _Pragma("unroll") for (int _i = 0; _i < 2; ++_i) \
;     __builtin_amdgcn_global_load_lds((const unsigned*)((const char*)(gbase) + (voff)[_i]), (PG8_LAS unsigned*)(lds + (bufoff) + ldsw + _i * 8192), 16, 0, 0); } while (0)
; #define PG8_LDA(dst, b, h) do { _Pragma("unroll") for (int m = 0; m < 4; ++m) _Pragma("unroll") for (int k = 0; k < 2; ++k) dst[m][k] = *(const PG8_LAS bf16x8*)(lds + PG8_SA(b, h) + aoff + m * 2048 + k * 1024); } while (0)
; #define PG8_MMA(ai, bj, At, Bt) do { __builtin_amdgcn_s_setprio(1); _Pragma("unroll") for (int m = 0; m < 4; ++m) _Pragma("unroll") for (int n = 0; n < 2; ++n) _Pragma("unroll") for (int k = 0; k < 2; ++k) \
;     acc[ai][bj][m][n] = __builtin_amdgcn_mfma_f32_16x16x32_bf16(Bt[n][k], At[m][k], acc[ai][bj][m][n], 0, 0, 0); __builtin_amdgcn_s_setprio(0); } while (0)
; #define PG8_WAIT_V(n) asm volatile("s_waitcnt vmcnt(" #n ")" ::: "memory")
; #define PG8_WAIT_L(n) asm volatile("s_waitcnt lgkmcnt(" #n ")" ::: "memory")
; #define PG8_BAR __builtin_amdgcn_s_barrier()
; #define PG8_SCHED __builtin_amdgcn_sched_barrier(0)
; DI void rows_rstd(float (&rs)[2][4], const float* ps, const Unit& u, int wr, int fr, int fq, int p_lo, int p_hi, float inv_dim) {
;   f32x4 pv[2][4];
; #pragma unroll
;   for (int ai = 0; ai < 2; ++ai)
; #pragma unroll
;     for (int m = 0; m < 4; ++m) pv[ai][m] = *(const f32x4*)(ps + (size_t)(u.pm * BM + ai * HALF + wr * 64 + m * 16 + fr) * 16 + 4 * fq);
; template <class Epi, class Sched>
; DI void gemm_phase(PG8_LAS unsigned char* lds, const Gemm g, const Sched& S, const Epi& E) {
;     ...
;       PG8_LDA(At, 1, 1); PG8_STAGE(PG8_SB(1, 0), b3, voffB); PG8_STAGE(PG8_SB(1, 1), b3 + hstepB, voffB); PG8_STAGE(PG8_SA(1, 0), a3, voffA);
;       PG8_WAIT_V(8); PG8_WAIT_L(0); PG8_BAR; PG8_MMA(1, 0, At, B0); PG8_MMA(1, 1, At, B1); PG8_BAR; PG8_SCHED;
;     }
;     if (wr == 0) PG8_BAR;
	s_add_i32 s16, s65, s2
	v_lshl_add_u64 v[178:179], v[178:179], 0, s[12:13]
	s_mov_b32 m0, s16
	ds_read_b128 v[186:189], v182 offset:49152
	ds_read_b128 v[190:193], v182 offset:50176
	ds_read_b128 v[194:197], v182 offset:51200
	ds_read_b128 v[198:201], v182 offset:52224
	ds_read_b128 v[202:205], v182 offset:53248
	ds_read_b128 v[206:209], v182 offset:54272
	ds_read_b128 v[214:217], v182 offset:55296
	ds_read_b128 v[218:221], v182 offset:56320
	global_load_lds_dwordx4 v[178:179], off
	s_add_i32 m0, s16, 0x2000
	s_add_u32 s30, s30, 0x40080
	v_lshl_add_u64 v[178:179], v[210:211], 0, s[12:13]
	s_addc_u32 s31, s31, 0
	s_add_i32 s16, s66, s2
	global_load_lds_dwordx4 v[178:179], off
	v_lshl_add_u64 v[178:179], s[30:31], 0, v[132:133]
	s_mov_b32 m0, s16
	s_nop 0
	global_load_lds_dwordx4 v[178:179], off
	v_lshl_add_u64 v[178:179], s[30:31], 0, v[136:137]
	s_add_i32 m0, s16, 0x2000
	s_nop 0
	global_load_lds_dwordx4 v[178:179], off
	v_lshl_add_u64 v[178:179], v[222:223], 0, s[12:13]
	s_mov_b32 m0, s36
	s_nop 0
	global_load_lds_dwordx4 v[178:179], off
	v_lshl_add_u64 v[178:179], v[224:225], 0, s[12:13]
	s_mov_b32 m0, s37
	s_nop 0
	global_load_lds_dwordx4 v[178:179], off
	s_waitcnt vmcnt(8)
	s_waitcnt lgkmcnt(0)
	s_barrier
	s_waitcnt lgkmcnt(0)
	v_mfma_f32_16x16x32_bf16 v[58:61], v[146:149], v[186:189], v[58:61]
	v_mfma_f32_16x16x32_bf16 v[62:65], v[154:157], v[186:189], v[62:65]
	v_mfma_f32_16x16x32_bf16 v[42:45], v[146:149], v[194:197], v[42:45]
	v_mfma_f32_16x16x32_bf16 v[46:49], v[154:157], v[194:197], v[46:49]
	v_mfma_f32_16x16x32_bf16 v[26:29], v[146:149], v[202:205], v[26:29]
	v_mfma_f32_16x16x32_bf16 v[30:33], v[154:157], v[202:205], v[30:33]
	v_mfma_f32_16x16x32_bf16 v[10:13], v[146:149], v[214:217], v[10:13]
	v_mfma_f32_16x16x32_bf16 v[14:17], v[154:157], v[214:217], v[14:17]
	v_mfma_f32_16x16x32_bf16 v[58:61], v[150:153], v[190:193], v[58:61]
	v_mfma_f32_16x16x32_bf16 v[62:65], v[158:161], v[190:193], v[62:65]
	v_mfma_f32_16x16x32_bf16 v[42:45], v[150:153], v[198:201], v[42:45]
	v_mfma_f32_16x16x32_bf16 v[46:49], v[158:161], v[198:201], v[46:49]
	v_mfma_f32_16x16x32_bf16 v[26:29], v[150:153], v[206:209], v[26:29]
	v_mfma_f32_16x16x32_bf16 v[30:33], v[158:161], v[206:209], v[30:33]
	v_mfma_f32_16x16x32_bf16 v[10:13], v[150:153], v[218:221], v[10:13]
	v_mfma_f32_16x16x32_bf16 v[14:17], v[158:161], v[218:221], v[14:17]
	v_mfma_f32_16x16x32_bf16 v[50:53], v[162:165], v[186:189], v[50:53]
	v_mfma_f32_16x16x32_bf16 v[54:57], v[170:173], v[186:189], v[54:57]
	v_mfma_f32_16x16x32_bf16 v[34:37], v[162:165], v[194:197], v[34:37]
	v_mfma_f32_16x16x32_bf16 v[38:41], v[170:173], v[194:197], v[38:41]
	v_mfma_f32_16x16x32_bf16 v[18:21], v[162:165], v[202:205], v[18:21]
	v_mfma_f32_16x16x32_bf16 v[22:25], v[170:173], v[202:205], v[22:25]
	v_mfma_f32_16x16x32_bf16 v[6:9], v[162:165], v[214:217], v[6:9]
	v_mfma_f32_16x16x32_bf16 v[2:5], v[170:173], v[214:217], v[2:5]
	v_mfma_f32_16x16x32_bf16 v[50:53], v[166:169], v[190:193], v[50:53]
	v_mfma_f32_16x16x32_bf16 v[54:57], v[174:177], v[190:193], v[54:57]
	v_mfma_f32_16x16x32_bf16 v[34:37], v[166:169], v[198:201], v[34:37]
	v_mfma_f32_16x16x32_bf16 v[38:41], v[174:177], v[198:201], v[38:41]
	v_mfma_f32_16x16x32_bf16 v[18:21], v[166:169], v[206:209], v[18:21]
	v_mfma_f32_16x16x32_bf16 v[22:25], v[174:177], v[206:209], v[22:25]
	v_mfma_f32_16x16x32_bf16 v[6:9], v[166:169], v[218:221], v[6:9]
	v_mfma_f32_16x16x32_bf16 v[2:5], v[174:177], v[218:221], v[2:5]
	s_barrier
	s_add_i32 s69, s69, 2
	s_add_u32 s6, s6, 0x100
	s_addc_u32 s7, s7, 0
	s_add_u32 s67, s67, 0x100
	s_addc_u32 s68, s68, 0
	s_cmp_gt_u32 s69, 13
	s_cbranch_scc0 .LBB0_286
	v_lshl_add_u32 v166, s4, 8, v1
	v_or_b32_e32 v164, 16, v166
	v_ashrrev_i32_e32 v165, 31, v164
	v_or_b32_e32 v158, 32, v166
	v_lshlrev_b64 v[146:147], 6, v[164:165]
	v_ashrrev_i32_e32 v159, 31, v158
	v_lshl_add_u64 v[146:147], v[138:139], 0, v[146:147]
	v_lshlrev_b64 v[148:149], 6, v[158:159]
	v_ashrrev_i32_e32 v167, 31, v166
	v_lshl_add_u64 v[148:149], v[138:139], 0, v[148:149]
	global_load_dwordx4 v[160:163], v[146:147], off
	global_load_dwordx4 v[168:171], v[148:149], off
	v_lshlrev_b64 v[146:147], 6, v[166:167]
	v_lshl_add_u64 v[146:147], v[138:139], 0, v[146:147]
	global_load_dwordx4 v[172:175], v[146:147], off
	v_or_b32_e32 v156, 48, v166
	v_ashrrev_i32_e32 v157, 31, v156
	v_add_u32_e32 v154, 0x80, v166
	v_lshlrev_b64 v[146:147], 6, v[156:157]
	v_ashrrev_i32_e32 v155, 31, v154
	v_add_u32_e32 v150, 0x90, v166
	v_lshl_add_u64 v[146:147], v[138:139], 0, v[146:147]
	v_lshlrev_b64 v[148:149], 6, v[154:155]
	v_ashrrev_i32_e32 v151, 31, v150
	v_lshl_add_u64 v[148:149], v[138:139], 0, v[148:149]
	global_load_dwordx4 v[176:179], v[146:147], off
	global_load_dwordx4 v[186:189], v[148:149], off
	v_lshlrev_b64 v[146:147], 6, v[150:151]
	v_lshl_add_u64 v[146:147], v[138:139], 0, v[146:147]
	global_load_dwordx4 v[190:193], v[146:147], off
	v_add_u32_e32 v148, 0xa0, v166
	v_ashrrev_i32_e32 v149, 31, v148
	v_lshlrev_b64 v[146:147], 6, v[148:149]
	v_lshl_add_u64 v[146:147], v[138:139], 0, v[146:147]
	global_load_dwordx4 v[194:197], v[146:147], off
	v_add_u32_e32 v146, 0xb0, v166
	v_ashrrev_i32_e32 v147, 31, v146
	v_lshlrev_b64 v[152:153], 6, v[146:147]
	v_lshl_add_u64 v[152:153], v[138:139], 0, v[152:153]
	global_load_dwordx4 v[198:201], v[152:153], off
	s_and_b64 vcc, exec, s[14:15]
	s_cbranch_vccz .LBB0_289
	s_barrier

; #define PG8_STAGE(bufoff, gbase, voff) do { _Pragma("unroll") for (int _i = 0; _i < 2; ++_i) \
;     __builtin_amdgcn_global_load_lds((const unsigned*)((const char*)(gbase) + (voff)[_i]), (PG8_LAS unsigned*)(lds + (bufoff) + ldsw + _i * 8192), 16, 0, 0); } while (0)
; #define PG8_LDA(dst, b, h) do { _Pragma("unroll") for (int m = 0; m < 4; ++m) _Pragma("unroll") for (int k = 0; k < 2; ++k) dst[m][k] = *(const PG8_LAS bf16x8*)(lds + PG8_SA(b, h) + aoff + m * 2048 + k * 1024); } while (0)
; #define PG8_LDB(dst, b, h) do { _Pragma("unroll") for (int n = 0; n < 2; ++n) _Pragma("unroll") for (int k = 0; k < 2; ++k) dst[n][k] = *(const PG8_LAS bf16x8*)(lds + PG8_SB(b, h) + boff + n * 2048 + k * 1024); } while (0)
; #define PG8_MMA(ai, bj, At, Bt) do { __builtin_amdgcn_s_setprio(1); _Pragma("unroll") for (int m = 0; m < 4; ++m) _Pragma("unroll") for (int n = 0; n < 2; ++n) _Pragma("unroll") for (int k = 0; k < 2; ++k) \
;     acc[ai][bj][m][n] = __builtin_amdgcn_mfma_f32_16x16x32_bf16(Bt[n][k], At[m][k], acc[ai][bj][m][n], 0, 0, 0); __builtin_amdgcn_s_setprio(0); } while (0)
; #define PG8_WAIT_V(n) asm volatile("s_waitcnt vmcnt(" #n ")" ::: "memory")
; #define PG8_WAIT_L(n) asm volatile("s_waitcnt lgkmcnt(" #n ")" ::: "memory")
; #define PG8_BAR __builtin_amdgcn_s_barrier()
; #define PG8_SCHED __builtin_amdgcn_sched_barrier(0)
; template <class Epi, class Sched>
; DI void gemm_phase(PG8_LAS unsigned char* lds, const Gemm g, const Sched& S, const Epi& E) {
;     ...
;       PG8_LDB(B0, 0, 0); PG8_LDB(B1, 0, 1); PG8_SCHED; PG8_LDA(At, 0, 0); PG8_STAGE(PG8_SA(1, 1), a1 + hstepA, voffA);
;       PG8_WAIT_V(8); PG8_WAIT_L(0); PG8_BAR; PG8_MMA(0, 0, At, B0); PG8_MMA(0, 1, At, B1); PG8_BAR; PG8_SCHED;
;       PG8_LDA(At, 0, 1); PG8_STAGE(PG8_SB(0, 0), b2, voffB); PG8_STAGE(PG8_SB(0, 1), b2 + hstepB, voffB); PG8_STAGE(PG8_SA(0, 0), a2, voffA);
;       PG8_WAIT_V(8); PG8_WAIT_L(0); PG8_BAR; PG8_MMA(1, 0, At, B0); PG8_MMA(1, 1, At, B1); PG8_BAR; PG8_SCHED;
.LBB0_563:
	ds_read_b128 v[128:131], v167
	ds_read_b128 v[132:135], v167 offset:1024
	ds_read_b128 v[136:139], v167 offset:2048
	ds_read_b128 v[140:143], v167 offset:3072
	ds_read_b128 v[158:161], v168
	ds_read_b128 v[162:165], v168 offset:1024
	ds_read_b128 v[172:175], v168 offset:2048
	ds_read_b128 v[176:179], v168 offset:3072
	s_add_u32 s16, s28, 0xfffc0080
	s_addc_u32 s17, s29, -1
	s_cmp_eq_u32 s70, 12
	s_cselect_b32 s35, s19, s17
	s_cselect_b32 s34, s27, s16
	s_cselect_b32 s31, s15, s69
	s_cselect_b32 s30, s67, s68
	v_lshl_add_u64 v[214:215], s[28:29], 0, v[154:155]
	s_add_i32 m0, s3, 0xc000
	ds_read_b128 v[180:183], v169
	ds_read_b128 v[184:187], v169 offset:1024
	ds_read_b128 v[188:191], v169 offset:2048
	ds_read_b128 v[192:195], v169 offset:3072
	ds_read_b128 v[196:199], v169 offset:4096
	ds_read_b128 v[200:203], v169 offset:5120
	ds_read_b128 v[204:207], v169 offset:6144
	ds_read_b128 v[208:211], v169 offset:7168
	global_load_lds_dwordx4 v[214:215], off
	v_lshl_add_u64 v[214:215], s[28:29], 0, v[156:157]
	s_add_i32 m0, s3, 0xe000
	s_nop 0
	global_load_lds_dwordx4 v[214:215], off
	s_waitcnt vmcnt(8)
	s_waitcnt lgkmcnt(0)
	s_barrier
	s_waitcnt lgkmcnt(0)
	v_mfma_f32_16x16x32_bf16 v[124:127], v[128:131], v[180:183], v[124:127]
	v_mfma_f32_16x16x32_bf16 v[120:123], v[136:139], v[180:183], v[120:123]
	v_mfma_f32_16x16x32_bf16 v[108:111], v[128:131], v[188:191], v[108:111]
	v_mfma_f32_16x16x32_bf16 v[104:107], v[136:139], v[188:191], v[104:107]
	v_mfma_f32_16x16x32_bf16 v[92:95], v[128:131], v[196:199], v[92:95]
	v_mfma_f32_16x16x32_bf16 v[88:91], v[136:139], v[196:199], v[88:91]
	v_mfma_f32_16x16x32_bf16 v[76:79], v[128:131], v[204:207], v[76:79]
	v_mfma_f32_16x16x32_bf16 v[72:75], v[136:139], v[204:207], v[72:75]
	v_mfma_f32_16x16x32_bf16 v[124:127], v[132:135], v[184:187], v[124:127]
	v_mfma_f32_16x16x32_bf16 v[120:123], v[140:143], v[184:187], v[120:123]
	v_mfma_f32_16x16x32_bf16 v[108:111], v[132:135], v[192:195], v[108:111]
	v_mfma_f32_16x16x32_bf16 v[104:107], v[140:143], v[192:195], v[104:107]
	v_mfma_f32_16x16x32_bf16 v[92:95], v[132:135], v[200:203], v[92:95]
	v_mfma_f32_16x16x32_bf16 v[88:91], v[140:143], v[200:203], v[88:91]
	v_mfma_f32_16x16x32_bf16 v[76:79], v[132:135], v[208:211], v[76:79]
	v_mfma_f32_16x16x32_bf16 v[72:75], v[140:143], v[208:211], v[72:75]
	v_mfma_f32_16x16x32_bf16 v[116:119], v[158:161], v[180:183], v[116:119]
	v_mfma_f32_16x16x32_bf16 v[112:115], v[172:175], v[180:183], v[112:115]
	v_mfma_f32_16x16x32_bf16 v[100:103], v[158:161], v[188:191], v[100:103]
	v_mfma_f32_16x16x32_bf16 v[96:99], v[172:175], v[188:191], v[96:99]
	v_mfma_f32_16x16x32_bf16 v[84:87], v[158:161], v[196:199], v[84:87]
	v_mfma_f32_16x16x32_bf16 v[80:83], v[172:175], v[196:199], v[80:83]
	v_mfma_f32_16x16x32_bf16 v[68:71], v[158:161], v[204:207], v[68:71]
	v_mfma_f32_16x16x32_bf16 v[64:67], v[172:175], v[204:207], v[64:67]
	v_mfma_f32_16x16x32_bf16 v[116:119], v[162:165], v[184:187], v[116:119]
	v_mfma_f32_16x16x32_bf16 v[112:115], v[176:179], v[184:187], v[112:115]
	v_mfma_f32_16x16x32_bf16 v[100:103], v[162:165], v[192:195], v[100:103]
	v_mfma_f32_16x16x32_bf16 v[96:99], v[176:179], v[192:195], v[96:99]
	v_mfma_f32_16x16x32_bf16 v[84:87], v[162:165], v[200:203], v[84:87]
	v_mfma_f32_16x16x32_bf16 v[80:83], v[176:179], v[200:203], v[80:83]
	v_mfma_f32_16x16x32_bf16 v[68:71], v[162:165], v[208:211], v[68:71]
	v_mfma_f32_16x16x32_bf16 v[64:67], v[176:179], v[208:211], v[64:67]
	s_barrier
	s_add_i32 s16, s55, s2
	v_lshl_add_u64 v[214:215], s[30:31], 0, v[146:147]
	s_mov_b32 m0, s16
	ds_read_b128 v[180:183], v169 offset:16384
	ds_read_b128 v[184:187], v169 offset:17408
	ds_read_b128 v[188:191], v169 offset:18432
	ds_read_b128 v[192:195], v169 offset:19456
	ds_read_b128 v[196:199], v169 offset:20480
	ds_read_b128 v[200:203], v169 offset:21504
	ds_read_b128 v[204:207], v169 offset:22528
	ds_read_b128 v[208:211], v169 offset:23552
	global_load_lds_dwordx4 v[214:215], off
	s_add_i32 m0, s16, 0x2000
	s_add_u32 s16, s30, 0x40000
	v_lshl_add_u64 v[216:217], s[30:31], 0, v[150:151]
	s_addc_u32 s17, s31, 0
	s_add_i32 s33, s64, s2
	global_load_lds_dwordx4 v[216:217], off
	v_lshl_add_u64 v[218:219], s[16:17], 0, v[146:147]
	s_mov_b32 m0, s33
	v_lshl_add_u64 v[220:221], s[34:35], 0, v[148:149]
	global_load_lds_dwordx4 v[218:219], off
	v_lshl_add_u64 v[218:219], s[16:17], 0, v[150:151]
	s_add_i32 m0, s33, 0x2000
	s_nop 0
	global_load_lds_dwordx4 v[218:219], off
	v_lshl_add_u64 v[218:219], s[34:35], 0, v[144:145]
	s_mov_b32 m0, s3
	s_nop 0
	global_load_lds_dwordx4 v[218:219], off
	s_mov_b32 m0, s36
	s_nop 0
	global_load_lds_dwordx4 v[220:221], off
	s_waitcnt vmcnt(8)
	s_waitcnt lgkmcnt(0)
	s_barrier
; #define PG8_STAGE(bufoff, gbase, voff) do { _Pragma("unroll") for (int _i = 0; _i < 2; ++_i) \
;     __builtin_amdgcn_global_load_lds((const unsigned*)((const char*)(gbase) + (voff)[_i]), (PG8_LAS unsigned*)(lds + (bufoff) + ldsw + _i * 8192), 16, 0, 0); } while (0)
; #define PG8_LDA(dst, b, h) do { _Pragma("unroll") for (int m = 0; m < 4; ++m) _Pragma("unroll") for (int k = 0; k < 2; ++k) dst[m][k] = *(const PG8_LAS bf16x8*)(lds + PG8_SA(b, h) + aoff + m * 2048 + k * 1024); } while (0)
; #define PG8_LDB(dst, b, h) do { _Pragma("unroll") for (int n = 0; n < 2; ++n) _Pragma("unroll") for (int k = 0; k < 2; ++k) dst[n][k] = *(const PG8_LAS bf16x8*)(lds + PG8_SB(b, h) + boff + n * 2048 + k * 1024); } while (0)
; #define PG8_MMA(ai, bj, At, Bt) do { __builtin_amdgcn_s_setprio(1); _Pragma("unroll") for (int m = 0; m < 4; ++m) _Pragma("unroll") for (int n = 0; n < 2; ++n) _Pragma("unroll") for (int k = 0; k < 2; ++k) \
;     acc[ai][bj][m][n] = __builtin_amdgcn_mfma_f32_16x16x32_bf16(Bt[n][k], At[m][k], acc[ai][bj][m][n], 0, 0, 0); __builtin_amdgcn_s_setprio(0); } while (0)
; #define PG8_WAIT_V(n) asm volatile("s_waitcnt vmcnt(" #n ")" ::: "memory")
; #define PG8_WAIT_L(n) asm volatile("s_waitcnt lgkmcnt(" #n ")" ::: "memory")
; #define PG8_BAR __builtin_amdgcn_s_barrier()
; #define PG8_SCHED __builtin_amdgcn_sched_barrier(0)
; template <class Epi, class Sched>
; DI void gemm_phase(PG8_LAS unsigned char* lds, const Gemm g, const Sched& S, const Epi& E) {
;     ...
;       PG8_WAIT_V(8); PG8_WAIT_L(0); PG8_BAR; PG8_MMA(0, 0, At, B0); PG8_MMA(0, 1, At, B1); PG8_BAR; PG8_SCHED;
;       PG8_LDA(At, 0, 1); PG8_STAGE(PG8_SB(0, 0), b2, voffB); PG8_STAGE(PG8_SB(0, 1), b2 + hstepB, voffB); PG8_STAGE(PG8_SA(0, 0), a2, voffA);
;       PG8_WAIT_V(8); PG8_WAIT_L(0); PG8_BAR; PG8_MMA(1, 0, At, B0); PG8_MMA(1, 1, At, B1); PG8_BAR; PG8_SCHED;
;       PG8_LDB(B0, 1, 0); PG8_LDB(B1, 1, 1); PG8_SCHED; PG8_LDA(At, 1, 0); PG8_STAGE(PG8_SA(0, 1), a2 + hstepA, voffA);
;       PG8_WAIT_V(8); PG8_WAIT_L(0); PG8_BAR; PG8_MMA(0, 0, At, B0); PG8_MMA(0, 1, At, B1); PG8_BAR; PG8_SCHED;
	s_waitcnt lgkmcnt(0)
	v_mfma_f32_16x16x32_bf16 v[60:63], v[128:131], v[180:183], v[60:63]
	v_mfma_f32_16x16x32_bf16 v[56:59], v[136:139], v[180:183], v[56:59]
	v_mfma_f32_16x16x32_bf16 v[44:47], v[128:131], v[188:191], v[44:47]
	v_mfma_f32_16x16x32_bf16 v[40:43], v[136:139], v[188:191], v[40:43]
	v_mfma_f32_16x16x32_bf16 v[28:31], v[128:131], v[196:199], v[28:31]
	v_mfma_f32_16x16x32_bf16 v[24:27], v[136:139], v[196:199], v[24:27]
	v_mfma_f32_16x16x32_bf16 v[12:15], v[128:131], v[204:207], v[12:15]
	v_mfma_f32_16x16x32_bf16 v[8:11], v[136:139], v[204:207], v[8:11]
	v_mfma_f32_16x16x32_bf16 v[60:63], v[132:135], v[184:187], v[60:63]
	v_mfma_f32_16x16x32_bf16 v[56:59], v[140:143], v[184:187], v[56:59]
	v_mfma_f32_16x16x32_bf16 v[44:47], v[132:135], v[192:195], v[44:47]
	v_mfma_f32_16x16x32_bf16 v[40:43], v[140:143], v[192:195], v[40:43]
	v_mfma_f32_16x16x32_bf16 v[28:31], v[132:135], v[200:203], v[28:31]
	v_mfma_f32_16x16x32_bf16 v[24:27], v[140:143], v[200:203], v[24:27]
	v_mfma_f32_16x16x32_bf16 v[12:15], v[132:135], v[208:211], v[12:15]
	v_mfma_f32_16x16x32_bf16 v[8:11], v[140:143], v[208:211], v[8:11]
	v_mfma_f32_16x16x32_bf16 v[52:55], v[158:161], v[180:183], v[52:55]
	v_mfma_f32_16x16x32_bf16 v[48:51], v[172:175], v[180:183], v[48:51]
	v_mfma_f32_16x16x32_bf16 v[36:39], v[158:161], v[188:191], v[36:39]
	v_mfma_f32_16x16x32_bf16 v[32:35], v[172:175], v[188:191], v[32:35]
	v_mfma_f32_16x16x32_bf16 v[20:23], v[158:161], v[196:199], v[20:23]
	v_mfma_f32_16x16x32_bf16 v[16:19], v[172:175], v[196:199], v[16:19]
	v_mfma_f32_16x16x32_bf16 v[4:7], v[158:161], v[204:207], v[4:7]
	v_mfma_f32_16x16x32_bf16 v[0:3], v[172:175], v[204:207], v[0:3]
	v_mfma_f32_16x16x32_bf16 v[52:55], v[162:165], v[184:187], v[52:55]
	v_mfma_f32_16x16x32_bf16 v[48:51], v[176:179], v[184:187], v[48:51]
	v_mfma_f32_16x16x32_bf16 v[36:39], v[162:165], v[192:195], v[36:39]
	v_mfma_f32_16x16x32_bf16 v[32:35], v[176:179], v[192:195], v[32:35]
	v_mfma_f32_16x16x32_bf16 v[20:23], v[162:165], v[200:203], v[20:23]
	v_mfma_f32_16x16x32_bf16 v[16:19], v[176:179], v[200:203], v[16:19]
	v_mfma_f32_16x16x32_bf16 v[4:7], v[162:165], v[208:211], v[4:7]
	v_mfma_f32_16x16x32_bf16 v[0:3], v[176:179], v[208:211], v[0:3]
	s_barrier
	s_add_i32 s33, s41, 0x110
	v_add_u32_e32 v140, s33, v166
	ds_read_b128 v[128:131], v140
	ds_read_b128 v[132:135], v140 offset:1024
	ds_read_b128 v[136:139], v140 offset:2048
	ds_read_b128 v[140:143], v140 offset:3072
	ds_read_b128 v[158:161], v171
	ds_read_b128 v[162:165], v171 offset:1024
	ds_read_b128 v[172:175], v171 offset:2048
	ds_read_b128 v[176:179], v171 offset:3072
	s_add_u32 s16, s34, 0x40000
	s_addc_u32 s17, s35, 0
	s_mov_b32 m0, s37
	v_lshl_add_u64 v[222:223], s[16:17], 0, v[144:145]
	ds_read_b128 v[180:183], v169 offset:32768
	ds_read_b128 v[184:187], v169 offset:33792
	ds_read_b128 v[188:191], v169 offset:34816
	ds_read_b128 v[192:195], v169 offset:35840
	ds_read_b128 v[196:199], v169 offset:36864
	ds_read_b128 v[200:203], v169 offset:37888
	ds_read_b128 v[204:207], v169 offset:38912
	ds_read_b128 v[208:211], v169 offset:39936
	global_load_lds_dwordx4 v[222:223], off
	v_lshl_add_u64 v[222:223], s[16:17], 0, v[148:149]
	s_mov_b32 m0, s38
	s_nop 0
	global_load_lds_dwordx4 v[222:223], off
	s_waitcnt vmcnt(8)
	s_waitcnt lgkmcnt(0)
	s_barrier
	s_waitcnt lgkmcnt(0)
	v_mfma_f32_16x16x32_bf16 v[124:127], v[128:131], v[180:183], v[124:127]
	v_mfma_f32_16x16x32_bf16 v[120:123], v[136:139], v[180:183], v[120:123]
	v_mfma_f32_16x16x32_bf16 v[108:111], v[128:131], v[188:191], v[108:111]
	v_mfma_f32_16x16x32_bf16 v[104:107], v[136:139], v[188:191], v[104:107]
	v_mfma_f32_16x16x32_bf16 v[92:95], v[128:131], v[196:199], v[92:95]
	v_mfma_f32_16x16x32_bf16 v[88:91], v[136:139], v[196:199], v[88:91]
	v_mfma_f32_16x16x32_bf16 v[76:79], v[128:131], v[204:207], v[76:79]
	v_mfma_f32_16x16x32_bf16 v[72:75], v[136:139], v[204:207], v[72:75]
	v_mfma_f32_16x16x32_bf16 v[124:127], v[132:135], v[184:187], v[124:127]
	v_mfma_f32_16x16x32_bf16 v[120:123], v[140:143], v[184:187], v[120:123]
	v_mfma_f32_16x16x32_bf16 v[108:111], v[132:135], v[192:195], v[108:111]
	v_mfma_f32_16x16x32_bf16 v[104:107], v[140:143], v[192:195], v[104:107]
	v_mfma_f32_16x16x32_bf16 v[92:95], v[132:135], v[200:203], v[92:95]
	v_mfma_f32_16x16x32_bf16 v[88:91], v[140:143], v[200:203], v[88:91]
	v_mfma_f32_16x16x32_bf16 v[76:79], v[132:135], v[208:211], v[76:79]
	v_mfma_f32_16x16x32_bf16 v[72:75], v[140:143], v[208:211], v[72:75]
	v_mfma_f32_16x16x32_bf16 v[116:119], v[158:161], v[180:183], v[116:119]
	v_mfma_f32_16x16x32_bf16 v[112:115], v[172:175], v[180:183], v[112:115]
	v_mfma_f32_16x16x32_bf16 v[100:103], v[158:161], v[188:191], v[100:103]
	v_mfma_f32_16x16x32_bf16 v[96:99], v[172:175], v[188:191], v[96:99]
	v_mfma_f32_16x16x32_bf16 v[84:87], v[158:161], v[196:199], v[84:87]
	v_mfma_f32_16x16x32_bf16 v[80:83], v[172:175], v[196:199], v[80:83]
	v_mfma_f32_16x16x32_bf16 v[68:71], v[158:161], v[204:207], v[68:71]
	v_mfma_f32_16x16x32_bf16 v[64:67], v[172:175], v[204:207], v[64:67]
	v_mfma_f32_16x16x32_bf16 v[116:119], v[162:165], v[184:187], v[116:119]
	v_mfma_f32_16x16x32_bf16 v[112:115], v[176:179], v[184:187], v[112:115]
	v_mfma_f32_16x16x32_bf16 v[100:103], v[162:165], v[192:195], v[100:103]
	v_mfma_f32_16x16x32_bf16 v[96:99], v[176:179], v[192:195], v[96:99]
	v_mfma_f32_16x16x32_bf16 v[84:87], v[162:165], v[200:203], v[84:87]
	v_mfma_f32_16x16x32_bf16 v[80:83], v[176:179], v[200:203], v[80:83]
	v_mfma_f32_16x16x32_bf16 v[68:71], v[162:165], v[208:211], v[68:71]
	v_mfma_f32_16x16x32_bf16 v[64:67], v[176:179], v[208:211], v[64:67]
	s_barrier
; #define PG8_STAGE(bufoff, gbase, voff) do { _Pragma("unroll") for (int _i = 0; _i < 2; ++_i) \
;     __builtin_amdgcn_global_load_lds((const unsigned*)((const char*)(gbase) + (voff)[_i]), (PG8_LAS unsigned*)(lds + (bufoff) + ldsw + _i * 8192), 16, 0, 0); } while (0)
; #define PG8_LDA(dst, b, h) do { _Pragma("unroll") for (int m = 0; m < 4; ++m) _Pragma("unroll") for (int k = 0; k < 2; ++k) dst[m][k] = *(const PG8_LAS bf16x8*)(lds + PG8_SA(b, h) + aoff + m * 2048 + k * 1024); } while (0)
; #define PG8_MMA(ai, bj, At, Bt) do { __builtin_amdgcn_s_setprio(1); _Pragma("unroll") for (int m = 0; m < 4; ++m) _Pragma("unroll") for (int n = 0; n < 2; ++n) _Pragma("unroll") for (int k = 0; k < 2; ++k) \
;     acc[ai][bj][m][n] = __builtin_amdgcn_mfma_f32_16x16x32_bf16(Bt[n][k], At[m][k], acc[ai][bj][m][n], 0, 0, 0); __builtin_amdgcn_s_setprio(0); } while (0)
; #define PG8_WAIT_V(n) asm volatile("s_waitcnt vmcnt(" #n ")" ::: "memory")
; #define PG8_WAIT_L(n) asm volatile("s_waitcnt lgkmcnt(" #n ")" ::: "memory")
; #define PG8_BAR __builtin_amdgcn_s_barrier()
; #define PG8_SCHED __builtin_amdgcn_sched_barrier(0)
;   DI void operator()(const f32x4 (&acc)[2][2][4][2], const Unit& u, int wr, int wc, int fr, int fq) const {
;     ...
;     RES_LD(0)
; template <class Epi, class Sched>
; DI void gemm_phase(PG8_LAS unsigned char* lds, const Gemm g, const Sched& S, const Epi& E) {
;     ...
;       PG8_LDA(At, 1, 1); PG8_STAGE(PG8_SB(1, 0), b3, voffB); PG8_STAGE(PG8_SB(1, 1), b3 + hstepB, voffB); PG8_STAGE(PG8_SA(1, 0), a3, voffA);
;       PG8_WAIT_V(8); PG8_WAIT_L(0); PG8_BAR; PG8_MMA(1, 0, At, B0); PG8_MMA(1, 1, At, B1); PG8_BAR; PG8_SCHED;
;     }
;     if (wr == 0) PG8_BAR;
;     E(acc, cur, wr, wc, fr, fq);
	s_add_i32 s16, s33, s2
	v_lshl_add_u64 v[214:215], v[214:215], 0, s[8:9]
	s_mov_b32 m0, s16
	ds_read_b128 v[180:183], v169 offset:49152
	ds_read_b128 v[184:187], v169 offset:50176
	ds_read_b128 v[188:191], v169 offset:51200
	ds_read_b128 v[192:195], v169 offset:52224
	ds_read_b128 v[196:199], v169 offset:53248
	ds_read_b128 v[200:203], v169 offset:54272
	ds_read_b128 v[204:207], v169 offset:55296
	ds_read_b128 v[208:211], v169 offset:56320
	global_load_lds_dwordx4 v[214:215], off
	s_add_i32 m0, s16, 0x2000
	s_add_u32 s16, s30, 0x40080
	v_lshl_add_u64 v[214:215], v[216:217], 0, s[8:9]
	s_addc_u32 s17, s31, 0
	s_add_i32 s30, s65, s2
	global_load_lds_dwordx4 v[214:215], off
	v_lshl_add_u64 v[214:215], s[16:17], 0, v[146:147]
	s_mov_b32 m0, s30
	s_nop 0
	global_load_lds_dwordx4 v[214:215], off
	v_lshl_add_u64 v[214:215], s[16:17], 0, v[150:151]
	s_add_i32 m0, s30, 0x2000
	s_nop 0
	global_load_lds_dwordx4 v[214:215], off
	v_lshl_add_u64 v[214:215], v[218:219], 0, s[8:9]
	s_mov_b32 m0, s4
	s_nop 0
	global_load_lds_dwordx4 v[214:215], off
	v_lshl_add_u64 v[214:215], v[220:221], 0, s[8:9]
	s_mov_b32 m0, s5
	s_nop 0
	global_load_lds_dwordx4 v[214:215], off
	s_waitcnt vmcnt(8)
	s_waitcnt lgkmcnt(0)
	s_barrier
	s_waitcnt lgkmcnt(0)
	v_mfma_f32_16x16x32_bf16 v[60:63], v[128:131], v[180:183], v[60:63]
	v_mfma_f32_16x16x32_bf16 v[56:59], v[136:139], v[180:183], v[56:59]
	v_mfma_f32_16x16x32_bf16 v[44:47], v[128:131], v[188:191], v[44:47]
	v_mfma_f32_16x16x32_bf16 v[40:43], v[136:139], v[188:191], v[40:43]
	v_mfma_f32_16x16x32_bf16 v[28:31], v[128:131], v[196:199], v[28:31]
	v_mfma_f32_16x16x32_bf16 v[24:27], v[136:139], v[196:199], v[24:27]
	v_mfma_f32_16x16x32_bf16 v[12:15], v[128:131], v[204:207], v[12:15]
	v_mfma_f32_16x16x32_bf16 v[8:11], v[136:139], v[204:207], v[8:11]
	v_mfma_f32_16x16x32_bf16 v[60:63], v[132:135], v[184:187], v[60:63]
	v_mfma_f32_16x16x32_bf16 v[56:59], v[140:143], v[184:187], v[56:59]
	v_mfma_f32_16x16x32_bf16 v[44:47], v[132:135], v[192:195], v[44:47]
	v_mfma_f32_16x16x32_bf16 v[40:43], v[140:143], v[192:195], v[40:43]
	v_mfma_f32_16x16x32_bf16 v[28:31], v[132:135], v[200:203], v[28:31]
	v_mfma_f32_16x16x32_bf16 v[24:27], v[140:143], v[200:203], v[24:27]
	v_mfma_f32_16x16x32_bf16 v[12:15], v[132:135], v[208:211], v[12:15]
	v_mfma_f32_16x16x32_bf16 v[8:11], v[140:143], v[208:211], v[8:11]
	v_mfma_f32_16x16x32_bf16 v[52:55], v[158:161], v[180:183], v[52:55]
	v_mfma_f32_16x16x32_bf16 v[48:51], v[172:175], v[180:183], v[48:51]
	v_mfma_f32_16x16x32_bf16 v[36:39], v[158:161], v[188:191], v[36:39]
	v_mfma_f32_16x16x32_bf16 v[32:35], v[172:175], v[188:191], v[32:35]
	v_mfma_f32_16x16x32_bf16 v[20:23], v[158:161], v[196:199], v[20:23]
	v_mfma_f32_16x16x32_bf16 v[16:19], v[172:175], v[196:199], v[16:19]
	v_mfma_f32_16x16x32_bf16 v[4:7], v[158:161], v[204:207], v[4:7]
	v_mfma_f32_16x16x32_bf16 v[0:3], v[172:175], v[204:207], v[0:3]
	v_mfma_f32_16x16x32_bf16 v[52:55], v[162:165], v[184:187], v[52:55]
	v_mfma_f32_16x16x32_bf16 v[48:51], v[176:179], v[184:187], v[48:51]
	v_mfma_f32_16x16x32_bf16 v[36:39], v[162:165], v[192:195], v[36:39]
	v_mfma_f32_16x16x32_bf16 v[32:35], v[176:179], v[192:195], v[32:35]
	v_mfma_f32_16x16x32_bf16 v[20:23], v[162:165], v[200:203], v[20:23]
	v_mfma_f32_16x16x32_bf16 v[16:19], v[176:179], v[200:203], v[16:19]
	v_mfma_f32_16x16x32_bf16 v[4:7], v[162:165], v[208:211], v[4:7]
	v_mfma_f32_16x16x32_bf16 v[0:3], v[176:179], v[208:211], v[0:3]
	s_barrier
	s_add_i32 s70, s70, 2
	s_add_u32 s28, s28, 0x100
	s_addc_u32 s29, s29, 0
	s_add_u32 s68, s68, 0x100
	s_addc_u32 s69, s69, 0
	s_cmp_gt_u32 s70, 13
	s_cbranch_scc0 .LBB0_563
	v_lshl_add_u32 v164, s26, 8, v153
	v_ashrrev_i32_e32 v165, 31, v164
	s_lshl_b32 s16, s12, 8
	v_lshlrev_b64 v[128:129], 10, v[164:165]
	s_ashr_i32 s17, s16, 31
	v_lshl_add_u64 v[186:187], v[128:129], 0, s[16:17]
	v_or_b32_e32 v186, v186, v152
	v_lshl_add_u64 v[162:163], v[186:187], 2, s[44:45]
	s_mov_b64 s[16:17], 0x10000
	v_add_co_u32_e32 v130, vcc, s39, v162
	global_load_dwordx4 v[158:161], v[162:163], off offset:16
	global_load_dwordx4 v[174:177], v[162:163], off
	global_load_dwordx4 v[178:181], v[162:163], off offset:528
	global_load_dwordx4 v[182:185], v[162:163], off offset:512
	v_lshl_add_u64 v[128:129], v[162:163], 0, s[16:17]
	v_addc_co_u32_e32 v131, vcc, 0, v163, vcc
	s_mov_b64 s[16:17], 0x10200
	global_load_dwordx4 v[140:143], v[130:131], off
	global_load_dwordx4 v[136:139], v[128:129], off offset:16
	v_lshl_add_u64 v[128:129], v[162:163], 0, s[16:17]
	global_load_dwordx4 v[132:135], v[130:131], off offset:512
	s_nop 0
	global_load_dwordx4 v[128:131], v[128:129], off offset:16
	s_and_b64 vcc, exec, s[10:11]
	s_cbranch_vccz .LBB0_566
	s_barrier

; #define PG8_STAGE(bufoff, gbase, voff) do { _Pragma("unroll") for (int _i = 0; _i < 2; ++_i) \
;     __builtin_amdgcn_global_load_lds((const unsigned*)((const char*)(gbase) + (voff)[_i]), (PG8_LAS unsigned*)(lds + (bufoff) + ldsw + _i * 8192), 16, 0, 0); } while (0)
; #define PG8_LDA(dst, b, h) do { _Pragma("unroll") for (int m = 0; m < 4; ++m) _Pragma("unroll") for (int k = 0; k < 2; ++k) dst[m][k] = *(const PG8_LAS bf16x8*)(lds + PG8_SA(b, h) + aoff + m * 2048 + k * 1024); } while (0)
; #define PG8_LDB(dst, b, h) do { _Pragma("unroll") for (int n = 0; n < 2; ++n) _Pragma("unroll") for (int k = 0; k < 2; ++k) dst[n][k] = *(const PG8_LAS bf16x8*)(lds + PG8_SB(b, h) + boff + n * 2048 + k * 1024); } while (0)
; #define PG8_MMA(ai, bj, At, Bt) do { __builtin_amdgcn_s_setprio(1); _Pragma("unroll") for (int m = 0; m < 4; ++m) _Pragma("unroll") for (int n = 0; n < 2; ++n) _Pragma("unroll") for (int k = 0; k < 2; ++k) \
;     acc[ai][bj][m][n] = __builtin_amdgcn_mfma_f32_16x16x32_bf16(Bt[n][k], At[m][k], acc[ai][bj][m][n], 0, 0, 0); __builtin_amdgcn_s_setprio(0); } while (0)
; #define PG8_WAIT_V(n) asm volatile("s_waitcnt vmcnt(" #n ")" ::: "memory")
; #define PG8_BAR __builtin_amdgcn_s_barrier()
; template <class Epi, class Sched>
; DI void gemm_phase(PG8_LAS unsigned char* lds, const Gemm g, const Sched& S, const Epi& E) {
;     ...
;     const bool has_next = S.next(ui + 1, nxt);
;     const char* nA = has_next ? (const char*)g.A + (size_t)nxt.pm * tstepA : cA; const char* nB = has_next ? (const char*)g.Bt + (size_t)nxt.pn * tstepB : cB;
; #pragma unroll 1
;     for (int t = 0; t < nt; t += 2) {
;       const bool last = (t == nt - 2);
;       const char* a1 = cA + (size_t)(t + 1) * kstep;
;       const char* a2 = last ? nA : cA + (size_t)(t + 2) * kstep; const char* b2 = last ? nB : cB + (size_t)(t + 2) * kstep;
;       const char* a3 = a2 + kstep; const char* b3 = b2 + kstep;
;       PG8_LDB(B0, 0, 0); PG8_LDB(B1, 0, 1); PG8_SCHED; PG8_LDA(At, 0, 0); PG8_STAGE(PG8_SA(1, 1), a1 + hstepA, voffA);
;       PG8_WAIT_V(8); PG8_WAIT_L(0); PG8_BAR; PG8_MMA(0, 0, At, B0); PG8_MMA(0, 1, At, B1); PG8_BAR; PG8_SCHED;
;       PG8_LDA(At, 0, 1); PG8_STAGE(PG8_SB(0, 0), b2, voffB); PG8_STAGE(PG8_SB(0, 1), b2 + hstepB, voffB); PG8_STAGE(PG8_SA(0, 0), a2, voffA);
;       PG8_WAIT_V(8); PG8_WAIT_L(0); PG8_BAR; PG8_MMA(1, 0, At, B0); PG8_MMA(1, 1, At, B1); PG8_BAR; PG8_SCHED;
.LBB0_647:
	ds_read_b128 v[144:147], v157
	ds_read_b128 v[148:151], v157 offset:1024
	ds_read_b128 v[174:177], v157 offset:2048
	ds_read_b128 v[178:181], v157 offset:3072
	ds_read_b128 v[182:185], v161
	ds_read_b128 v[186:189], v161 offset:1024
	ds_read_b128 v[190:193], v161 offset:2048
	ds_read_b128 v[194:197], v161 offset:3072
	s_add_u32 s16, s6, 0xfffc0080
	s_addc_u32 s17, s7, -1
	s_cmp_eq_u32 s68, 12
	s_cselect_b32 s37, s1, s17
	s_cselect_b32 s36, s25, s16
	s_cselect_b32 s35, s23, s67
	s_cselect_b32 s34, s65, s66
	v_lshl_add_u64 v[154:155], s[6:7], 0, v[140:141]
	s_add_i32 m0, s21, 0xc000
	ds_read_b128 v[198:201], v165
	ds_read_b128 v[202:205], v165 offset:1024
	ds_read_b128 v[206:209], v165 offset:2048
	ds_read_b128 v[214:217], v165 offset:3072
	ds_read_b128 v[218:221], v165 offset:4096
	ds_read_b128 v[222:225], v165 offset:5120
	ds_read_b128 v[226:229], v165 offset:6144
	ds_read_b128 v[230:233], v165 offset:7168
	global_load_lds_dwordx4 v[154:155], off
	v_lshl_add_u64 v[154:155], s[6:7], 0, v[142:143]
	s_add_i32 m0, s21, 0xe000
	s_nop 0
	global_load_lds_dwordx4 v[154:155], off
	s_waitcnt vmcnt(8)
	s_waitcnt lgkmcnt(0)
	s_barrier
	s_waitcnt lgkmcnt(0)
	v_mfma_f32_16x16x32_bf16 v[124:127], v[144:147], v[198:201], v[124:127]
	v_mfma_f32_16x16x32_bf16 v[120:123], v[174:177], v[198:201], v[120:123]
	v_mfma_f32_16x16x32_bf16 v[108:111], v[144:147], v[206:209], v[108:111]
	v_mfma_f32_16x16x32_bf16 v[104:107], v[174:177], v[206:209], v[104:107]
	v_mfma_f32_16x16x32_bf16 v[92:95], v[144:147], v[218:221], v[92:95]
	v_mfma_f32_16x16x32_bf16 v[88:91], v[174:177], v[218:221], v[88:91]
	v_mfma_f32_16x16x32_bf16 v[76:79], v[144:147], v[226:229], v[76:79]
	v_mfma_f32_16x16x32_bf16 v[72:75], v[174:177], v[226:229], v[72:75]
	v_mfma_f32_16x16x32_bf16 v[124:127], v[148:151], v[202:205], v[124:127]
	v_mfma_f32_16x16x32_bf16 v[120:123], v[178:181], v[202:205], v[120:123]
	v_mfma_f32_16x16x32_bf16 v[108:111], v[148:151], v[214:217], v[108:111]
	v_mfma_f32_16x16x32_bf16 v[104:107], v[178:181], v[214:217], v[104:107]
	v_mfma_f32_16x16x32_bf16 v[92:95], v[148:151], v[222:225], v[92:95]
	v_mfma_f32_16x16x32_bf16 v[88:91], v[178:181], v[222:225], v[88:91]
	v_mfma_f32_16x16x32_bf16 v[76:79], v[148:151], v[230:233], v[76:79]
	v_mfma_f32_16x16x32_bf16 v[72:75], v[178:181], v[230:233], v[72:75]
	v_mfma_f32_16x16x32_bf16 v[116:119], v[182:185], v[198:201], v[116:119]
	v_mfma_f32_16x16x32_bf16 v[112:115], v[190:193], v[198:201], v[112:115]
	v_mfma_f32_16x16x32_bf16 v[100:103], v[182:185], v[206:209], v[100:103]
	v_mfma_f32_16x16x32_bf16 v[96:99], v[190:193], v[206:209], v[96:99]
	v_mfma_f32_16x16x32_bf16 v[84:87], v[182:185], v[218:221], v[84:87]
	v_mfma_f32_16x16x32_bf16 v[80:83], v[190:193], v[218:221], v[80:83]
	v_mfma_f32_16x16x32_bf16 v[68:71], v[182:185], v[226:229], v[68:71]
	v_mfma_f32_16x16x32_bf16 v[64:67], v[190:193], v[226:229], v[64:67]
	v_mfma_f32_16x16x32_bf16 v[116:119], v[186:189], v[202:205], v[116:119]
	v_mfma_f32_16x16x32_bf16 v[112:115], v[194:197], v[202:205], v[112:115]
	v_mfma_f32_16x16x32_bf16 v[100:103], v[186:189], v[214:217], v[100:103]
	v_mfma_f32_16x16x32_bf16 v[96:99], v[194:197], v[214:217], v[96:99]
	v_mfma_f32_16x16x32_bf16 v[84:87], v[186:189], v[222:225], v[84:87]
	v_mfma_f32_16x16x32_bf16 v[80:83], v[194:197], v[222:225], v[80:83]
	v_mfma_f32_16x16x32_bf16 v[68:71], v[186:189], v[230:233], v[68:71]
	v_mfma_f32_16x16x32_bf16 v[64:67], v[194:197], v[230:233], v[64:67]
	s_barrier
	s_add_i32 s16, s39, s2
	v_lshl_add_u64 v[154:155], s[34:35], 0, v[132:133]
	s_mov_b32 m0, s16
	ds_read_b128 v[198:201], v165 offset:16384
	ds_read_b128 v[202:205], v165 offset:17408
	ds_read_b128 v[206:209], v165 offset:18432
	ds_read_b128 v[214:217], v165 offset:19456
	ds_read_b128 v[218:221], v165 offset:20480
	ds_read_b128 v[222:225], v165 offset:21504
	ds_read_b128 v[226:229], v165 offset:22528
	ds_read_b128 v[230:233], v165 offset:23552
	global_load_lds_dwordx4 v[154:155], off
	s_add_i32 m0, s16, 0x2000
	s_add_u32 s16, s34, 0x40000
	v_lshl_add_u64 v[158:159], s[34:35], 0, v[128:129]
	s_addc_u32 s17, s35, 0
	s_add_i32 s33, s40, s2
	global_load_lds_dwordx4 v[158:159], off
	v_lshl_add_u64 v[162:163], s[16:17], 0, v[132:133]
	s_mov_b32 m0, s33
	v_lshl_add_u64 v[166:167], s[36:37], 0, v[130:131]
	global_load_lds_dwordx4 v[162:163], off
	v_lshl_add_u64 v[162:163], s[16:17], 0, v[128:129]
	s_add_i32 m0, s33, 0x2000
	s_nop 0
	global_load_lds_dwordx4 v[162:163], off
	v_lshl_add_u64 v[162:163], s[36:37], 0, v[134:135]
	s_mov_b32 m0, s21
	s_nop 0
	global_load_lds_dwordx4 v[162:163], off
	s_mov_b32 m0, s4
	s_nop 0
	global_load_lds_dwordx4 v[166:167], off
	s_waitcnt vmcnt(8)
	s_waitcnt lgkmcnt(0)
	s_barrier
; #define PG8_STAGE(bufoff, gbase, voff) do { _Pragma("unroll") for (int _i = 0; _i < 2; ++_i) \
;     __builtin_amdgcn_global_load_lds((const unsigned*)((const char*)(gbase) + (voff)[_i]), (PG8_LAS unsigned*)(lds + (bufoff) + ldsw + _i * 8192), 16, 0, 0); } while (0)
; #define PG8_LDA(dst, b, h) do { _Pragma("unroll") for (int m = 0; m < 4; ++m) _Pragma("unroll") for (int k = 0; k < 2; ++k) dst[m][k] = *(const PG8_LAS bf16x8*)(lds + PG8_SA(b, h) + aoff + m * 2048 + k * 1024); } while (0)
; #define PG8_LDB(dst, b, h) do { _Pragma("unroll") for (int n = 0; n < 2; ++n) _Pragma("unroll") for (int k = 0; k < 2; ++k) dst[n][k] = *(const PG8_LAS bf16x8*)(lds + PG8_SB(b, h) + boff + n * 2048 + k * 1024); } while (0)
; #define PG8_MMA(ai, bj, At, Bt) do { __builtin_amdgcn_s_setprio(1); _Pragma("unroll") for (int m = 0; m < 4; ++m) _Pragma("unroll") for (int n = 0; n < 2; ++n) _Pragma("unroll") for (int k = 0; k < 2; ++k) \
;     acc[ai][bj][m][n] = __builtin_amdgcn_mfma_f32_16x16x32_bf16(Bt[n][k], At[m][k], acc[ai][bj][m][n], 0, 0, 0); __builtin_amdgcn_s_setprio(0); } while (0)
; #define PG8_WAIT_V(n) asm volatile("s_waitcnt vmcnt(" #n ")" ::: "memory")
; #define PG8_WAIT_L(n) asm volatile("s_waitcnt lgkmcnt(" #n ")" ::: "memory")
; #define PG8_BAR __builtin_amdgcn_s_barrier()
; #define PG8_SCHED __builtin_amdgcn_sched_barrier(0)
; template <class Epi, class Sched>
; DI void gemm_phase(PG8_LAS unsigned char* lds, const Gemm g, const Sched& S, const Epi& E) {
;     ...
;       PG8_WAIT_V(8); PG8_WAIT_L(0); PG8_BAR; PG8_MMA(1, 0, At, B0); PG8_MMA(1, 1, At, B1); PG8_BAR; PG8_SCHED;
;       PG8_LDB(B0, 1, 0); PG8_LDB(B1, 1, 1); PG8_SCHED; PG8_LDA(At, 1, 0); PG8_STAGE(PG8_SA(0, 1), a2 + hstepA, voffA);
;       PG8_WAIT_V(8); PG8_WAIT_L(0); PG8_BAR; PG8_MMA(0, 0, At, B0); PG8_MMA(0, 1, At, B1); PG8_BAR; PG8_SCHED;
	s_waitcnt lgkmcnt(0)
	v_mfma_f32_16x16x32_bf16 v[60:63], v[144:147], v[198:201], v[60:63]
	v_mfma_f32_16x16x32_bf16 v[56:59], v[174:177], v[198:201], v[56:59]
	v_mfma_f32_16x16x32_bf16 v[44:47], v[144:147], v[206:209], v[44:47]
	v_mfma_f32_16x16x32_bf16 v[40:43], v[174:177], v[206:209], v[40:43]
	v_mfma_f32_16x16x32_bf16 v[28:31], v[144:147], v[218:221], v[28:31]
	v_mfma_f32_16x16x32_bf16 v[24:27], v[174:177], v[218:221], v[24:27]
	v_mfma_f32_16x16x32_bf16 v[12:15], v[144:147], v[226:229], v[12:15]
	v_mfma_f32_16x16x32_bf16 v[8:11], v[174:177], v[226:229], v[8:11]
	v_mfma_f32_16x16x32_bf16 v[60:63], v[148:151], v[202:205], v[60:63]
	v_mfma_f32_16x16x32_bf16 v[56:59], v[178:181], v[202:205], v[56:59]
	v_mfma_f32_16x16x32_bf16 v[44:47], v[148:151], v[214:217], v[44:47]
	v_mfma_f32_16x16x32_bf16 v[40:43], v[178:181], v[214:217], v[40:43]
	v_mfma_f32_16x16x32_bf16 v[28:31], v[148:151], v[222:225], v[28:31]
	v_mfma_f32_16x16x32_bf16 v[24:27], v[178:181], v[222:225], v[24:27]
	v_mfma_f32_16x16x32_bf16 v[12:15], v[148:151], v[230:233], v[12:15]
	v_mfma_f32_16x16x32_bf16 v[8:11], v[178:181], v[230:233], v[8:11]
	v_mfma_f32_16x16x32_bf16 v[52:55], v[182:185], v[198:201], v[52:55]
	v_mfma_f32_16x16x32_bf16 v[48:51], v[190:193], v[198:201], v[48:51]
	v_mfma_f32_16x16x32_bf16 v[36:39], v[182:185], v[206:209], v[36:39]
	v_mfma_f32_16x16x32_bf16 v[32:35], v[190:193], v[206:209], v[32:35]
	v_mfma_f32_16x16x32_bf16 v[20:23], v[182:185], v[218:221], v[20:23]
	v_mfma_f32_16x16x32_bf16 v[16:19], v[190:193], v[218:221], v[16:19]
	v_mfma_f32_16x16x32_bf16 v[4:7], v[182:185], v[226:229], v[4:7]
	v_mfma_f32_16x16x32_bf16 v[0:3], v[190:193], v[226:229], v[0:3]
	v_mfma_f32_16x16x32_bf16 v[52:55], v[186:189], v[202:205], v[52:55]
	v_mfma_f32_16x16x32_bf16 v[48:51], v[194:197], v[202:205], v[48:51]
	v_mfma_f32_16x16x32_bf16 v[36:39], v[186:189], v[214:217], v[36:39]
	v_mfma_f32_16x16x32_bf16 v[32:35], v[194:197], v[214:217], v[32:35]
	v_mfma_f32_16x16x32_bf16 v[20:23], v[186:189], v[222:225], v[20:23]
	v_mfma_f32_16x16x32_bf16 v[16:19], v[194:197], v[222:225], v[16:19]
	v_mfma_f32_16x16x32_bf16 v[4:7], v[186:189], v[230:233], v[4:7]
	v_mfma_f32_16x16x32_bf16 v[0:3], v[194:197], v[230:233], v[0:3]
	s_barrier
	ds_read_b128 v[144:147], v171
	ds_read_b128 v[148:151], v171 offset:1024
	ds_read_b128 v[174:177], v171 offset:2048
	ds_read_b128 v[178:181], v171 offset:3072
	ds_read_b128 v[182:185], v173
	ds_read_b128 v[186:189], v173 offset:1024
	ds_read_b128 v[190:193], v173 offset:2048
	ds_read_b128 v[194:197], v173 offset:3072
	s_add_u32 s16, s36, 0x40000
	s_addc_u32 s17, s37, 0
	s_mov_b32 m0, s5
	v_lshl_add_u64 v[210:211], s[16:17], 0, v[134:135]
	ds_read_b128 v[198:201], v165 offset:32768
	ds_read_b128 v[202:205], v165 offset:33792
	ds_read_b128 v[206:209], v165 offset:34816
	ds_read_b128 v[214:217], v165 offset:35840
	ds_read_b128 v[218:221], v165 offset:36864
	ds_read_b128 v[222:225], v165 offset:37888
	ds_read_b128 v[226:229], v165 offset:38912
	ds_read_b128 v[230:233], v165 offset:39936
	global_load_lds_dwordx4 v[210:211], off
	v_lshl_add_u64 v[210:211], s[16:17], 0, v[130:131]
	s_mov_b32 m0, s18
	s_nop 0
	global_load_lds_dwordx4 v[210:211], off
	s_waitcnt vmcnt(8)
	s_waitcnt lgkmcnt(0)
	s_barrier
	s_waitcnt lgkmcnt(0)
	v_mfma_f32_16x16x32_bf16 v[124:127], v[144:147], v[198:201], v[124:127]
	v_mfma_f32_16x16x32_bf16 v[120:123], v[174:177], v[198:201], v[120:123]
	v_mfma_f32_16x16x32_bf16 v[108:111], v[144:147], v[206:209], v[108:111]
	v_mfma_f32_16x16x32_bf16 v[104:107], v[174:177], v[206:209], v[104:107]
	v_mfma_f32_16x16x32_bf16 v[92:95], v[144:147], v[218:221], v[92:95]
	v_mfma_f32_16x16x32_bf16 v[88:91], v[174:177], v[218:221], v[88:91]
	v_mfma_f32_16x16x32_bf16 v[76:79], v[144:147], v[226:229], v[76:79]
	v_mfma_f32_16x16x32_bf16 v[72:75], v[174:177], v[226:229], v[72:75]
	v_mfma_f32_16x16x32_bf16 v[124:127], v[148:151], v[202:205], v[124:127]
	v_mfma_f32_16x16x32_bf16 v[120:123], v[178:181], v[202:205], v[120:123]
	v_mfma_f32_16x16x32_bf16 v[108:111], v[148:151], v[214:217], v[108:111]
	v_mfma_f32_16x16x32_bf16 v[104:107], v[178:181], v[214:217], v[104:107]
	v_mfma_f32_16x16x32_bf16 v[92:95], v[148:151], v[222:225], v[92:95]
	v_mfma_f32_16x16x32_bf16 v[88:91], v[178:181], v[222:225], v[88:91]
	v_mfma_f32_16x16x32_bf16 v[76:79], v[148:151], v[230:233], v[76:79]
	v_mfma_f32_16x16x32_bf16 v[72:75], v[178:181], v[230:233], v[72:75]
	v_mfma_f32_16x16x32_bf16 v[116:119], v[182:185], v[198:201], v[116:119]
	v_mfma_f32_16x16x32_bf16 v[112:115], v[190:193], v[198:201], v[112:115]
	v_mfma_f32_16x16x32_bf16 v[100:103], v[182:185], v[206:209], v[100:103]
	v_mfma_f32_16x16x32_bf16 v[96:99], v[190:193], v[206:209], v[96:99]
	v_mfma_f32_16x16x32_bf16 v[84:87], v[182:185], v[218:221], v[84:87]
	v_mfma_f32_16x16x32_bf16 v[80:83], v[190:193], v[218:221], v[80:83]
	v_mfma_f32_16x16x32_bf16 v[68:71], v[182:185], v[226:229], v[68:71]
	v_mfma_f32_16x16x32_bf16 v[64:67], v[190:193], v[226:229], v[64:67]
	v_mfma_f32_16x16x32_bf16 v[116:119], v[186:189], v[202:205], v[116:119]
	v_mfma_f32_16x16x32_bf16 v[112:115], v[194:197], v[202:205], v[112:115]
	v_mfma_f32_16x16x32_bf16 v[100:103], v[186:189], v[214:217], v[100:103]
	v_mfma_f32_16x16x32_bf16 v[96:99], v[194:197], v[214:217], v[96:99]
	v_mfma_f32_16x16x32_bf16 v[84:87], v[186:189], v[222:225], v[84:87]
	v_mfma_f32_16x16x32_bf16 v[80:83], v[194:197], v[222:225], v[80:83]
	v_mfma_f32_16x16x32_bf16 v[68:71], v[186:189], v[230:233], v[68:71]
	v_mfma_f32_16x16x32_bf16 v[64:67], v[194:197], v[230:233], v[64:67]
	s_barrier
; #define PG8_STAGE(bufoff, gbase, voff) do { _Pragma("unroll") for (int _i = 0; _i < 2; ++_i) \
;     __builtin_amdgcn_global_load_lds((const unsigned*)((const char*)(gbase) + (voff)[_i]), (PG8_LAS unsigned*)(lds + (bufoff) + ldsw + _i * 8192), 16, 0, 0); } while (0)
; #define PG8_LDA(dst, b, h) do { _Pragma("unroll") for (int m = 0; m < 4; ++m) _Pragma("unroll") for (int k = 0; k < 2; ++k) dst[m][k] = *(const PG8_LAS bf16x8*)(lds + PG8_SA(b, h) + aoff + m * 2048 + k * 1024); } while (0)
; #define PG8_MMA(ai, bj, At, Bt) do { __builtin_amdgcn_s_setprio(1); _Pragma("unroll") for (int m = 0; m < 4; ++m) _Pragma("unroll") for (int n = 0; n < 2; ++n) _Pragma("unroll") for (int k = 0; k < 2; ++k) \
;     acc[ai][bj][m][n] = __builtin_amdgcn_mfma_f32_16x16x32_bf16(Bt[n][k], At[m][k], acc[ai][bj][m][n], 0, 0, 0); __builtin_amdgcn_s_setprio(0); } while (0)
; #define PG8_WAIT_V(n) asm volatile("s_waitcnt vmcnt(" #n ")" ::: "memory")
; #define PG8_WAIT_L(n) asm volatile("s_waitcnt lgkmcnt(" #n ")" ::: "memory")
; #define PG8_BAR __builtin_amdgcn_s_barrier()
; #define PG8_SCHED __builtin_amdgcn_sched_barrier(0)
; DI void rows_rstd(float (&rs)[2][4], const float* ps, const Unit& u, int wr, int fr, int fq, int p_lo, int p_hi, float inv_dim) {
;   f32x4 pv[2][4];
; #pragma unroll
;   for (int ai = 0; ai < 2; ++ai)
; #pragma unroll
;     for (int m = 0; m < 4; ++m) pv[ai][m] = *(const f32x4*)(ps + (size_t)(u.pm * BM + ai * HALF + wr * 64 + m * 16 + fr) * 16 + 4 * fq);
; template <class Epi, class Sched>
; DI void gemm_phase(PG8_LAS unsigned char* lds, const Gemm g, const Sched& S, const Epi& E) {
;     ...
;       PG8_LDA(At, 1, 1); PG8_STAGE(PG8_SB(1, 0), b3, voffB); PG8_STAGE(PG8_SB(1, 1), b3 + hstepB, voffB); PG8_STAGE(PG8_SA(1, 0), a3, voffA);
;       PG8_WAIT_V(8); PG8_WAIT_L(0); PG8_BAR; PG8_MMA(1, 0, At, B0); PG8_MMA(1, 1, At, B1); PG8_BAR; PG8_SCHED;
;     }
;     if (wr == 0) PG8_BAR;
;     E(acc, cur, wr, wc, fr, fq);
	s_add_i32 s16, s45, s2
	v_lshl_add_u64 v[154:155], v[154:155], 0, s[10:11]
	s_mov_b32 m0, s16
	ds_read_b128 v[198:201], v165 offset:49152
	ds_read_b128 v[202:205], v165 offset:50176
	ds_read_b128 v[206:209], v165 offset:51200
	ds_read_b128 v[214:217], v165 offset:52224
	ds_read_b128 v[218:221], v165 offset:53248
	ds_read_b128 v[222:225], v165 offset:54272
	ds_read_b128 v[226:229], v165 offset:55296
	ds_read_b128 v[230:233], v165 offset:56320
	global_load_lds_dwordx4 v[154:155], off
	s_add_i32 m0, s16, 0x2000
	s_add_u32 s16, s34, 0x40080
	v_lshl_add_u64 v[154:155], v[158:159], 0, s[10:11]
	s_addc_u32 s17, s35, 0
	s_add_i32 s33, s53, s2
	global_load_lds_dwordx4 v[154:155], off
	v_lshl_add_u64 v[154:155], s[16:17], 0, v[132:133]
	s_mov_b32 m0, s33
	s_nop 0
	global_load_lds_dwordx4 v[154:155], off
	v_lshl_add_u64 v[154:155], s[16:17], 0, v[128:129]
	s_add_i32 m0, s33, 0x2000
	s_nop 0
	global_load_lds_dwordx4 v[154:155], off
	v_lshl_add_u64 v[154:155], v[162:163], 0, s[10:11]
	s_mov_b32 m0, s19
	s_nop 0
	global_load_lds_dwordx4 v[154:155], off
	v_lshl_add_u64 v[154:155], v[166:167], 0, s[10:11]
	s_mov_b32 m0, s38
	s_nop 0
	global_load_lds_dwordx4 v[154:155], off
	s_waitcnt vmcnt(8)
	s_waitcnt lgkmcnt(0)
	s_barrier
	s_waitcnt lgkmcnt(0)
	v_mfma_f32_16x16x32_bf16 v[60:63], v[144:147], v[198:201], v[60:63]
	v_mfma_f32_16x16x32_bf16 v[56:59], v[174:177], v[198:201], v[56:59]
	v_mfma_f32_16x16x32_bf16 v[44:47], v[144:147], v[206:209], v[44:47]
	v_mfma_f32_16x16x32_bf16 v[40:43], v[174:177], v[206:209], v[40:43]
	v_mfma_f32_16x16x32_bf16 v[28:31], v[144:147], v[218:221], v[28:31]
	v_mfma_f32_16x16x32_bf16 v[24:27], v[174:177], v[218:221], v[24:27]
	v_mfma_f32_16x16x32_bf16 v[12:15], v[144:147], v[226:229], v[12:15]
	v_mfma_f32_16x16x32_bf16 v[8:11], v[174:177], v[226:229], v[8:11]
	v_mfma_f32_16x16x32_bf16 v[60:63], v[148:151], v[202:205], v[60:63]
	v_mfma_f32_16x16x32_bf16 v[56:59], v[178:181], v[202:205], v[56:59]
	v_mfma_f32_16x16x32_bf16 v[44:47], v[148:151], v[214:217], v[44:47]
	v_mfma_f32_16x16x32_bf16 v[40:43], v[178:181], v[214:217], v[40:43]
	v_mfma_f32_16x16x32_bf16 v[28:31], v[148:151], v[222:225], v[28:31]
	v_mfma_f32_16x16x32_bf16 v[24:27], v[178:181], v[222:225], v[24:27]
	v_mfma_f32_16x16x32_bf16 v[12:15], v[148:151], v[230:233], v[12:15]
	v_mfma_f32_16x16x32_bf16 v[8:11], v[178:181], v[230:233], v[8:11]
	v_mfma_f32_16x16x32_bf16 v[52:55], v[182:185], v[198:201], v[52:55]
	v_mfma_f32_16x16x32_bf16 v[48:51], v[190:193], v[198:201], v[48:51]
	v_mfma_f32_16x16x32_bf16 v[36:39], v[182:185], v[206:209], v[36:39]
	v_mfma_f32_16x16x32_bf16 v[32:35], v[190:193], v[206:209], v[32:35]
	v_mfma_f32_16x16x32_bf16 v[20:23], v[182:185], v[218:221], v[20:23]
	v_mfma_f32_16x16x32_bf16 v[16:19], v[190:193], v[218:221], v[16:19]
	v_mfma_f32_16x16x32_bf16 v[4:7], v[182:185], v[226:229], v[4:7]
	v_mfma_f32_16x16x32_bf16 v[0:3], v[190:193], v[226:229], v[0:3]
	v_mfma_f32_16x16x32_bf16 v[52:55], v[186:189], v[202:205], v[52:55]
	v_mfma_f32_16x16x32_bf16 v[48:51], v[194:197], v[202:205], v[48:51]
	v_mfma_f32_16x16x32_bf16 v[36:39], v[186:189], v[214:217], v[36:39]
	v_mfma_f32_16x16x32_bf16 v[32:35], v[194:197], v[214:217], v[32:35]
	v_mfma_f32_16x16x32_bf16 v[20:23], v[186:189], v[222:225], v[20:23]
	v_mfma_f32_16x16x32_bf16 v[16:19], v[194:197], v[222:225], v[16:19]
	v_mfma_f32_16x16x32_bf16 v[4:7], v[186:189], v[230:233], v[4:7]
	v_mfma_f32_16x16x32_bf16 v[0:3], v[194:197], v[230:233], v[0:3]
	s_barrier
	s_add_i32 s68, s68, 2
	s_add_u32 s6, s6, 0x100
	s_addc_u32 s7, s7, 0
	s_add_u32 s66, s66, 0x100
	s_addc_u32 s67, s67, 0
	s_cmp_gt_u32 s68, 13
	s_cbranch_scc0 .LBB0_647
	v_lshl_add_u32 v166, s0, 8, v153
	v_or_b32_e32 v162, 16, v166
	v_ashrrev_i32_e32 v167, 31, v166
	v_ashrrev_i32_e32 v163, 31, v162
	v_or_b32_e32 v158, 32, v166
	v_lshlrev_b64 v[146:147], 6, v[166:167]
	v_lshlrev_b64 v[144:145], 6, v[162:163]
	v_ashrrev_i32_e32 v159, 31, v158
	v_lshl_add_u64 v[146:147], v[138:139], 0, v[146:147]
	v_or_b32_e32 v154, 48, v166
	v_lshl_add_u64 v[144:145], v[138:139], 0, v[144:145]
	global_load_dwordx4 v[174:177], v[146:147], off
	v_lshlrev_b64 v[146:147], 6, v[158:159]
	v_ashrrev_i32_e32 v155, 31, v154
	v_lshl_add_u64 v[146:147], v[138:139], 0, v[146:147]
	global_load_dwordx4 v[178:181], v[144:145], off
	global_load_dwordx4 v[182:185], v[146:147], off
	v_lshlrev_b64 v[144:145], 6, v[154:155]
	v_lshl_add_u64 v[144:145], v[138:139], 0, v[144:145]
	global_load_dwordx4 v[186:189], v[144:145], off
	v_add_u32_e32 v150, 0x80, v166
	v_ashrrev_i32_e32 v151, 31, v150
	v_lshlrev_b64 v[144:145], 6, v[150:151]
	v_add_u32_e32 v148, 0x90, v166
	v_lshl_add_u64 v[144:145], v[138:139], 0, v[144:145]
	v_ashrrev_i32_e32 v149, 31, v148
	global_load_dwordx4 v[190:193], v[144:145], off
	v_lshlrev_b64 v[144:145], 6, v[148:149]
	v_lshl_add_u64 v[144:145], v[138:139], 0, v[144:145]
	global_load_dwordx4 v[194:197], v[144:145], off
	v_and_b32_e32 v145, 64, v169
	v_add_u32_e32 v144, 0xb0, v166
	v_add_u32_e32 v146, 0xa0, v166
	v_add_u32_e32 v152, 64, v145
	v_ashrrev_i32_e32 v145, 31, v144
	v_ashrrev_i32_e32 v147, 31, v146
	v_lshlrev_b64 v[198:199], 6, v[144:145]
	v_lshlrev_b64 v[200:201], 6, v[146:147]
	v_lshl_add_u64 v[198:199], v[138:139], 0, v[198:199]
	v_lshl_add_u64 v[202:203], v[138:139], 0, v[200:201]
	global_load_dwordx4 v[198:201], v[198:199], off
	s_nop 0
	global_load_dwordx4 v[202:205], v[202:203], off
	s_and_b64 vcc, exec, s[12:13]
	s_cbranch_vccz .LBB0_650
	s_barrier

; #define PG8_STAGE(bufoff, gbase, voff) do { _Pragma("unroll") for (int _i = 0; _i < 2; ++_i) \
;     __builtin_amdgcn_global_load_lds((const unsigned*)((const char*)(gbase) + (voff)[_i]), (PG8_LAS unsigned*)(lds + (bufoff) + ldsw + _i * 8192), 16, 0, 0); } while (0)
; #define PG8_LDA(dst, b, h) do { _Pragma("unroll") for (int m = 0; m < 4; ++m) _Pragma("unroll") for (int k = 0; k < 2; ++k) dst[m][k] = *(const PG8_LAS bf16x8*)(lds + PG8_SA(b, h) + aoff + m * 2048 + k * 1024); } while (0)
; #define PG8_LDB(dst, b, h) do { _Pragma("unroll") for (int n = 0; n < 2; ++n) _Pragma("unroll") for (int k = 0; k < 2; ++k) dst[n][k] = *(const PG8_LAS bf16x8*)(lds + PG8_SB(b, h) + boff + n * 2048 + k * 1024); } while (0)
; #define PG8_MMA(ai, bj, At, Bt) do { __builtin_amdgcn_s_setprio(1); _Pragma("unroll") for (int m = 0; m < 4; ++m) _Pragma("unroll") for (int n = 0; n < 2; ++n) _Pragma("unroll") for (int k = 0; k < 2; ++k) \
;     acc[ai][bj][m][n] = __builtin_amdgcn_mfma_f32_16x16x32_bf16(Bt[n][k], At[m][k], acc[ai][bj][m][n], 0, 0, 0); __builtin_amdgcn_s_setprio(0); } while (0)
; #define PG8_WAIT_V(n) asm volatile("s_waitcnt vmcnt(" #n ")" ::: "memory")
; #define PG8_WAIT_L(n) asm volatile("s_waitcnt lgkmcnt(" #n ")" ::: "memory")
; template <class Epi, class Sched>
; DI void gemm_phase(PG8_LAS unsigned char* lds, const Gemm g, const Sched& S, const Epi& E) {
;     ...
;     const char* nA = has_next ? (const char*)g.A + (size_t)nxt.pm * tstepA : cA; const char* nB = has_next ? (const char*)g.Bt + (size_t)nxt.pn * tstepB : cB;
; #pragma unroll 1
;     for (int t = 0; t < nt; t += 2) {
;       const bool last = (t == nt - 2);
;       const char* a1 = cA + (size_t)(t + 1) * kstep;
;       const char* a2 = last ? nA : cA + (size_t)(t + 2) * kstep; const char* b2 = last ? nB : cB + (size_t)(t + 2) * kstep;
;       const char* a3 = a2 + kstep; const char* b3 = b2 + kstep;
;       PG8_LDB(B0, 0, 0); PG8_LDB(B1, 0, 1); PG8_SCHED; PG8_LDA(At, 0, 0); PG8_STAGE(PG8_SA(1, 1), a1 + hstepA, voffA);
;       PG8_WAIT_V(8); PG8_WAIT_L(0); PG8_BAR; PG8_MMA(0, 0, At, B0); PG8_MMA(0, 1, At, B1); PG8_BAR; PG8_SCHED;
;       PG8_LDA(At, 0, 1); PG8_STAGE(PG8_SB(0, 0), b2, voffB); PG8_STAGE(PG8_SB(0, 1), b2 + hstepB, voffB); PG8_STAGE(PG8_SA(0, 0), a2, voffA);
;       PG8_WAIT_V(8); PG8_WAIT_L(0); PG8_BAR; PG8_MMA(1, 0, At, B0); PG8_MMA(1, 1, At, B1); PG8_BAR; PG8_SCHED;
.LBB0_721:
	ds_read_b128 v[128:131], v156
	ds_read_b128 v[132:135], v156 offset:1024
	ds_read_b128 v[150:153], v156 offset:2048
	ds_read_b128 v[162:165], v156 offset:3072
	ds_read_b128 v[166:169], v157
	ds_read_b128 v[170:173], v157 offset:1024
	ds_read_b128 v[174:177], v157 offset:2048
	ds_read_b128 v[178:181], v157 offset:3072
	s_add_u32 s26, s24, 0x100
	s_addc_u32 s27, s25, 0
	s_cmp_eq_u32 s65, 40
	s_cselect_b32 s31, s21, s27
	s_cselect_b32 s30, s20, s26
	s_cselect_b32 s29, s23, s64
	s_cselect_b32 s28, s22, s55
	v_lshl_add_u64 v[210:211], s[24:25], 0, v[146:147]
	s_add_i32 m0, s3, 0xc000
	ds_read_b128 v[182:185], v158
	ds_read_b128 v[186:189], v158 offset:1024
	ds_read_b128 v[190:193], v158 offset:2048
	ds_read_b128 v[194:197], v158 offset:3072
	ds_read_b128 v[198:201], v158 offset:4096
	ds_read_b128 v[202:205], v158 offset:5120
	ds_read_b128 v[206:209], v158 offset:6144
	ds_read_b128 v[214:217], v158 offset:7168
	global_load_lds_dwordx4 v[210:211], off
	v_lshl_add_u64 v[210:211], s[24:25], 0, v[148:149]
	s_add_i32 m0, s3, 0xe000
	s_nop 0
	global_load_lds_dwordx4 v[210:211], off
	s_waitcnt vmcnt(8)
	s_waitcnt lgkmcnt(0)
	s_barrier
	s_waitcnt lgkmcnt(0)
	v_mfma_f32_16x16x32_bf16 v[124:127], v[128:131], v[182:185], v[124:127]
	v_mfma_f32_16x16x32_bf16 v[120:123], v[150:153], v[182:185], v[120:123]
	v_mfma_f32_16x16x32_bf16 v[108:111], v[128:131], v[190:193], v[108:111]
	v_mfma_f32_16x16x32_bf16 v[104:107], v[150:153], v[190:193], v[104:107]
	v_mfma_f32_16x16x32_bf16 v[92:95], v[128:131], v[198:201], v[92:95]
	v_mfma_f32_16x16x32_bf16 v[88:91], v[150:153], v[198:201], v[88:91]
	v_mfma_f32_16x16x32_bf16 v[76:79], v[128:131], v[206:209], v[76:79]
	v_mfma_f32_16x16x32_bf16 v[72:75], v[150:153], v[206:209], v[72:75]
	v_mfma_f32_16x16x32_bf16 v[124:127], v[132:135], v[186:189], v[124:127]
	v_mfma_f32_16x16x32_bf16 v[120:123], v[162:165], v[186:189], v[120:123]
	v_mfma_f32_16x16x32_bf16 v[108:111], v[132:135], v[194:197], v[108:111]
	v_mfma_f32_16x16x32_bf16 v[104:107], v[162:165], v[194:197], v[104:107]
	v_mfma_f32_16x16x32_bf16 v[92:95], v[132:135], v[202:205], v[92:95]
	v_mfma_f32_16x16x32_bf16 v[88:91], v[162:165], v[202:205], v[88:91]
	v_mfma_f32_16x16x32_bf16 v[76:79], v[132:135], v[214:217], v[76:79]
	v_mfma_f32_16x16x32_bf16 v[72:75], v[162:165], v[214:217], v[72:75]
	v_mfma_f32_16x16x32_bf16 v[116:119], v[166:169], v[182:185], v[116:119]
	v_mfma_f32_16x16x32_bf16 v[112:115], v[174:177], v[182:185], v[112:115]
	v_mfma_f32_16x16x32_bf16 v[100:103], v[166:169], v[190:193], v[100:103]
	v_mfma_f32_16x16x32_bf16 v[96:99], v[174:177], v[190:193], v[96:99]
	v_mfma_f32_16x16x32_bf16 v[84:87], v[166:169], v[198:201], v[84:87]
	v_mfma_f32_16x16x32_bf16 v[80:83], v[174:177], v[198:201], v[80:83]
	v_mfma_f32_16x16x32_bf16 v[68:71], v[166:169], v[206:209], v[68:71]
	v_mfma_f32_16x16x32_bf16 v[64:67], v[174:177], v[206:209], v[64:67]
	v_mfma_f32_16x16x32_bf16 v[116:119], v[170:173], v[186:189], v[116:119]
	v_mfma_f32_16x16x32_bf16 v[112:115], v[178:181], v[186:189], v[112:115]
	v_mfma_f32_16x16x32_bf16 v[100:103], v[170:173], v[194:197], v[100:103]
	v_mfma_f32_16x16x32_bf16 v[96:99], v[178:181], v[194:197], v[96:99]
	v_mfma_f32_16x16x32_bf16 v[84:87], v[170:173], v[202:205], v[84:87]
	v_mfma_f32_16x16x32_bf16 v[80:83], v[178:181], v[202:205], v[80:83]
	v_mfma_f32_16x16x32_bf16 v[68:71], v[170:173], v[214:217], v[68:71]
	v_mfma_f32_16x16x32_bf16 v[64:67], v[178:181], v[214:217], v[64:67]
	s_barrier
	s_add_i32 s16, s37, s2
	v_lshl_add_u64 v[210:211], s[28:29], 0, v[138:139]
	s_mov_b32 m0, s16
	ds_read_b128 v[182:185], v158 offset:16384
	ds_read_b128 v[186:189], v158 offset:17408
	ds_read_b128 v[190:193], v158 offset:18432
	ds_read_b128 v[194:197], v158 offset:19456
	ds_read_b128 v[198:201], v158 offset:20480
	ds_read_b128 v[202:205], v158 offset:21504
	ds_read_b128 v[206:209], v158 offset:22528
	ds_read_b128 v[214:217], v158 offset:23552
	global_load_lds_dwordx4 v[210:211], off
	s_add_i32 m0, s16, 0x2000
	s_add_u32 s16, s28, 0xb0000
	v_lshl_add_u64 v[218:219], s[28:29], 0, v[142:143]
	s_addc_u32 s17, s29, 0
	s_add_i32 s24, s38, s2
	global_load_lds_dwordx4 v[218:219], off
	v_lshl_add_u64 v[220:221], s[16:17], 0, v[138:139]
	s_mov_b32 m0, s24
	v_lshl_add_u64 v[222:223], s[30:31], 0, v[140:141]
	global_load_lds_dwordx4 v[220:221], off
	v_lshl_add_u64 v[220:221], s[16:17], 0, v[142:143]
	s_add_i32 m0, s24, 0x2000
	s_nop 0
	global_load_lds_dwordx4 v[220:221], off
	v_lshl_add_u64 v[220:221], s[30:31], 0, v[136:137]
	s_mov_b32 m0, s3
	s_nop 0
	global_load_lds_dwordx4 v[220:221], off
	s_mov_b32 m0, s34
	s_nop 0
	global_load_lds_dwordx4 v[222:223], off
	s_waitcnt vmcnt(8)
	s_waitcnt lgkmcnt(0)
	s_barrier
; #define PG8_STAGE(bufoff, gbase, voff) do { _Pragma("unroll") for (int _i = 0; _i < 2; ++_i) \
;     __builtin_amdgcn_global_load_lds((const unsigned*)((const char*)(gbase) + (voff)[_i]), (PG8_LAS unsigned*)(lds + (bufoff) + ldsw + _i * 8192), 16, 0, 0); } while (0)
; #define PG8_LDA(dst, b, h) do { _Pragma("unroll") for (int m = 0; m < 4; ++m) _Pragma("unroll") for (int k = 0; k < 2; ++k) dst[m][k] = *(const PG8_LAS bf16x8*)(lds + PG8_SA(b, h) + aoff + m * 2048 + k * 1024); } while (0)
; #define PG8_LDB(dst, b, h) do { _Pragma("unroll") for (int n = 0; n < 2; ++n) _Pragma("unroll") for (int k = 0; k < 2; ++k) dst[n][k] = *(const PG8_LAS bf16x8*)(lds + PG8_SB(b, h) + boff + n * 2048 + k * 1024); } while (0)
; #define PG8_MMA(ai, bj, At, Bt) do { __builtin_amdgcn_s_setprio(1); _Pragma("unroll") for (int m = 0; m < 4; ++m) _Pragma("unroll") for (int n = 0; n < 2; ++n) _Pragma("unroll") for (int k = 0; k < 2; ++k) \
;     acc[ai][bj][m][n] = __builtin_amdgcn_mfma_f32_16x16x32_bf16(Bt[n][k], At[m][k], acc[ai][bj][m][n], 0, 0, 0); __builtin_amdgcn_s_setprio(0); } while (0)
; #define PG8_WAIT_V(n) asm volatile("s_waitcnt vmcnt(" #n ")" ::: "memory")
; #define PG8_WAIT_L(n) asm volatile("s_waitcnt lgkmcnt(" #n ")" ::: "memory")
; #define PG8_BAR __builtin_amdgcn_s_barrier()
; #define PG8_SCHED __builtin_amdgcn_sched_barrier(0)
; template <class Epi, class Sched>
; DI void gemm_phase(PG8_LAS unsigned char* lds, const Gemm g, const Sched& S, const Epi& E) {
;     ...
;       PG8_WAIT_V(8); PG8_WAIT_L(0); PG8_BAR; PG8_MMA(1, 0, At, B0); PG8_MMA(1, 1, At, B1); PG8_BAR; PG8_SCHED;
;       PG8_LDB(B0, 1, 0); PG8_LDB(B1, 1, 1); PG8_SCHED; PG8_LDA(At, 1, 0); PG8_STAGE(PG8_SA(0, 1), a2 + hstepA, voffA);
;       PG8_WAIT_V(8); PG8_WAIT_L(0); PG8_BAR; PG8_MMA(0, 0, At, B0); PG8_MMA(0, 1, At, B1); PG8_BAR; PG8_SCHED;
	s_waitcnt lgkmcnt(0)
	v_mfma_f32_16x16x32_bf16 v[60:63], v[128:131], v[182:185], v[60:63]
	v_mfma_f32_16x16x32_bf16 v[56:59], v[150:153], v[182:185], v[56:59]
	v_mfma_f32_16x16x32_bf16 v[44:47], v[128:131], v[190:193], v[44:47]
	v_mfma_f32_16x16x32_bf16 v[40:43], v[150:153], v[190:193], v[40:43]
	v_mfma_f32_16x16x32_bf16 v[28:31], v[128:131], v[198:201], v[28:31]
	v_mfma_f32_16x16x32_bf16 v[24:27], v[150:153], v[198:201], v[24:27]
	v_mfma_f32_16x16x32_bf16 v[12:15], v[128:131], v[206:209], v[12:15]
	v_mfma_f32_16x16x32_bf16 v[8:11], v[150:153], v[206:209], v[8:11]
	v_mfma_f32_16x16x32_bf16 v[60:63], v[132:135], v[186:189], v[60:63]
	v_mfma_f32_16x16x32_bf16 v[56:59], v[162:165], v[186:189], v[56:59]
	v_mfma_f32_16x16x32_bf16 v[44:47], v[132:135], v[194:197], v[44:47]
	v_mfma_f32_16x16x32_bf16 v[40:43], v[162:165], v[194:197], v[40:43]
	v_mfma_f32_16x16x32_bf16 v[28:31], v[132:135], v[202:205], v[28:31]
	v_mfma_f32_16x16x32_bf16 v[24:27], v[162:165], v[202:205], v[24:27]
	v_mfma_f32_16x16x32_bf16 v[12:15], v[132:135], v[214:217], v[12:15]
	v_mfma_f32_16x16x32_bf16 v[8:11], v[162:165], v[214:217], v[8:11]
	v_mfma_f32_16x16x32_bf16 v[52:55], v[166:169], v[182:185], v[52:55]
	v_mfma_f32_16x16x32_bf16 v[48:51], v[174:177], v[182:185], v[48:51]
	v_mfma_f32_16x16x32_bf16 v[36:39], v[166:169], v[190:193], v[36:39]
	v_mfma_f32_16x16x32_bf16 v[32:35], v[174:177], v[190:193], v[32:35]
	v_mfma_f32_16x16x32_bf16 v[20:23], v[166:169], v[198:201], v[20:23]
	v_mfma_f32_16x16x32_bf16 v[16:19], v[174:177], v[198:201], v[16:19]
	v_mfma_f32_16x16x32_bf16 v[4:7], v[166:169], v[206:209], v[4:7]
	v_mfma_f32_16x16x32_bf16 v[0:3], v[174:177], v[206:209], v[0:3]
	v_mfma_f32_16x16x32_bf16 v[52:55], v[170:173], v[186:189], v[52:55]
	v_mfma_f32_16x16x32_bf16 v[48:51], v[178:181], v[186:189], v[48:51]
	v_mfma_f32_16x16x32_bf16 v[36:39], v[170:173], v[194:197], v[36:39]
	v_mfma_f32_16x16x32_bf16 v[32:35], v[178:181], v[194:197], v[32:35]
	v_mfma_f32_16x16x32_bf16 v[20:23], v[170:173], v[202:205], v[20:23]
	v_mfma_f32_16x16x32_bf16 v[16:19], v[178:181], v[202:205], v[16:19]
	v_mfma_f32_16x16x32_bf16 v[4:7], v[170:173], v[214:217], v[4:7]
	v_mfma_f32_16x16x32_bf16 v[0:3], v[178:181], v[214:217], v[0:3]
	s_barrier
	s_mov_b32 s16, 0x18000
	s_add_i32 s24, s16, 0x110
	v_add_u32_e32 v161, s24, v155
	ds_read_b128 v[128:131], v161
	ds_read_b128 v[132:135], v161 offset:1024
	ds_read_b128 v[150:153], v161 offset:2048
	ds_read_b128 v[162:165], v161 offset:3072
	ds_read_b128 v[166:169], v160
	ds_read_b128 v[170:173], v160 offset:1024
	ds_read_b128 v[174:177], v160 offset:2048
	ds_read_b128 v[178:181], v160 offset:3072
	s_add_u32 s16, s30, 0xb0000
	s_addc_u32 s17, s31, 0
	s_mov_b32 m0, s18
	v_lshl_add_u64 v[224:225], s[16:17], 0, v[136:137]
	ds_read_b128 v[182:185], v158 offset:32768
	ds_read_b128 v[186:189], v158 offset:33792
	ds_read_b128 v[190:193], v158 offset:34816
	ds_read_b128 v[194:197], v158 offset:35840
	ds_read_b128 v[198:201], v158 offset:36864
	ds_read_b128 v[202:205], v158 offset:37888
	ds_read_b128 v[206:209], v158 offset:38912
	ds_read_b128 v[214:217], v158 offset:39936
	global_load_lds_dwordx4 v[224:225], off
	v_lshl_add_u64 v[224:225], s[16:17], 0, v[140:141]
	s_mov_b32 m0, s19
	s_nop 0
	global_load_lds_dwordx4 v[224:225], off
	s_waitcnt vmcnt(8)
	s_waitcnt lgkmcnt(0)
	s_barrier
	s_waitcnt lgkmcnt(0)
	v_mfma_f32_16x16x32_bf16 v[124:127], v[128:131], v[182:185], v[124:127]
	v_mfma_f32_16x16x32_bf16 v[120:123], v[150:153], v[182:185], v[120:123]
	v_mfma_f32_16x16x32_bf16 v[108:111], v[128:131], v[190:193], v[108:111]
	v_mfma_f32_16x16x32_bf16 v[104:107], v[150:153], v[190:193], v[104:107]
	v_mfma_f32_16x16x32_bf16 v[92:95], v[128:131], v[198:201], v[92:95]
	v_mfma_f32_16x16x32_bf16 v[88:91], v[150:153], v[198:201], v[88:91]
	v_mfma_f32_16x16x32_bf16 v[76:79], v[128:131], v[206:209], v[76:79]
	v_mfma_f32_16x16x32_bf16 v[72:75], v[150:153], v[206:209], v[72:75]
	v_mfma_f32_16x16x32_bf16 v[124:127], v[132:135], v[186:189], v[124:127]
	v_mfma_f32_16x16x32_bf16 v[120:123], v[162:165], v[186:189], v[120:123]
	v_mfma_f32_16x16x32_bf16 v[108:111], v[132:135], v[194:197], v[108:111]
	v_mfma_f32_16x16x32_bf16 v[104:107], v[162:165], v[194:197], v[104:107]
	v_mfma_f32_16x16x32_bf16 v[92:95], v[132:135], v[202:205], v[92:95]
	v_mfma_f32_16x16x32_bf16 v[88:91], v[162:165], v[202:205], v[88:91]
	v_mfma_f32_16x16x32_bf16 v[76:79], v[132:135], v[214:217], v[76:79]
	v_mfma_f32_16x16x32_bf16 v[72:75], v[162:165], v[214:217], v[72:75]
	v_mfma_f32_16x16x32_bf16 v[116:119], v[166:169], v[182:185], v[116:119]
	v_mfma_f32_16x16x32_bf16 v[112:115], v[174:177], v[182:185], v[112:115]
	v_mfma_f32_16x16x32_bf16 v[100:103], v[166:169], v[190:193], v[100:103]
	v_mfma_f32_16x16x32_bf16 v[96:99], v[174:177], v[190:193], v[96:99]
	v_mfma_f32_16x16x32_bf16 v[84:87], v[166:169], v[198:201], v[84:87]
	v_mfma_f32_16x16x32_bf16 v[80:83], v[174:177], v[198:201], v[80:83]
	v_mfma_f32_16x16x32_bf16 v[68:71], v[166:169], v[206:209], v[68:71]
	v_mfma_f32_16x16x32_bf16 v[64:67], v[174:177], v[206:209], v[64:67]
	v_mfma_f32_16x16x32_bf16 v[116:119], v[170:173], v[186:189], v[116:119]
	v_mfma_f32_16x16x32_bf16 v[112:115], v[178:181], v[186:189], v[112:115]
	v_mfma_f32_16x16x32_bf16 v[100:103], v[170:173], v[194:197], v[100:103]
	v_mfma_f32_16x16x32_bf16 v[96:99], v[178:181], v[194:197], v[96:99]
	v_mfma_f32_16x16x32_bf16 v[84:87], v[170:173], v[202:205], v[84:87]
	v_mfma_f32_16x16x32_bf16 v[80:83], v[178:181], v[202:205], v[80:83]
	v_mfma_f32_16x16x32_bf16 v[68:71], v[170:173], v[214:217], v[68:71]
	v_mfma_f32_16x16x32_bf16 v[64:67], v[178:181], v[214:217], v[64:67]
	s_barrier
; #define PG8_STAGE(bufoff, gbase, voff) do { _Pragma("unroll") for (int _i = 0; _i < 2; ++_i) \
;     __builtin_amdgcn_global_load_lds((const unsigned*)((const char*)(gbase) + (voff)[_i]), (PG8_LAS unsigned*)(lds + (bufoff) + ldsw + _i * 8192), 16, 0, 0); } while (0)
; #define PG8_LDA(dst, b, h) do { _Pragma("unroll") for (int m = 0; m < 4; ++m) _Pragma("unroll") for (int k = 0; k < 2; ++k) dst[m][k] = *(const PG8_LAS bf16x8*)(lds + PG8_SA(b, h) + aoff + m * 2048 + k * 1024); } while (0)
; #define PG8_MMA(ai, bj, At, Bt) do { __builtin_amdgcn_s_setprio(1); _Pragma("unroll") for (int m = 0; m < 4; ++m) _Pragma("unroll") for (int n = 0; n < 2; ++n) _Pragma("unroll") for (int k = 0; k < 2; ++k) \
;     acc[ai][bj][m][n] = __builtin_amdgcn_mfma_f32_16x16x32_bf16(Bt[n][k], At[m][k], acc[ai][bj][m][n], 0, 0, 0); __builtin_amdgcn_s_setprio(0); } while (0)
; #define PG8_WAIT_V(n) asm volatile("s_waitcnt vmcnt(" #n ")" ::: "memory")
; #define PG8_WAIT_L(n) asm volatile("s_waitcnt lgkmcnt(" #n ")" ::: "memory")
; #define PG8_BAR __builtin_amdgcn_s_barrier()
; #define PG8_SCHED __builtin_amdgcn_sched_barrier(0)
;   DI void operator()(const f32x4 (&acc)[2][2][4][2], const Unit& u, int wr, int wc, int fr, int fq) const {
;     ...
;     RES_LD(0)
; template <class Epi, class Sched>
; DI void gemm_phase(PG8_LAS unsigned char* lds, const Gemm g, const Sched& S, const Epi& E) {
;     ...
;       PG8_LDA(At, 1, 1); PG8_STAGE(PG8_SB(1, 0), b3, voffB); PG8_STAGE(PG8_SB(1, 1), b3 + hstepB, voffB); PG8_STAGE(PG8_SA(1, 0), a3, voffA);
;       PG8_WAIT_V(8); PG8_WAIT_L(0); PG8_BAR; PG8_MMA(1, 0, At, B0); PG8_MMA(1, 1, At, B1); PG8_BAR; PG8_SCHED;
;     }
;     if (wr == 0) PG8_BAR;
;     E(acc, cur, wr, wc, fr, fq);
	s_add_i32 s16, s24, s2
	v_lshl_add_u64 v[210:211], v[210:211], 0, s[10:11]
	s_mov_b32 m0, s16
	ds_read_b128 v[182:185], v158 offset:49152
	ds_read_b128 v[186:189], v158 offset:50176
	ds_read_b128 v[190:193], v158 offset:51200
	ds_read_b128 v[194:197], v158 offset:52224
	ds_read_b128 v[198:201], v158 offset:53248
	ds_read_b128 v[202:205], v158 offset:54272
	ds_read_b128 v[206:209], v158 offset:55296
	ds_read_b128 v[214:217], v158 offset:56320
	global_load_lds_dwordx4 v[210:211], off
	s_add_i32 m0, s16, 0x2000
	s_add_u32 s16, s28, 0xb0080
	v_lshl_add_u64 v[210:211], v[218:219], 0, s[10:11]
	s_addc_u32 s17, s29, 0
	s_add_i32 s24, s39, s2
	global_load_lds_dwordx4 v[210:211], off
	v_lshl_add_u64 v[210:211], s[16:17], 0, v[138:139]
	s_mov_b32 m0, s24
	s_nop 0
	global_load_lds_dwordx4 v[210:211], off
	v_lshl_add_u64 v[210:211], s[16:17], 0, v[142:143]
	s_add_i32 m0, s24, 0x2000
	s_nop 0
	global_load_lds_dwordx4 v[210:211], off
	v_lshl_add_u64 v[210:211], v[220:221], 0, s[10:11]
	s_mov_b32 m0, s5
	s_nop 0
	global_load_lds_dwordx4 v[210:211], off
	v_lshl_add_u64 v[210:211], v[222:223], 0, s[10:11]
	s_mov_b32 m0, s35
	s_nop 0
	global_load_lds_dwordx4 v[210:211], off
	s_waitcnt vmcnt(8)
	s_waitcnt lgkmcnt(0)
	s_barrier
	s_waitcnt lgkmcnt(0)
	v_mfma_f32_16x16x32_bf16 v[60:63], v[128:131], v[182:185], v[60:63]
	v_mfma_f32_16x16x32_bf16 v[56:59], v[150:153], v[182:185], v[56:59]
	v_mfma_f32_16x16x32_bf16 v[44:47], v[128:131], v[190:193], v[44:47]
	v_mfma_f32_16x16x32_bf16 v[40:43], v[150:153], v[190:193], v[40:43]
	v_mfma_f32_16x16x32_bf16 v[28:31], v[128:131], v[198:201], v[28:31]
	v_mfma_f32_16x16x32_bf16 v[24:27], v[150:153], v[198:201], v[24:27]
	v_mfma_f32_16x16x32_bf16 v[12:15], v[128:131], v[206:209], v[12:15]
	v_mfma_f32_16x16x32_bf16 v[8:11], v[150:153], v[206:209], v[8:11]
	v_mfma_f32_16x16x32_bf16 v[60:63], v[132:135], v[186:189], v[60:63]
	v_mfma_f32_16x16x32_bf16 v[56:59], v[162:165], v[186:189], v[56:59]
	v_mfma_f32_16x16x32_bf16 v[44:47], v[132:135], v[194:197], v[44:47]
	v_mfma_f32_16x16x32_bf16 v[40:43], v[162:165], v[194:197], v[40:43]
	v_mfma_f32_16x16x32_bf16 v[28:31], v[132:135], v[202:205], v[28:31]
	v_mfma_f32_16x16x32_bf16 v[24:27], v[162:165], v[202:205], v[24:27]
	v_mfma_f32_16x16x32_bf16 v[12:15], v[132:135], v[214:217], v[12:15]
	v_mfma_f32_16x16x32_bf16 v[8:11], v[162:165], v[214:217], v[8:11]
	v_mfma_f32_16x16x32_bf16 v[52:55], v[166:169], v[182:185], v[52:55]
	v_mfma_f32_16x16x32_bf16 v[48:51], v[174:177], v[182:185], v[48:51]
	v_mfma_f32_16x16x32_bf16 v[36:39], v[166:169], v[190:193], v[36:39]
	v_mfma_f32_16x16x32_bf16 v[32:35], v[174:177], v[190:193], v[32:35]
	v_mfma_f32_16x16x32_bf16 v[20:23], v[166:169], v[198:201], v[20:23]
	v_mfma_f32_16x16x32_bf16 v[16:19], v[174:177], v[198:201], v[16:19]
	v_mfma_f32_16x16x32_bf16 v[4:7], v[166:169], v[206:209], v[4:7]
	v_mfma_f32_16x16x32_bf16 v[0:3], v[174:177], v[206:209], v[0:3]
	v_mfma_f32_16x16x32_bf16 v[52:55], v[170:173], v[186:189], v[52:55]
	v_mfma_f32_16x16x32_bf16 v[48:51], v[178:181], v[186:189], v[48:51]
	v_mfma_f32_16x16x32_bf16 v[36:39], v[170:173], v[194:197], v[36:39]
	v_mfma_f32_16x16x32_bf16 v[32:35], v[178:181], v[194:197], v[32:35]
	v_mfma_f32_16x16x32_bf16 v[20:23], v[170:173], v[202:205], v[20:23]
	v_mfma_f32_16x16x32_bf16 v[16:19], v[178:181], v[202:205], v[16:19]
	v_mfma_f32_16x16x32_bf16 v[4:7], v[170:173], v[214:217], v[4:7]
	v_mfma_f32_16x16x32_bf16 v[0:3], v[178:181], v[214:217], v[0:3]
	s_barrier
	s_add_i32 s65, s65, 2
	s_add_u32 s55, s55, 0x100
	s_addc_u32 s64, s64, 0
	s_cmp_gt_u32 s65, 41
	s_mov_b64 s[24:25], s[26:27]
	s_cbranch_scc0 .LBB0_721
	v_lshl_add_u32 v152, s53, 8, v154
	v_ashrrev_i32_e32 v153, 31, v152
	s_lshl_b32 s16, s45, 8
	v_lshlrev_b64 v[128:129], 11, v[152:153]
	s_ashr_i32 s17, s16, 31
	v_lshl_add_u64 v[128:129], s[50:51], 0, v[128:129]
	v_lshl_add_u64 v[128:129], s[16:17], 1, v[128:129]
	v_lshl_add_u64 v[128:129], v[128:129], 0, s[14:15]
	v_lshl_add_u64 v[150:151], v[128:129], 0, v[144:145]
	s_mov_b32 s16, 0x8000
	v_add_co_u32_e32 v128, vcc, s16, v150
	global_load_dwordx4 v[164:167], v[150:151], off
	global_load_dwordx4 v[168:171], v[150:151], off offset:256
	v_addc_co_u32_e32 v129, vcc, 0, v151, vcc
	global_load_dwordx4 v[132:135], v[128:129], off
	s_nop 0
	global_load_dwordx4 v[128:131], v[128:129], off offset:256
	s_and_b64 vcc, exec, s[12:13]
	s_cbranch_vccz .LBB0_724
	s_barrier

; #define PG8_STAGE(bufoff, gbase, voff) do { _Pragma("unroll") for (int _i = 0; _i < 2; ++_i) \
;     __builtin_amdgcn_global_load_lds((const unsigned*)((const char*)(gbase) + (voff)[_i]), (PG8_LAS unsigned*)(lds + (bufoff) + ldsw + _i * 8192), 16, 0, 0); } while (0)
; #define PG8_LDA(dst, b, h) do { _Pragma("unroll") for (int m = 0; m < 4; ++m) _Pragma("unroll") for (int k = 0; k < 2; ++k) dst[m][k] = *(const PG8_LAS bf16x8*)(lds + PG8_SA(b, h) + aoff + m * 2048 + k * 1024); } while (0)
; #define PG8_LDB(dst, b, h) do { _Pragma("unroll") for (int n = 0; n < 2; ++n) _Pragma("unroll") for (int k = 0; k < 2; ++k) dst[n][k] = *(const PG8_LAS bf16x8*)(lds + PG8_SB(b, h) + boff + n * 2048 + k * 1024); } while (0)
; #define PG8_MMA(ai, bj, At, Bt) do { __builtin_amdgcn_s_setprio(1); _Pragma("unroll") for (int m = 0; m < 4; ++m) _Pragma("unroll") for (int n = 0; n < 2; ++n) _Pragma("unroll") for (int k = 0; k < 2; ++k) \
;     acc[ai][bj][m][n] = __builtin_amdgcn_mfma_f32_16x16x32_bf16(Bt[n][k], At[m][k], acc[ai][bj][m][n], 0, 0, 0); __builtin_amdgcn_s_setprio(0); } while (0)
; #define PG8_WAIT_V(n) asm volatile("s_waitcnt vmcnt(" #n ")" ::: "memory")
; #define PG8_WAIT_L(n) asm volatile("s_waitcnt lgkmcnt(" #n ")" ::: "memory")
; template <class Epi, class Sched>
; DI void gemm_phase(PG8_LAS unsigned char* lds, const Gemm g, const Sched& S, const Epi& E) {
;     ...
;     const char* nA = has_next ? (const char*)g.A + (size_t)nxt.pm * tstepA : cA; const char* nB = has_next ? (const char*)g.Bt + (size_t)nxt.pn * tstepB : cB;
; #pragma unroll 1
;     for (int t = 0; t < nt; t += 2) {
;       const bool last = (t == nt - 2);
;       const char* a1 = cA + (size_t)(t + 1) * kstep;
;       const char* a2 = last ? nA : cA + (size_t)(t + 2) * kstep; const char* b2 = last ? nB : cB + (size_t)(t + 2) * kstep;
;       const char* a3 = a2 + kstep; const char* b3 = b2 + kstep;
;       PG8_LDB(B0, 0, 0); PG8_LDB(B1, 0, 1); PG8_SCHED; PG8_LDA(At, 0, 0); PG8_STAGE(PG8_SA(1, 1), a1 + hstepA, voffA);
;       PG8_WAIT_V(8); PG8_WAIT_L(0); PG8_BAR; PG8_MMA(0, 0, At, B0); PG8_MMA(0, 1, At, B1); PG8_BAR; PG8_SCHED;
;       PG8_LDA(At, 0, 1); PG8_STAGE(PG8_SB(0, 0), b2, voffB); PG8_STAGE(PG8_SB(0, 1), b2 + hstepB, voffB); PG8_STAGE(PG8_SA(0, 0), a2, voffA);
;       PG8_WAIT_V(8); PG8_WAIT_L(0); PG8_BAR; PG8_MMA(1, 0, At, B0); PG8_MMA(1, 1, At, B1); PG8_BAR; PG8_SCHED;
.LBB0_807:
	ds_read_b128 v[144:147], v195
	ds_read_b128 v[148:151], v195 offset:1024
	ds_read_b128 v[152:155], v195 offset:2048
	ds_read_b128 v[156:159], v195 offset:3072
	ds_read_b128 v[160:163], v196
	ds_read_b128 v[164:167], v196 offset:1024
	ds_read_b128 v[168:171], v196 offset:2048
	ds_read_b128 v[172:175], v196 offset:3072
	s_add_u32 s16, s10, 0xfffc0080
	s_addc_u32 s17, s11, -1
	s_cmp_eq_u32 s73, 12
	s_cselect_b32 s45, s1, s17
	s_cselect_b32 s44, s9, s16
	s_cselect_b32 s41, s22, s72
	s_cselect_b32 s40, s29, s31
	v_lshl_add_u64 v[192:193], s[10:11], 0, v[138:139]
	s_add_i32 m0, s3, 0xc000
	ds_read_b128 v[176:179], v197
	ds_read_b128 v[180:183], v197 offset:1024
	ds_read_b128 v[184:187], v197 offset:2048
	ds_read_b128 v[188:191], v197 offset:3072
	ds_read_b128 v[202:205], v197 offset:4096
	ds_read_b128 v[206:209], v197 offset:5120
	ds_read_b128 v[214:217], v197 offset:6144
	ds_read_b128 v[218:221], v197 offset:7168
	global_load_lds_dwordx4 v[192:193], off
	v_lshl_add_u64 v[192:193], s[10:11], 0, v[140:141]
	s_add_i32 m0, s3, 0xe000
	s_nop 0
	global_load_lds_dwordx4 v[192:193], off
	s_waitcnt vmcnt(8)
	s_waitcnt lgkmcnt(0)
	s_barrier
	s_waitcnt lgkmcnt(0)
	v_mfma_f32_16x16x32_bf16 v[124:127], v[144:147], v[176:179], v[124:127]
	v_mfma_f32_16x16x32_bf16 v[120:123], v[152:155], v[176:179], v[120:123]
	v_mfma_f32_16x16x32_bf16 v[108:111], v[144:147], v[184:187], v[108:111]
	v_mfma_f32_16x16x32_bf16 v[104:107], v[152:155], v[184:187], v[104:107]
	v_mfma_f32_16x16x32_bf16 v[92:95], v[144:147], v[202:205], v[92:95]
	v_mfma_f32_16x16x32_bf16 v[88:91], v[152:155], v[202:205], v[88:91]
	v_mfma_f32_16x16x32_bf16 v[76:79], v[144:147], v[214:217], v[76:79]
	v_mfma_f32_16x16x32_bf16 v[72:75], v[152:155], v[214:217], v[72:75]
	v_mfma_f32_16x16x32_bf16 v[124:127], v[148:151], v[180:183], v[124:127]
	v_mfma_f32_16x16x32_bf16 v[120:123], v[156:159], v[180:183], v[120:123]
	v_mfma_f32_16x16x32_bf16 v[108:111], v[148:151], v[188:191], v[108:111]
	v_mfma_f32_16x16x32_bf16 v[104:107], v[156:159], v[188:191], v[104:107]
	v_mfma_f32_16x16x32_bf16 v[92:95], v[148:151], v[206:209], v[92:95]
	v_mfma_f32_16x16x32_bf16 v[88:91], v[156:159], v[206:209], v[88:91]
	v_mfma_f32_16x16x32_bf16 v[76:79], v[148:151], v[218:221], v[76:79]
	v_mfma_f32_16x16x32_bf16 v[72:75], v[156:159], v[218:221], v[72:75]
	v_mfma_f32_16x16x32_bf16 v[116:119], v[160:163], v[176:179], v[116:119]
	v_mfma_f32_16x16x32_bf16 v[112:115], v[168:171], v[176:179], v[112:115]
	v_mfma_f32_16x16x32_bf16 v[100:103], v[160:163], v[184:187], v[100:103]
	v_mfma_f32_16x16x32_bf16 v[96:99], v[168:171], v[184:187], v[96:99]
	v_mfma_f32_16x16x32_bf16 v[84:87], v[160:163], v[202:205], v[84:87]
	v_mfma_f32_16x16x32_bf16 v[80:83], v[168:171], v[202:205], v[80:83]
	v_mfma_f32_16x16x32_bf16 v[68:71], v[160:163], v[214:217], v[68:71]
	v_mfma_f32_16x16x32_bf16 v[64:67], v[168:171], v[214:217], v[64:67]
	v_mfma_f32_16x16x32_bf16 v[116:119], v[164:167], v[180:183], v[116:119]
	v_mfma_f32_16x16x32_bf16 v[112:115], v[172:175], v[180:183], v[112:115]
	v_mfma_f32_16x16x32_bf16 v[100:103], v[164:167], v[188:191], v[100:103]
	v_mfma_f32_16x16x32_bf16 v[96:99], v[172:175], v[188:191], v[96:99]
	v_mfma_f32_16x16x32_bf16 v[84:87], v[164:167], v[206:209], v[84:87]
	v_mfma_f32_16x16x32_bf16 v[80:83], v[172:175], v[206:209], v[80:83]
	v_mfma_f32_16x16x32_bf16 v[68:71], v[164:167], v[218:221], v[68:71]
	v_mfma_f32_16x16x32_bf16 v[64:67], v[172:175], v[218:221], v[64:67]
	s_barrier
	s_add_i32 s16, s4, s2
	v_lshl_add_u64 v[192:193], s[40:41], 0, v[130:131]
	s_mov_b32 m0, s16
	ds_read_b128 v[176:179], v197 offset:16384
	ds_read_b128 v[180:183], v197 offset:17408
	ds_read_b128 v[184:187], v197 offset:18432
	ds_read_b128 v[188:191], v197 offset:19456
	ds_read_b128 v[202:205], v197 offset:20480
	ds_read_b128 v[206:209], v197 offset:21504
	ds_read_b128 v[214:217], v197 offset:22528
	ds_read_b128 v[218:221], v197 offset:23552
	global_load_lds_dwordx4 v[192:193], off
	s_add_i32 m0, s16, 0x2000
	s_add_u32 s16, s40, 0x40000
	v_lshl_add_u64 v[210:211], s[40:41], 0, v[134:135]
	s_addc_u32 s17, s41, 0
	s_add_i32 s33, s5, s2
	global_load_lds_dwordx4 v[210:211], off
	v_lshl_add_u64 v[222:223], s[16:17], 0, v[130:131]
	s_mov_b32 m0, s33
	v_lshl_add_u64 v[224:225], s[44:45], 0, v[132:133]
	global_load_lds_dwordx4 v[222:223], off
	v_lshl_add_u64 v[222:223], s[16:17], 0, v[134:135]
	s_add_i32 m0, s33, 0x2000
	s_nop 0
	global_load_lds_dwordx4 v[222:223], off
	v_lshl_add_u64 v[222:223], s[44:45], 0, v[128:129]
	s_mov_b32 m0, s3
	s_nop 0
	global_load_lds_dwordx4 v[222:223], off
	s_mov_b32 m0, s27
	s_nop 0
	global_load_lds_dwordx4 v[224:225], off
	s_waitcnt vmcnt(8)
	s_waitcnt lgkmcnt(0)
	s_barrier
; #define PG8_STAGE(bufoff, gbase, voff) do { _Pragma("unroll") for (int _i = 0; _i < 2; ++_i) \
;     __builtin_amdgcn_global_load_lds((const unsigned*)((const char*)(gbase) + (voff)[_i]), (PG8_LAS unsigned*)(lds + (bufoff) + ldsw + _i * 8192), 16, 0, 0); } while (0)
; #define PG8_LDA(dst, b, h) do { _Pragma("unroll") for (int m = 0; m < 4; ++m) _Pragma("unroll") for (int k = 0; k < 2; ++k) dst[m][k] = *(const PG8_LAS bf16x8*)(lds + PG8_SA(b, h) + aoff + m * 2048 + k * 1024); } while (0)
; #define PG8_LDB(dst, b, h) do { _Pragma("unroll") for (int n = 0; n < 2; ++n) _Pragma("unroll") for (int k = 0; k < 2; ++k) dst[n][k] = *(const PG8_LAS bf16x8*)(lds + PG8_SB(b, h) + boff + n * 2048 + k * 1024); } while (0)
; #define PG8_MMA(ai, bj, At, Bt) do { __builtin_amdgcn_s_setprio(1); _Pragma("unroll") for (int m = 0; m < 4; ++m) _Pragma("unroll") for (int n = 0; n < 2; ++n) _Pragma("unroll") for (int k = 0; k < 2; ++k) \
;     acc[ai][bj][m][n] = __builtin_amdgcn_mfma_f32_16x16x32_bf16(Bt[n][k], At[m][k], acc[ai][bj][m][n], 0, 0, 0); __builtin_amdgcn_s_setprio(0); } while (0)
; #define PG8_WAIT_V(n) asm volatile("s_waitcnt vmcnt(" #n ")" ::: "memory")
; #define PG8_WAIT_L(n) asm volatile("s_waitcnt lgkmcnt(" #n ")" ::: "memory")
; #define PG8_BAR __builtin_amdgcn_s_barrier()
; #define PG8_SCHED __builtin_amdgcn_sched_barrier(0)
; template <class Epi, class Sched>
; DI void gemm_phase(PG8_LAS unsigned char* lds, const Gemm g, const Sched& S, const Epi& E) {
;     ...
;       PG8_WAIT_V(8); PG8_WAIT_L(0); PG8_BAR; PG8_MMA(1, 0, At, B0); PG8_MMA(1, 1, At, B1); PG8_BAR; PG8_SCHED;
;       PG8_LDB(B0, 1, 0); PG8_LDB(B1, 1, 1); PG8_SCHED; PG8_LDA(At, 1, 0); PG8_STAGE(PG8_SA(0, 1), a2 + hstepA, voffA);
;       PG8_WAIT_V(8); PG8_WAIT_L(0); PG8_BAR; PG8_MMA(0, 0, At, B0); PG8_MMA(0, 1, At, B1); PG8_BAR; PG8_SCHED;
	s_waitcnt lgkmcnt(0)
	v_mfma_f32_16x16x32_bf16 v[60:63], v[144:147], v[176:179], v[60:63]
	v_mfma_f32_16x16x32_bf16 v[56:59], v[152:155], v[176:179], v[56:59]
	v_mfma_f32_16x16x32_bf16 v[44:47], v[144:147], v[184:187], v[44:47]
	v_mfma_f32_16x16x32_bf16 v[40:43], v[152:155], v[184:187], v[40:43]
	v_mfma_f32_16x16x32_bf16 v[28:31], v[144:147], v[202:205], v[28:31]
	v_mfma_f32_16x16x32_bf16 v[24:27], v[152:155], v[202:205], v[24:27]
	v_mfma_f32_16x16x32_bf16 v[12:15], v[144:147], v[214:217], v[12:15]
	v_mfma_f32_16x16x32_bf16 v[8:11], v[152:155], v[214:217], v[8:11]
	v_mfma_f32_16x16x32_bf16 v[60:63], v[148:151], v[180:183], v[60:63]
	v_mfma_f32_16x16x32_bf16 v[56:59], v[156:159], v[180:183], v[56:59]
	v_mfma_f32_16x16x32_bf16 v[44:47], v[148:151], v[188:191], v[44:47]
	v_mfma_f32_16x16x32_bf16 v[40:43], v[156:159], v[188:191], v[40:43]
	v_mfma_f32_16x16x32_bf16 v[28:31], v[148:151], v[206:209], v[28:31]
	v_mfma_f32_16x16x32_bf16 v[24:27], v[156:159], v[206:209], v[24:27]
	v_mfma_f32_16x16x32_bf16 v[12:15], v[148:151], v[218:221], v[12:15]
	v_mfma_f32_16x16x32_bf16 v[8:11], v[156:159], v[218:221], v[8:11]
	v_mfma_f32_16x16x32_bf16 v[52:55], v[160:163], v[176:179], v[52:55]
	v_mfma_f32_16x16x32_bf16 v[48:51], v[168:171], v[176:179], v[48:51]
	v_mfma_f32_16x16x32_bf16 v[36:39], v[160:163], v[184:187], v[36:39]
	v_mfma_f32_16x16x32_bf16 v[32:35], v[168:171], v[184:187], v[32:35]
	v_mfma_f32_16x16x32_bf16 v[20:23], v[160:163], v[202:205], v[20:23]
	v_mfma_f32_16x16x32_bf16 v[16:19], v[168:171], v[202:205], v[16:19]
	v_mfma_f32_16x16x32_bf16 v[4:7], v[160:163], v[214:217], v[4:7]
	v_mfma_f32_16x16x32_bf16 v[0:3], v[168:171], v[214:217], v[0:3]
	v_mfma_f32_16x16x32_bf16 v[52:55], v[164:167], v[180:183], v[52:55]
	v_mfma_f32_16x16x32_bf16 v[48:51], v[172:175], v[180:183], v[48:51]
	v_mfma_f32_16x16x32_bf16 v[36:39], v[164:167], v[188:191], v[36:39]
	v_mfma_f32_16x16x32_bf16 v[32:35], v[172:175], v[188:191], v[32:35]
	v_mfma_f32_16x16x32_bf16 v[20:23], v[164:167], v[206:209], v[20:23]
	v_mfma_f32_16x16x32_bf16 v[16:19], v[172:175], v[206:209], v[16:19]
	v_mfma_f32_16x16x32_bf16 v[4:7], v[164:167], v[218:221], v[4:7]
	v_mfma_f32_16x16x32_bf16 v[0:3], v[172:175], v[218:221], v[0:3]
	s_barrier
	ds_read_b128 v[144:147], v199
	ds_read_b128 v[148:151], v199 offset:1024
	ds_read_b128 v[152:155], v199 offset:2048
	ds_read_b128 v[156:159], v199 offset:3072
	ds_read_b128 v[160:163], v200
	ds_read_b128 v[164:167], v200 offset:1024
	ds_read_b128 v[168:171], v200 offset:2048
	ds_read_b128 v[172:175], v200 offset:3072
	s_add_u32 s16, s44, 0x40000
	s_addc_u32 s17, s45, 0
	s_mov_b32 m0, s53
	v_lshl_add_u64 v[226:227], s[16:17], 0, v[128:129]
	ds_read_b128 v[176:179], v197 offset:32768
	ds_read_b128 v[180:183], v197 offset:33792
	ds_read_b128 v[184:187], v197 offset:34816
	ds_read_b128 v[188:191], v197 offset:35840
	ds_read_b128 v[202:205], v197 offset:36864
	ds_read_b128 v[206:209], v197 offset:37888
	ds_read_b128 v[214:217], v197 offset:38912
	ds_read_b128 v[218:221], v197 offset:39936
	global_load_lds_dwordx4 v[226:227], off
	v_lshl_add_u64 v[226:227], s[16:17], 0, v[132:133]
	s_mov_b32 m0, s55
	s_nop 0
	global_load_lds_dwordx4 v[226:227], off
	s_waitcnt vmcnt(8)
	s_waitcnt lgkmcnt(0)
	s_barrier
	s_waitcnt lgkmcnt(0)
	v_mfma_f32_16x16x32_bf16 v[124:127], v[144:147], v[176:179], v[124:127]
	v_mfma_f32_16x16x32_bf16 v[120:123], v[152:155], v[176:179], v[120:123]
	v_mfma_f32_16x16x32_bf16 v[108:111], v[144:147], v[184:187], v[108:111]
	v_mfma_f32_16x16x32_bf16 v[104:107], v[152:155], v[184:187], v[104:107]
	v_mfma_f32_16x16x32_bf16 v[92:95], v[144:147], v[202:205], v[92:95]
	v_mfma_f32_16x16x32_bf16 v[88:91], v[152:155], v[202:205], v[88:91]
	v_mfma_f32_16x16x32_bf16 v[76:79], v[144:147], v[214:217], v[76:79]
	v_mfma_f32_16x16x32_bf16 v[72:75], v[152:155], v[214:217], v[72:75]
	v_mfma_f32_16x16x32_bf16 v[124:127], v[148:151], v[180:183], v[124:127]
	v_mfma_f32_16x16x32_bf16 v[120:123], v[156:159], v[180:183], v[120:123]
	v_mfma_f32_16x16x32_bf16 v[108:111], v[148:151], v[188:191], v[108:111]
	v_mfma_f32_16x16x32_bf16 v[104:107], v[156:159], v[188:191], v[104:107]
	v_mfma_f32_16x16x32_bf16 v[92:95], v[148:151], v[206:209], v[92:95]
	v_mfma_f32_16x16x32_bf16 v[88:91], v[156:159], v[206:209], v[88:91]
	v_mfma_f32_16x16x32_bf16 v[76:79], v[148:151], v[218:221], v[76:79]
	v_mfma_f32_16x16x32_bf16 v[72:75], v[156:159], v[218:221], v[72:75]
	v_mfma_f32_16x16x32_bf16 v[116:119], v[160:163], v[176:179], v[116:119]
	v_mfma_f32_16x16x32_bf16 v[112:115], v[168:171], v[176:179], v[112:115]
	v_mfma_f32_16x16x32_bf16 v[100:103], v[160:163], v[184:187], v[100:103]
	v_mfma_f32_16x16x32_bf16 v[96:99], v[168:171], v[184:187], v[96:99]
	v_mfma_f32_16x16x32_bf16 v[84:87], v[160:163], v[202:205], v[84:87]
	v_mfma_f32_16x16x32_bf16 v[80:83], v[168:171], v[202:205], v[80:83]
	v_mfma_f32_16x16x32_bf16 v[68:71], v[160:163], v[214:217], v[68:71]
	v_mfma_f32_16x16x32_bf16 v[64:67], v[168:171], v[214:217], v[64:67]
	v_mfma_f32_16x16x32_bf16 v[116:119], v[164:167], v[180:183], v[116:119]
	v_mfma_f32_16x16x32_bf16 v[112:115], v[172:175], v[180:183], v[112:115]
	v_mfma_f32_16x16x32_bf16 v[100:103], v[164:167], v[188:191], v[100:103]
	v_mfma_f32_16x16x32_bf16 v[96:99], v[172:175], v[188:191], v[96:99]
	v_mfma_f32_16x16x32_bf16 v[84:87], v[164:167], v[206:209], v[84:87]
	v_mfma_f32_16x16x32_bf16 v[80:83], v[172:175], v[206:209], v[80:83]
	v_mfma_f32_16x16x32_bf16 v[68:71], v[164:167], v[218:221], v[68:71]
	v_mfma_f32_16x16x32_bf16 v[64:67], v[172:175], v[218:221], v[64:67]
	s_barrier
; #define PG8_STAGE(bufoff, gbase, voff) do { _Pragma("unroll") for (int _i = 0; _i < 2; ++_i) \
;     __builtin_amdgcn_global_load_lds((const unsigned*)((const char*)(gbase) + (voff)[_i]), (PG8_LAS unsigned*)(lds + (bufoff) + ldsw + _i * 8192), 16, 0, 0); } while (0)
; #define PG8_LDA(dst, b, h) do { _Pragma("unroll") for (int m = 0; m < 4; ++m) _Pragma("unroll") for (int k = 0; k < 2; ++k) dst[m][k] = *(const PG8_LAS bf16x8*)(lds + PG8_SA(b, h) + aoff + m * 2048 + k * 1024); } while (0)
; #define PG8_MMA(ai, bj, At, Bt) do { __builtin_amdgcn_s_setprio(1); _Pragma("unroll") for (int m = 0; m < 4; ++m) _Pragma("unroll") for (int n = 0; n < 2; ++n) _Pragma("unroll") for (int k = 0; k < 2; ++k) \
;     acc[ai][bj][m][n] = __builtin_amdgcn_mfma_f32_16x16x32_bf16(Bt[n][k], At[m][k], acc[ai][bj][m][n], 0, 0, 0); __builtin_amdgcn_s_setprio(0); } while (0)
; #define PG8_WAIT_V(n) asm volatile("s_waitcnt vmcnt(" #n ")" ::: "memory")
; #define PG8_WAIT_L(n) asm volatile("s_waitcnt lgkmcnt(" #n ")" ::: "memory")
; #define PG8_BAR __builtin_amdgcn_s_barrier()
; #define PG8_SCHED __builtin_amdgcn_sched_barrier(0)
; DI void rows_rstd(float (&rs)[2][4], const float* ps, const Unit& u, int wr, int fr, int fq, int p_lo, int p_hi, float inv_dim) {
;   f32x4 pv[2][4];
; #pragma unroll
;   for (int ai = 0; ai < 2; ++ai)
; #pragma unroll
;     for (int m = 0; m < 4; ++m) pv[ai][m] = *(const f32x4*)(ps + (size_t)(u.pm * BM + ai * HALF + wr * 64 + m * 16 + fr) * 16 + 4 * fq);
; template <class Epi, class Sched>
; DI void gemm_phase(PG8_LAS unsigned char* lds, const Gemm g, const Sched& S, const Epi& E) {
;     ...
;       PG8_LDA(At, 1, 1); PG8_STAGE(PG8_SB(1, 0), b3, voffB); PG8_STAGE(PG8_SB(1, 1), b3 + hstepB, voffB); PG8_STAGE(PG8_SA(1, 0), a3, voffA);
;       PG8_WAIT_V(8); PG8_WAIT_L(0); PG8_BAR; PG8_MMA(1, 0, At, B0); PG8_MMA(1, 1, At, B1); PG8_BAR; PG8_SCHED;
;     }
;     if (wr == 0) PG8_BAR;
;     E(acc, cur, wr, wc, fr, fq);
	s_add_i32 s16, s69, s2
	v_lshl_add_u64 v[192:193], v[192:193], 0, s[14:15]
	s_mov_b32 m0, s16
	ds_read_b128 v[176:179], v197 offset:49152
	ds_read_b128 v[180:183], v197 offset:50176
	ds_read_b128 v[184:187], v197 offset:51200
	ds_read_b128 v[188:191], v197 offset:52224
	ds_read_b128 v[202:205], v197 offset:53248
	ds_read_b128 v[206:209], v197 offset:54272
	ds_read_b128 v[214:217], v197 offset:55296
	ds_read_b128 v[218:221], v197 offset:56320
	global_load_lds_dwordx4 v[192:193], off
	s_add_i32 m0, s16, 0x2000
	s_add_u32 s16, s40, 0x40080
	v_lshl_add_u64 v[192:193], v[210:211], 0, s[14:15]
	s_addc_u32 s17, s41, 0
	s_add_i32 s33, s70, s2
	global_load_lds_dwordx4 v[192:193], off
	v_lshl_add_u64 v[192:193], s[16:17], 0, v[130:131]
	s_mov_b32 m0, s33
	s_nop 0
	global_load_lds_dwordx4 v[192:193], off
	v_lshl_add_u64 v[192:193], s[16:17], 0, v[134:135]
	s_add_i32 m0, s33, 0x2000
	s_nop 0
	global_load_lds_dwordx4 v[192:193], off
	v_lshl_add_u64 v[192:193], v[222:223], 0, s[14:15]
	s_mov_b32 m0, s65
	s_nop 0
	global_load_lds_dwordx4 v[192:193], off
	v_lshl_add_u64 v[192:193], v[224:225], 0, s[14:15]
	s_mov_b32 m0, s66
	s_nop 0
	global_load_lds_dwordx4 v[192:193], off
	s_waitcnt vmcnt(8)
	s_waitcnt lgkmcnt(0)
	s_barrier
	s_waitcnt lgkmcnt(0)
	v_mfma_f32_16x16x32_bf16 v[60:63], v[144:147], v[176:179], v[60:63]
	v_mfma_f32_16x16x32_bf16 v[56:59], v[152:155], v[176:179], v[56:59]
	v_mfma_f32_16x16x32_bf16 v[44:47], v[144:147], v[184:187], v[44:47]
	v_mfma_f32_16x16x32_bf16 v[40:43], v[152:155], v[184:187], v[40:43]
	v_mfma_f32_16x16x32_bf16 v[28:31], v[144:147], v[202:205], v[28:31]
	v_mfma_f32_16x16x32_bf16 v[24:27], v[152:155], v[202:205], v[24:27]
	v_mfma_f32_16x16x32_bf16 v[12:15], v[144:147], v[214:217], v[12:15]
	v_mfma_f32_16x16x32_bf16 v[8:11], v[152:155], v[214:217], v[8:11]
	v_mfma_f32_16x16x32_bf16 v[60:63], v[148:151], v[180:183], v[60:63]
	v_mfma_f32_16x16x32_bf16 v[56:59], v[156:159], v[180:183], v[56:59]
	v_mfma_f32_16x16x32_bf16 v[44:47], v[148:151], v[188:191], v[44:47]
	v_mfma_f32_16x16x32_bf16 v[40:43], v[156:159], v[188:191], v[40:43]
	v_mfma_f32_16x16x32_bf16 v[28:31], v[148:151], v[206:209], v[28:31]
	v_mfma_f32_16x16x32_bf16 v[24:27], v[156:159], v[206:209], v[24:27]
	v_mfma_f32_16x16x32_bf16 v[12:15], v[148:151], v[218:221], v[12:15]
	v_mfma_f32_16x16x32_bf16 v[8:11], v[156:159], v[218:221], v[8:11]
	v_mfma_f32_16x16x32_bf16 v[52:55], v[160:163], v[176:179], v[52:55]
	v_mfma_f32_16x16x32_bf16 v[48:51], v[168:171], v[176:179], v[48:51]
	v_mfma_f32_16x16x32_bf16 v[36:39], v[160:163], v[184:187], v[36:39]
	v_mfma_f32_16x16x32_bf16 v[32:35], v[168:171], v[184:187], v[32:35]
	v_mfma_f32_16x16x32_bf16 v[20:23], v[160:163], v[202:205], v[20:23]
	v_mfma_f32_16x16x32_bf16 v[16:19], v[168:171], v[202:205], v[16:19]
	v_mfma_f32_16x16x32_bf16 v[4:7], v[160:163], v[214:217], v[4:7]
	v_mfma_f32_16x16x32_bf16 v[0:3], v[168:171], v[214:217], v[0:3]
	v_mfma_f32_16x16x32_bf16 v[52:55], v[164:167], v[180:183], v[52:55]
	v_mfma_f32_16x16x32_bf16 v[48:51], v[172:175], v[180:183], v[48:51]
	v_mfma_f32_16x16x32_bf16 v[36:39], v[164:167], v[188:191], v[36:39]
	v_mfma_f32_16x16x32_bf16 v[32:35], v[172:175], v[188:191], v[32:35]
	v_mfma_f32_16x16x32_bf16 v[20:23], v[164:167], v[206:209], v[20:23]
	v_mfma_f32_16x16x32_bf16 v[16:19], v[172:175], v[206:209], v[16:19]
	v_mfma_f32_16x16x32_bf16 v[4:7], v[164:167], v[218:221], v[4:7]
	v_mfma_f32_16x16x32_bf16 v[0:3], v[172:175], v[218:221], v[0:3]
	s_barrier
	s_add_i32 s73, s73, 2
	s_add_u32 s10, s10, 0x100
	s_addc_u32 s11, s11, 0
	s_add_u32 s31, s31, 0x100
	s_addc_u32 s72, s72, 0
	s_cmp_gt_u32 s73, 13
	s_cbranch_scc0 .LBB0_807
	v_lshl_add_u32 v184, s8, 8, v143
	v_or_b32_e32 v180, 16, v184
	v_ashrrev_i32_e32 v181, 31, v180
	v_or_b32_e32 v172, 32, v184
	v_lshlrev_b64 v[178:179], 6, v[180:181]
	v_ashrrev_i32_e32 v173, 31, v172
	v_ashrrev_i32_e32 v185, 31, v184
	v_lshl_add_u64 v[144:145], v[136:137], 0, v[178:179]
	v_lshlrev_b64 v[170:171], 6, v[172:173]
	v_lshlrev_b64 v[182:183], 6, v[184:185]
	v_lshl_add_u64 v[146:147], v[136:137], 0, v[170:171]
	global_load_dwordx4 v[162:165], v[144:145], off
	global_load_dwordx4 v[174:177], v[146:147], off
	v_lshl_add_u64 v[144:145], v[136:137], 0, v[182:183]
	global_load_dwordx4 v[186:189], v[144:145], off
	v_or_b32_e32 v168, 48, v184
	v_ashrrev_i32_e32 v169, 31, v168
	v_add_u32_e32 v160, 0x80, v184
	v_add_u32_e32 v156, 0x90, v184
	v_lshlrev_b64 v[166:167], 6, v[168:169]
	v_ashrrev_i32_e32 v161, 31, v160
	v_ashrrev_i32_e32 v157, 31, v156
	v_lshl_add_u64 v[144:145], v[136:137], 0, v[166:167]
	v_lshlrev_b64 v[158:159], 6, v[160:161]
	v_lshlrev_b64 v[154:155], 6, v[156:157]
	v_lshl_add_u64 v[146:147], v[136:137], 0, v[158:159]
	global_load_dwordx4 v[190:193], v[144:145], off
	global_load_dwordx4 v[202:205], v[146:147], off
	v_lshl_add_u64 v[144:145], v[136:137], 0, v[154:155]
	global_load_dwordx4 v[206:209], v[144:145], off
	v_add_u32_e32 v150, 0xa0, v184
	v_ashrrev_i32_e32 v151, 31, v150
	v_lshlrev_b64 v[148:149], 6, v[150:151]
	v_add_u32_e32 v146, 0xb0, v184
	v_lshl_add_u64 v[144:145], v[136:137], 0, v[148:149]
	v_ashrrev_i32_e32 v147, 31, v146
	global_load_dwordx4 v[214:217], v[144:145], off
	v_lshlrev_b64 v[144:145], 6, v[146:147]
	v_lshl_add_u64 v[152:153], v[136:137], 0, v[144:145]
	global_load_dwordx4 v[218:221], v[152:153], off
	s_and_b64 vcc, exec, s[20:21]
	s_cbranch_vccz .LBB0_810
	s_barrier

; #define PG8_STAGE(bufoff, gbase, voff) do { _Pragma("unroll") for (int _i = 0; _i < 2; ++_i) \
;     __builtin_amdgcn_global_load_lds((const unsigned*)((const char*)(gbase) + (voff)[_i]), (PG8_LAS unsigned*)(lds + (bufoff) + ldsw + _i * 8192), 16, 0, 0); } while (0)
; #define PG8_LDA(dst, b, h) do { _Pragma("unroll") for (int m = 0; m < 4; ++m) _Pragma("unroll") for (int k = 0; k < 2; ++k) dst[m][k] = *(const PG8_LAS bf16x8*)(lds + PG8_SA(b, h) + aoff + m * 2048 + k * 1024); } while (0)
; #define PG8_LDB(dst, b, h) do { _Pragma("unroll") for (int n = 0; n < 2; ++n) _Pragma("unroll") for (int k = 0; k < 2; ++k) dst[n][k] = *(const PG8_LAS bf16x8*)(lds + PG8_SB(b, h) + boff + n * 2048 + k * 1024); } while (0)
; #define PG8_MMA(ai, bj, At, Bt) do { __builtin_amdgcn_s_setprio(1); _Pragma("unroll") for (int m = 0; m < 4; ++m) _Pragma("unroll") for (int n = 0; n < 2; ++n) _Pragma("unroll") for (int k = 0; k < 2; ++k) \
;     acc[ai][bj][m][n] = __builtin_amdgcn_mfma_f32_16x16x32_bf16(Bt[n][k], At[m][k], acc[ai][bj][m][n], 0, 0, 0); __builtin_amdgcn_s_setprio(0); } while (0)
; #define PG8_WAIT_V(n) asm volatile("s_waitcnt vmcnt(" #n ")" ::: "memory")
; #define PG8_WAIT_L(n) asm volatile("s_waitcnt lgkmcnt(" #n ")" ::: "memory")
; template <class Epi, class Sched>
; DI void gemm_phase(PG8_LAS unsigned char* lds, const Gemm g, const Sched& S, const Epi& E) {
;     ...
;     const char* nA = has_next ? (const char*)g.A + (size_t)nxt.pm * tstepA : cA; const char* nB = has_next ? (const char*)g.Bt + (size_t)nxt.pn * tstepB : cB;
; #pragma unroll 1
;     for (int t = 0; t < nt; t += 2) {
;       const bool last = (t == nt - 2);
;       const char* a1 = cA + (size_t)(t + 1) * kstep;
;       const char* a2 = last ? nA : cA + (size_t)(t + 2) * kstep; const char* b2 = last ? nB : cB + (size_t)(t + 2) * kstep;
;       const char* a3 = a2 + kstep; const char* b3 = b2 + kstep;
;       PG8_LDB(B0, 0, 0); PG8_LDB(B1, 0, 1); PG8_SCHED; PG8_LDA(At, 0, 0); PG8_STAGE(PG8_SA(1, 1), a1 + hstepA, voffA);
;       PG8_WAIT_V(8); PG8_WAIT_L(0); PG8_BAR; PG8_MMA(0, 0, At, B0); PG8_MMA(0, 1, At, B1); PG8_BAR; PG8_SCHED;
;       PG8_LDA(At, 0, 1); PG8_STAGE(PG8_SB(0, 0), b2, voffB); PG8_STAGE(PG8_SB(0, 1), b2 + hstepB, voffB); PG8_STAGE(PG8_SA(0, 0), a2, voffA);
;       PG8_WAIT_V(8); PG8_WAIT_L(0); PG8_BAR; PG8_MMA(1, 0, At, B0); PG8_MMA(1, 1, At, B1); PG8_BAR; PG8_SCHED;
.LBB0_930:
	ds_read_b128 v[128:131], v191
	ds_read_b128 v[132:135], v191 offset:1024
	ds_read_b128 v[136:139], v191 offset:2048
	ds_read_b128 v[140:143], v191 offset:3072
	ds_read_b128 v[144:147], v192
	ds_read_b128 v[148:151], v192 offset:1024
	ds_read_b128 v[152:155], v192 offset:2048
	ds_read_b128 v[172:175], v192 offset:3072
	s_add_u32 s12, s0, 0x100
	s_addc_u32 s13, s1, 0
	s_cmp_eq_u32 s74, 8
	s_cselect_b32 s39, s35, s13
	s_cselect_b32 s38, s34, s12
	s_cselect_b32 s15, s37, s73
	s_cselect_b32 s14, s36, s72
	s_mov_b32 m0, s65
	v_lshl_add_u64 v[188:189], s[0:1], 0, v[166:167]
	ds_read_b128 v[176:179], v193
	ds_read_b128 v[180:183], v193 offset:1024
	ds_read_b128 v[184:187], v193 offset:2048
	ds_read_b128 v[198:201], v193 offset:3072
	ds_read_b128 v[202:205], v193 offset:4096
	ds_read_b128 v[206:209], v193 offset:5120
	ds_read_b128 v[214:217], v193 offset:6144
	ds_read_b128 v[218:221], v193 offset:7168
	global_load_lds_dwordx4 v[188:189], off
	v_lshl_add_u64 v[188:189], s[0:1], 0, v[168:169]
	s_add_i32 m0, s3, 0xe000
	s_nop 0
	global_load_lds_dwordx4 v[188:189], off
	s_waitcnt vmcnt(8)
	s_waitcnt lgkmcnt(0)
	s_barrier
	s_waitcnt lgkmcnt(0)
	v_mfma_f32_16x16x32_bf16 v[120:123], v[128:131], v[176:179], v[120:123]
	v_mfma_f32_16x16x32_bf16 v[124:127], v[136:139], v[176:179], v[124:127]
	v_mfma_f32_16x16x32_bf16 v[104:107], v[128:131], v[184:187], v[104:107]
	v_mfma_f32_16x16x32_bf16 v[108:111], v[136:139], v[184:187], v[108:111]
	v_mfma_f32_16x16x32_bf16 v[88:91], v[128:131], v[202:205], v[88:91]
	v_mfma_f32_16x16x32_bf16 v[92:95], v[136:139], v[202:205], v[92:95]
	v_mfma_f32_16x16x32_bf16 v[72:75], v[128:131], v[214:217], v[72:75]
	v_mfma_f32_16x16x32_bf16 v[76:79], v[136:139], v[214:217], v[76:79]
	v_mfma_f32_16x16x32_bf16 v[120:123], v[132:135], v[180:183], v[120:123]
	v_mfma_f32_16x16x32_bf16 v[124:127], v[140:143], v[180:183], v[124:127]
	v_mfma_f32_16x16x32_bf16 v[104:107], v[132:135], v[198:201], v[104:107]
	v_mfma_f32_16x16x32_bf16 v[108:111], v[140:143], v[198:201], v[108:111]
	v_mfma_f32_16x16x32_bf16 v[88:91], v[132:135], v[206:209], v[88:91]
	v_mfma_f32_16x16x32_bf16 v[92:95], v[140:143], v[206:209], v[92:95]
	v_mfma_f32_16x16x32_bf16 v[72:75], v[132:135], v[218:221], v[72:75]
	v_mfma_f32_16x16x32_bf16 v[76:79], v[140:143], v[218:221], v[76:79]
	v_mfma_f32_16x16x32_bf16 v[112:115], v[144:147], v[176:179], v[112:115]
	v_mfma_f32_16x16x32_bf16 v[116:119], v[152:155], v[176:179], v[116:119]
	v_mfma_f32_16x16x32_bf16 v[96:99], v[144:147], v[184:187], v[96:99]
	v_mfma_f32_16x16x32_bf16 v[100:103], v[152:155], v[184:187], v[100:103]
	v_mfma_f32_16x16x32_bf16 v[80:83], v[144:147], v[202:205], v[80:83]
	v_mfma_f32_16x16x32_bf16 v[84:87], v[152:155], v[202:205], v[84:87]
	v_mfma_f32_16x16x32_bf16 v[64:67], v[144:147], v[214:217], v[64:67]
	v_mfma_f32_16x16x32_bf16 v[68:71], v[152:155], v[214:217], v[68:71]
	v_mfma_f32_16x16x32_bf16 v[112:115], v[148:151], v[180:183], v[112:115]
	v_mfma_f32_16x16x32_bf16 v[116:119], v[172:175], v[180:183], v[116:119]
	v_mfma_f32_16x16x32_bf16 v[96:99], v[148:151], v[198:201], v[96:99]
	v_mfma_f32_16x16x32_bf16 v[100:103], v[172:175], v[198:201], v[100:103]
	v_mfma_f32_16x16x32_bf16 v[80:83], v[148:151], v[206:209], v[80:83]
	v_mfma_f32_16x16x32_bf16 v[84:87], v[172:175], v[206:209], v[84:87]
	v_mfma_f32_16x16x32_bf16 v[64:67], v[148:151], v[218:221], v[64:67]
	v_mfma_f32_16x16x32_bf16 v[68:71], v[172:175], v[218:221], v[68:71]
	s_barrier
	s_add_i32 s0, s44, s2
	v_lshl_add_u64 v[188:189], s[14:15], 0, v[158:159]
	s_mov_b32 m0, s0
	ds_read_b128 v[176:179], v193 offset:16384
	ds_read_b128 v[180:183], v193 offset:17408
	ds_read_b128 v[184:187], v193 offset:18432
	ds_read_b128 v[198:201], v193 offset:19456
	ds_read_b128 v[202:205], v193 offset:20480
	ds_read_b128 v[206:209], v193 offset:21504
	ds_read_b128 v[214:217], v193 offset:22528
	ds_read_b128 v[218:221], v193 offset:23552
	global_load_lds_dwordx4 v[188:189], off
	s_add_i32 m0, s0, 0x2000
	s_add_u32 s0, s14, 0x30000
	v_lshl_add_u64 v[210:211], s[14:15], 0, v[162:163]
	s_addc_u32 s1, s15, 0
	s_add_i32 s16, s45, s2
	global_load_lds_dwordx4 v[210:211], off
	v_lshl_add_u64 v[222:223], s[0:1], 0, v[158:159]
	s_mov_b32 m0, s16
	v_lshl_add_u64 v[224:225], s[38:39], 0, v[160:161]
	global_load_lds_dwordx4 v[222:223], off
	v_lshl_add_u64 v[222:223], s[0:1], 0, v[162:163]
	s_add_i32 m0, s16, 0x2000
	s_nop 0
	global_load_lds_dwordx4 v[222:223], off
	v_lshl_add_u64 v[222:223], s[38:39], 0, v[156:157]
	s_mov_b32 m0, s3
	s_nop 0
	global_load_lds_dwordx4 v[222:223], off
	s_mov_b32 m0, s4
	s_nop 0
	global_load_lds_dwordx4 v[224:225], off
	s_waitcnt vmcnt(8)
	s_waitcnt lgkmcnt(0)
	s_barrier
; #define PG8_STAGE(bufoff, gbase, voff) do { _Pragma("unroll") for (int _i = 0; _i < 2; ++_i) \
;     __builtin_amdgcn_global_load_lds((const unsigned*)((const char*)(gbase) + (voff)[_i]), (PG8_LAS unsigned*)(lds + (bufoff) + ldsw + _i * 8192), 16, 0, 0); } while (0)
; #define PG8_LDA(dst, b, h) do { _Pragma("unroll") for (int m = 0; m < 4; ++m) _Pragma("unroll") for (int k = 0; k < 2; ++k) dst[m][k] = *(const PG8_LAS bf16x8*)(lds + PG8_SA(b, h) + aoff + m * 2048 + k * 1024); } while (0)
; #define PG8_LDB(dst, b, h) do { _Pragma("unroll") for (int n = 0; n < 2; ++n) _Pragma("unroll") for (int k = 0; k < 2; ++k) dst[n][k] = *(const PG8_LAS bf16x8*)(lds + PG8_SB(b, h) + boff + n * 2048 + k * 1024); } while (0)
; #define PG8_MMA(ai, bj, At, Bt) do { __builtin_amdgcn_s_setprio(1); _Pragma("unroll") for (int m = 0; m < 4; ++m) _Pragma("unroll") for (int n = 0; n < 2; ++n) _Pragma("unroll") for (int k = 0; k < 2; ++k) \
;     acc[ai][bj][m][n] = __builtin_amdgcn_mfma_f32_16x16x32_bf16(Bt[n][k], At[m][k], acc[ai][bj][m][n], 0, 0, 0); __builtin_amdgcn_s_setprio(0); } while (0)
; #define PG8_WAIT_V(n) asm volatile("s_waitcnt vmcnt(" #n ")" ::: "memory")
; #define PG8_WAIT_L(n) asm volatile("s_waitcnt lgkmcnt(" #n ")" ::: "memory")
; #define PG8_BAR __builtin_amdgcn_s_barrier()
; #define PG8_SCHED __builtin_amdgcn_sched_barrier(0)
; template <class Epi, class Sched>
; DI void gemm_phase(PG8_LAS unsigned char* lds, const Gemm g, const Sched& S, const Epi& E) {
;     ...
;       PG8_WAIT_V(8); PG8_WAIT_L(0); PG8_BAR; PG8_MMA(1, 0, At, B0); PG8_MMA(1, 1, At, B1); PG8_BAR; PG8_SCHED;
;       PG8_LDB(B0, 1, 0); PG8_LDB(B1, 1, 1); PG8_SCHED; PG8_LDA(At, 1, 0); PG8_STAGE(PG8_SA(0, 1), a2 + hstepA, voffA);
;       PG8_WAIT_V(8); PG8_WAIT_L(0); PG8_BAR; PG8_MMA(0, 0, At, B0); PG8_MMA(0, 1, At, B1); PG8_BAR; PG8_SCHED;
	s_waitcnt lgkmcnt(0)
	v_mfma_f32_16x16x32_bf16 v[56:59], v[128:131], v[176:179], v[56:59]
	v_mfma_f32_16x16x32_bf16 v[60:63], v[136:139], v[176:179], v[60:63]
	v_mfma_f32_16x16x32_bf16 v[40:43], v[128:131], v[184:187], v[40:43]
	v_mfma_f32_16x16x32_bf16 v[44:47], v[136:139], v[184:187], v[44:47]
	v_mfma_f32_16x16x32_bf16 v[24:27], v[128:131], v[202:205], v[24:27]
	v_mfma_f32_16x16x32_bf16 v[28:31], v[136:139], v[202:205], v[28:31]
	v_mfma_f32_16x16x32_bf16 v[8:11], v[128:131], v[214:217], v[8:11]
	v_mfma_f32_16x16x32_bf16 v[12:15], v[136:139], v[214:217], v[12:15]
	v_mfma_f32_16x16x32_bf16 v[56:59], v[132:135], v[180:183], v[56:59]
	v_mfma_f32_16x16x32_bf16 v[60:63], v[140:143], v[180:183], v[60:63]
	v_mfma_f32_16x16x32_bf16 v[40:43], v[132:135], v[198:201], v[40:43]
	v_mfma_f32_16x16x32_bf16 v[44:47], v[140:143], v[198:201], v[44:47]
	v_mfma_f32_16x16x32_bf16 v[24:27], v[132:135], v[206:209], v[24:27]
	v_mfma_f32_16x16x32_bf16 v[28:31], v[140:143], v[206:209], v[28:31]
	v_mfma_f32_16x16x32_bf16 v[8:11], v[132:135], v[218:221], v[8:11]
	v_mfma_f32_16x16x32_bf16 v[12:15], v[140:143], v[218:221], v[12:15]
	v_mfma_f32_16x16x32_bf16 v[48:51], v[144:147], v[176:179], v[48:51]
	v_mfma_f32_16x16x32_bf16 v[52:55], v[152:155], v[176:179], v[52:55]
	v_mfma_f32_16x16x32_bf16 v[32:35], v[144:147], v[184:187], v[32:35]
	v_mfma_f32_16x16x32_bf16 v[36:39], v[152:155], v[184:187], v[36:39]
	v_mfma_f32_16x16x32_bf16 v[16:19], v[144:147], v[202:205], v[16:19]
	v_mfma_f32_16x16x32_bf16 v[20:23], v[152:155], v[202:205], v[20:23]
	v_mfma_f32_16x16x32_bf16 v[4:7], v[144:147], v[214:217], v[4:7]
	v_mfma_f32_16x16x32_bf16 v[0:3], v[152:155], v[214:217], v[0:3]
	v_mfma_f32_16x16x32_bf16 v[48:51], v[148:151], v[180:183], v[48:51]
	v_mfma_f32_16x16x32_bf16 v[52:55], v[172:175], v[180:183], v[52:55]
	v_mfma_f32_16x16x32_bf16 v[32:35], v[148:151], v[198:201], v[32:35]
	v_mfma_f32_16x16x32_bf16 v[36:39], v[172:175], v[198:201], v[36:39]
	v_mfma_f32_16x16x32_bf16 v[16:19], v[148:151], v[206:209], v[16:19]
	v_mfma_f32_16x16x32_bf16 v[20:23], v[172:175], v[206:209], v[20:23]
	v_mfma_f32_16x16x32_bf16 v[4:7], v[148:151], v[218:221], v[4:7]
	v_mfma_f32_16x16x32_bf16 v[0:3], v[172:175], v[218:221], v[0:3]
	s_barrier
	ds_read_b128 v[128:131], v195
	ds_read_b128 v[132:135], v195 offset:1024
	ds_read_b128 v[136:139], v195 offset:2048
	ds_read_b128 v[140:143], v195 offset:3072
	ds_read_b128 v[144:147], v196
	ds_read_b128 v[148:151], v196 offset:1024
	ds_read_b128 v[152:155], v196 offset:2048
	ds_read_b128 v[172:175], v196 offset:3072
	s_add_u32 s0, s38, 0x58000
	s_addc_u32 s1, s39, 0
	s_mov_b32 m0, s5
	v_lshl_add_u64 v[226:227], s[0:1], 0, v[156:157]
	ds_read_b128 v[176:179], v193 offset:32768
	ds_read_b128 v[180:183], v193 offset:33792
	ds_read_b128 v[184:187], v193 offset:34816
	ds_read_b128 v[198:201], v193 offset:35840
	ds_read_b128 v[202:205], v193 offset:36864
	ds_read_b128 v[206:209], v193 offset:37888
	ds_read_b128 v[214:217], v193 offset:38912
	ds_read_b128 v[218:221], v193 offset:39936
	global_load_lds_dwordx4 v[226:227], off
	v_lshl_add_u64 v[226:227], s[0:1], 0, v[160:161]
	s_mov_b32 m0, s18
	s_nop 0
	global_load_lds_dwordx4 v[226:227], off
	s_waitcnt vmcnt(8)
	s_waitcnt lgkmcnt(0)
	s_barrier
	s_waitcnt lgkmcnt(0)
	v_mfma_f32_16x16x32_bf16 v[120:123], v[128:131], v[176:179], v[120:123]
	v_mfma_f32_16x16x32_bf16 v[124:127], v[136:139], v[176:179], v[124:127]
	v_mfma_f32_16x16x32_bf16 v[104:107], v[128:131], v[184:187], v[104:107]
	v_mfma_f32_16x16x32_bf16 v[108:111], v[136:139], v[184:187], v[108:111]
	v_mfma_f32_16x16x32_bf16 v[88:91], v[128:131], v[202:205], v[88:91]
	v_mfma_f32_16x16x32_bf16 v[92:95], v[136:139], v[202:205], v[92:95]
	v_mfma_f32_16x16x32_bf16 v[72:75], v[128:131], v[214:217], v[72:75]
	v_mfma_f32_16x16x32_bf16 v[76:79], v[136:139], v[214:217], v[76:79]
	v_mfma_f32_16x16x32_bf16 v[120:123], v[132:135], v[180:183], v[120:123]
	v_mfma_f32_16x16x32_bf16 v[124:127], v[140:143], v[180:183], v[124:127]
	v_mfma_f32_16x16x32_bf16 v[104:107], v[132:135], v[198:201], v[104:107]
	v_mfma_f32_16x16x32_bf16 v[108:111], v[140:143], v[198:201], v[108:111]
	v_mfma_f32_16x16x32_bf16 v[88:91], v[132:135], v[206:209], v[88:91]
	v_mfma_f32_16x16x32_bf16 v[92:95], v[140:143], v[206:209], v[92:95]
	v_mfma_f32_16x16x32_bf16 v[72:75], v[132:135], v[218:221], v[72:75]
	v_mfma_f32_16x16x32_bf16 v[76:79], v[140:143], v[218:221], v[76:79]
	v_mfma_f32_16x16x32_bf16 v[112:115], v[144:147], v[176:179], v[112:115]
	v_mfma_f32_16x16x32_bf16 v[116:119], v[152:155], v[176:179], v[116:119]
	v_mfma_f32_16x16x32_bf16 v[96:99], v[144:147], v[184:187], v[96:99]
	v_mfma_f32_16x16x32_bf16 v[100:103], v[152:155], v[184:187], v[100:103]
	v_mfma_f32_16x16x32_bf16 v[80:83], v[144:147], v[202:205], v[80:83]
	v_mfma_f32_16x16x32_bf16 v[84:87], v[152:155], v[202:205], v[84:87]
	v_mfma_f32_16x16x32_bf16 v[64:67], v[144:147], v[214:217], v[64:67]
	v_mfma_f32_16x16x32_bf16 v[68:71], v[152:155], v[214:217], v[68:71]
	v_mfma_f32_16x16x32_bf16 v[112:115], v[148:151], v[180:183], v[112:115]
	v_mfma_f32_16x16x32_bf16 v[116:119], v[172:175], v[180:183], v[116:119]
	v_mfma_f32_16x16x32_bf16 v[96:99], v[148:151], v[198:201], v[96:99]
	v_mfma_f32_16x16x32_bf16 v[100:103], v[172:175], v[198:201], v[100:103]
	v_mfma_f32_16x16x32_bf16 v[80:83], v[148:151], v[206:209], v[80:83]
	v_mfma_f32_16x16x32_bf16 v[84:87], v[172:175], v[206:209], v[84:87]
	v_mfma_f32_16x16x32_bf16 v[64:67], v[148:151], v[218:221], v[64:67]
	v_mfma_f32_16x16x32_bf16 v[68:71], v[172:175], v[218:221], v[68:71]
	s_barrier
; #define PG8_STAGE(bufoff, gbase, voff) do { _Pragma("unroll") for (int _i = 0; _i < 2; ++_i) \
;     __builtin_amdgcn_global_load_lds((const unsigned*)((const char*)(gbase) + (voff)[_i]), (PG8_LAS unsigned*)(lds + (bufoff) + ldsw + _i * 8192), 16, 0, 0); } while (0)
; #define PG8_LDA(dst, b, h) do { _Pragma("unroll") for (int m = 0; m < 4; ++m) _Pragma("unroll") for (int k = 0; k < 2; ++k) dst[m][k] = *(const PG8_LAS bf16x8*)(lds + PG8_SA(b, h) + aoff + m * 2048 + k * 1024); } while (0)
; #define PG8_MMA(ai, bj, At, Bt) do { __builtin_amdgcn_s_setprio(1); _Pragma("unroll") for (int m = 0; m < 4; ++m) _Pragma("unroll") for (int n = 0; n < 2; ++n) _Pragma("unroll") for (int k = 0; k < 2; ++k) \
;     acc[ai][bj][m][n] = __builtin_amdgcn_mfma_f32_16x16x32_bf16(Bt[n][k], At[m][k], acc[ai][bj][m][n], 0, 0, 0); __builtin_amdgcn_s_setprio(0); } while (0)
; #define PG8_WAIT_V(n) asm volatile("s_waitcnt vmcnt(" #n ")" ::: "memory")
; #define PG8_WAIT_L(n) asm volatile("s_waitcnt lgkmcnt(" #n ")" ::: "memory")
; #define PG8_BAR __builtin_amdgcn_s_barrier()
; #define PG8_SCHED __builtin_amdgcn_sched_barrier(0)
; template <class Epi, class Sched>
; DI void gemm_phase(PG8_LAS unsigned char* lds, const Gemm g, const Sched& S, const Epi& E) {
;     ...
;       PG8_LDA(At, 1, 1); PG8_STAGE(PG8_SB(1, 0), b3, voffB); PG8_STAGE(PG8_SB(1, 1), b3 + hstepB, voffB); PG8_STAGE(PG8_SA(1, 0), a3, voffA);
;       PG8_WAIT_V(8); PG8_WAIT_L(0); PG8_BAR; PG8_MMA(1, 0, At, B0); PG8_MMA(1, 1, At, B1); PG8_BAR; PG8_SCHED;
;     }
;     if (wr == 0) PG8_BAR;
	s_add_i32 s0, s66, s2
	v_lshl_add_u64 v[188:189], v[188:189], 0, s[26:27]
	s_mov_b32 m0, s0
	ds_read_b128 v[176:179], v193 offset:49152
	ds_read_b128 v[180:183], v193 offset:50176
	ds_read_b128 v[184:187], v193 offset:51200
	ds_read_b128 v[198:201], v193 offset:52224
	ds_read_b128 v[202:205], v193 offset:53248
	ds_read_b128 v[206:209], v193 offset:54272
	ds_read_b128 v[214:217], v193 offset:55296
	ds_read_b128 v[218:221], v193 offset:56320
	global_load_lds_dwordx4 v[188:189], off
	s_add_i32 m0, s0, 0x2000
	s_add_u32 s0, s14, 0x30080
	v_lshl_add_u64 v[188:189], v[210:211], 0, s[26:27]
	s_addc_u32 s1, s15, 0
	s_add_i32 s14, s67, s2
	global_load_lds_dwordx4 v[188:189], off
	v_lshl_add_u64 v[188:189], s[0:1], 0, v[158:159]
	s_mov_b32 m0, s14
	s_nop 0
	global_load_lds_dwordx4 v[188:189], off
	v_lshl_add_u64 v[188:189], s[0:1], 0, v[162:163]
	s_add_i32 m0, s14, 0x2000
	s_nop 0
	global_load_lds_dwordx4 v[188:189], off
	v_lshl_add_u64 v[188:189], v[222:223], 0, s[26:27]
	s_mov_b32 m0, s19
	s_nop 0
	global_load_lds_dwordx4 v[188:189], off
	v_lshl_add_u64 v[188:189], v[224:225], 0, s[26:27]
	s_mov_b32 m0, s31
	s_nop 0
	global_load_lds_dwordx4 v[188:189], off
	s_waitcnt vmcnt(8)
	s_waitcnt lgkmcnt(0)
	s_barrier
	s_waitcnt lgkmcnt(0)
	v_mfma_f32_16x16x32_bf16 v[56:59], v[128:131], v[176:179], v[56:59]
	v_mfma_f32_16x16x32_bf16 v[60:63], v[136:139], v[176:179], v[60:63]
	v_mfma_f32_16x16x32_bf16 v[40:43], v[128:131], v[184:187], v[40:43]
	v_mfma_f32_16x16x32_bf16 v[44:47], v[136:139], v[184:187], v[44:47]
	v_mfma_f32_16x16x32_bf16 v[24:27], v[128:131], v[202:205], v[24:27]
	v_mfma_f32_16x16x32_bf16 v[28:31], v[136:139], v[202:205], v[28:31]
	v_mfma_f32_16x16x32_bf16 v[8:11], v[128:131], v[214:217], v[8:11]
	v_mfma_f32_16x16x32_bf16 v[12:15], v[136:139], v[214:217], v[12:15]
	v_mfma_f32_16x16x32_bf16 v[56:59], v[132:135], v[180:183], v[56:59]
	v_mfma_f32_16x16x32_bf16 v[60:63], v[140:143], v[180:183], v[60:63]
	v_mfma_f32_16x16x32_bf16 v[40:43], v[132:135], v[198:201], v[40:43]
	v_mfma_f32_16x16x32_bf16 v[44:47], v[140:143], v[198:201], v[44:47]
	v_mfma_f32_16x16x32_bf16 v[24:27], v[132:135], v[206:209], v[24:27]
	v_mfma_f32_16x16x32_bf16 v[28:31], v[140:143], v[206:209], v[28:31]
	v_mfma_f32_16x16x32_bf16 v[8:11], v[132:135], v[218:221], v[8:11]
	v_mfma_f32_16x16x32_bf16 v[12:15], v[140:143], v[218:221], v[12:15]
	v_mfma_f32_16x16x32_bf16 v[48:51], v[144:147], v[176:179], v[48:51]
	v_mfma_f32_16x16x32_bf16 v[52:55], v[152:155], v[176:179], v[52:55]
	v_mfma_f32_16x16x32_bf16 v[32:35], v[144:147], v[184:187], v[32:35]
	v_mfma_f32_16x16x32_bf16 v[36:39], v[152:155], v[184:187], v[36:39]
	v_mfma_f32_16x16x32_bf16 v[16:19], v[144:147], v[202:205], v[16:19]
	v_mfma_f32_16x16x32_bf16 v[20:23], v[152:155], v[202:205], v[20:23]
	v_mfma_f32_16x16x32_bf16 v[4:7], v[144:147], v[214:217], v[4:7]
	v_mfma_f32_16x16x32_bf16 v[0:3], v[152:155], v[214:217], v[0:3]
	v_mfma_f32_16x16x32_bf16 v[48:51], v[148:151], v[180:183], v[48:51]
	v_mfma_f32_16x16x32_bf16 v[52:55], v[172:175], v[180:183], v[52:55]
	v_mfma_f32_16x16x32_bf16 v[32:35], v[148:151], v[198:201], v[32:35]
	v_mfma_f32_16x16x32_bf16 v[36:39], v[172:175], v[198:201], v[36:39]
	v_mfma_f32_16x16x32_bf16 v[16:19], v[148:151], v[206:209], v[16:19]
	v_mfma_f32_16x16x32_bf16 v[20:23], v[172:175], v[206:209], v[20:23]
	v_mfma_f32_16x16x32_bf16 v[4:7], v[148:151], v[218:221], v[4:7]
	v_mfma_f32_16x16x32_bf16 v[0:3], v[172:175], v[218:221], v[0:3]
	s_barrier
	s_add_i32 s74, s74, 2
	s_add_u32 s72, s72, 0x100
	s_addc_u32 s73, s73, 0
	s_cmp_gt_u32 s74, 9
	s_mov_b64 s[0:1], s[12:13]
	s_cbranch_scc0 .LBB0_930
	s_and_b64 vcc, exec, s[28:29]
	s_cbranch_vccz .LBB0_933
	s_barrier

; #define PG8_STAGE(bufoff, gbase, voff) do { _Pragma("unroll") for (int _i = 0; _i < 2; ++_i) \
;     __builtin_amdgcn_global_load_lds((const unsigned*)((const char*)(gbase) + (voff)[_i]), (PG8_LAS unsigned*)(lds + (bufoff) + ldsw + _i * 8192), 16, 0, 0); } while (0)
; #define PG8_LDA(dst, b, h) do { _Pragma("unroll") for (int m = 0; m < 4; ++m) _Pragma("unroll") for (int k = 0; k < 2; ++k) dst[m][k] = *(const PG8_LAS bf16x8*)(lds + PG8_SA(b, h) + aoff + m * 2048 + k * 1024); } while (0)
; #define PG8_LDB(dst, b, h) do { _Pragma("unroll") for (int n = 0; n < 2; ++n) _Pragma("unroll") for (int k = 0; k < 2; ++k) dst[n][k] = *(const PG8_LAS bf16x8*)(lds + PG8_SB(b, h) + boff + n * 2048 + k * 1024); } while (0)
; #define PG8_MMA(ai, bj, At, Bt) do { __builtin_amdgcn_s_setprio(1); _Pragma("unroll") for (int m = 0; m < 4; ++m) _Pragma("unroll") for (int n = 0; n < 2; ++n) _Pragma("unroll") for (int k = 0; k < 2; ++k) \
;     acc[ai][bj][m][n] = __builtin_amdgcn_mfma_f32_16x16x32_bf16(Bt[n][k], At[m][k], acc[ai][bj][m][n], 0, 0, 0); __builtin_amdgcn_s_setprio(0); } while (0)
; #define PG8_WAIT_V(n) asm volatile("s_waitcnt vmcnt(" #n ")" ::: "memory")
; #define PG8_WAIT_L(n) asm volatile("s_waitcnt lgkmcnt(" #n ")" ::: "memory")
; template <class Epi, class Sched>
; DI void gemm_phase(PG8_LAS unsigned char* lds, const Gemm g, const Sched& S, const Epi& E) {
;     ...
;     const char* nA = has_next ? (const char*)g.A + (size_t)nxt.pm * tstepA : cA; const char* nB = has_next ? (const char*)g.Bt + (size_t)nxt.pn * tstepB : cB;
; #pragma unroll 1
;     for (int t = 0; t < nt; t += 2) {
;       const bool last = (t == nt - 2);
;       const char* a1 = cA + (size_t)(t + 1) * kstep;
;       const char* a2 = last ? nA : cA + (size_t)(t + 2) * kstep; const char* b2 = last ? nB : cB + (size_t)(t + 2) * kstep;
;       const char* a3 = a2 + kstep; const char* b3 = b2 + kstep;
;       PG8_LDB(B0, 0, 0); PG8_LDB(B1, 0, 1); PG8_SCHED; PG8_LDA(At, 0, 0); PG8_STAGE(PG8_SA(1, 1), a1 + hstepA, voffA);
;       PG8_WAIT_V(8); PG8_WAIT_L(0); PG8_BAR; PG8_MMA(0, 0, At, B0); PG8_MMA(0, 1, At, B1); PG8_BAR; PG8_SCHED;
;       PG8_LDA(At, 0, 1); PG8_STAGE(PG8_SB(0, 0), b2, voffB); PG8_STAGE(PG8_SB(0, 1), b2 + hstepB, voffB); PG8_STAGE(PG8_SA(0, 0), a2, voffA);
;       PG8_WAIT_V(8); PG8_WAIT_L(0); PG8_BAR; PG8_MMA(1, 0, At, B0); PG8_MMA(1, 1, At, B1); PG8_BAR; PG8_SCHED;
.LBB0_984:
	s_add_u32 s33, s12, s70
	s_addc_u32 s56, s13, s71
	s_add_u32 s57, s33, 0x100
	s_addc_u32 s62, s56, 0
	s_and_b64 s[16:17], s[64:65], exec
	s_cselect_b32 s73, s39, s62
	s_cselect_b32 s72, s38, s57
	s_add_u32 s16, s10, s70
	s_addc_u32 s17, s11, s71
	s_add_u32 s57, s16, 0x100
	s_addc_u32 s62, s17, 0
	s_and_b64 s[16:17], s[64:65], exec
	s_cselect_b32 s75, s1, s62
	s_cselect_b32 s74, s37, s57
	s_add_u32 s66, s33, 0x58080
	ds_read_b128 v[128:131], v171
	ds_read_b128 v[132:135], v171 offset:1024
	ds_read_b128 v[136:139], v171 offset:2048
	ds_read_b128 v[140:143], v171 offset:3072
	ds_read_b128 v[144:147], v190
	ds_read_b128 v[148:151], v190 offset:1024
	ds_read_b128 v[152:155], v190 offset:2048
	ds_read_b128 v[172:175], v190 offset:3072
	s_addc_u32 s67, s56, 0
	s_add_i32 s16, s94, s55
	s_add_i32 m0, s68, 0xc000
	s_add_i32 s57, s68, 0xe000
	s_add_i32 s56, s16, 0x2000
	s_add_u32 s76, s74, 0x10000
	s_addc_u32 s77, s75, 0
	s_add_i32 s63, s95, s55
	s_add_i32 s62, s63, 0x2000
	s_add_u32 s70, s72, 0x58000
	s_addc_u32 s71, s73, 0
	s_add_i32 vcc_lo, s18, s55
	s_add_i32 s33, vcc_lo, 0x2000
	s_add_u32 s64, s74, 0x10080
	s_addc_u32 s65, s75, 0
	s_add_i32 vcc_hi, s19, s55
	s_add_i32 s17, vcc_hi, 0x2000
	v_lshl_add_u64 v[188:189], s[66:67], 0, v[156:157]
	ds_read_b128 v[176:179], v191
	ds_read_b128 v[180:183], v191 offset:1024
	ds_read_b128 v[184:187], v191 offset:2048
	ds_read_b128 v[196:199], v191 offset:3072
	ds_read_b128 v[200:203], v191 offset:4096
	ds_read_b128 v[204:207], v191 offset:5120
	ds_read_b128 v[208:211], v191 offset:6144
	ds_read_b128 v[214:217], v191 offset:7168
	global_load_lds_dwordx4 v[188:189], off
	v_lshl_add_u64 v[188:189], s[66:67], 0, v[160:161]
	s_mov_b32 m0, s57
	s_nop 0
	global_load_lds_dwordx4 v[188:189], off
	s_waitcnt vmcnt(8)
	s_waitcnt lgkmcnt(0)
	s_barrier
	s_waitcnt lgkmcnt(0)
	v_mfma_f32_16x16x32_bf16 v[124:127], v[128:131], v[176:179], v[124:127]
	v_mfma_f32_16x16x32_bf16 v[120:123], v[136:139], v[176:179], v[120:123]
	v_mfma_f32_16x16x32_bf16 v[108:111], v[128:131], v[184:187], v[108:111]
	v_mfma_f32_16x16x32_bf16 v[104:107], v[136:139], v[184:187], v[104:107]
	v_mfma_f32_16x16x32_bf16 v[92:95], v[128:131], v[200:203], v[92:95]
	v_mfma_f32_16x16x32_bf16 v[88:91], v[136:139], v[200:203], v[88:91]
	v_mfma_f32_16x16x32_bf16 v[76:79], v[128:131], v[208:211], v[76:79]
	v_mfma_f32_16x16x32_bf16 v[72:75], v[136:139], v[208:211], v[72:75]
	v_mfma_f32_16x16x32_bf16 v[124:127], v[132:135], v[180:183], v[124:127]
	v_mfma_f32_16x16x32_bf16 v[120:123], v[140:143], v[180:183], v[120:123]
	v_mfma_f32_16x16x32_bf16 v[108:111], v[132:135], v[196:199], v[108:111]
	v_mfma_f32_16x16x32_bf16 v[104:107], v[140:143], v[196:199], v[104:107]
	v_mfma_f32_16x16x32_bf16 v[92:95], v[132:135], v[204:207], v[92:95]
	v_mfma_f32_16x16x32_bf16 v[88:91], v[140:143], v[204:207], v[88:91]
	v_mfma_f32_16x16x32_bf16 v[76:79], v[132:135], v[214:217], v[76:79]
	v_mfma_f32_16x16x32_bf16 v[72:75], v[140:143], v[214:217], v[72:75]
	v_mfma_f32_16x16x32_bf16 v[116:119], v[144:147], v[176:179], v[116:119]
	v_mfma_f32_16x16x32_bf16 v[112:115], v[152:155], v[176:179], v[112:115]
	v_mfma_f32_16x16x32_bf16 v[100:103], v[144:147], v[184:187], v[100:103]
	v_mfma_f32_16x16x32_bf16 v[96:99], v[152:155], v[184:187], v[96:99]
	v_mfma_f32_16x16x32_bf16 v[84:87], v[144:147], v[200:203], v[84:87]
	v_mfma_f32_16x16x32_bf16 v[80:83], v[152:155], v[200:203], v[80:83]
	v_mfma_f32_16x16x32_bf16 v[68:71], v[144:147], v[208:211], v[68:71]
	v_mfma_f32_16x16x32_bf16 v[64:67], v[152:155], v[208:211], v[64:67]
	v_mfma_f32_16x16x32_bf16 v[116:119], v[148:151], v[180:183], v[116:119]
	v_mfma_f32_16x16x32_bf16 v[112:115], v[172:175], v[180:183], v[112:115]
	v_mfma_f32_16x16x32_bf16 v[100:103], v[148:151], v[196:199], v[100:103]
	v_mfma_f32_16x16x32_bf16 v[96:99], v[172:175], v[196:199], v[96:99]
	v_mfma_f32_16x16x32_bf16 v[84:87], v[148:151], v[204:207], v[84:87]
	v_mfma_f32_16x16x32_bf16 v[80:83], v[172:175], v[204:207], v[80:83]
	v_mfma_f32_16x16x32_bf16 v[68:71], v[148:151], v[214:217], v[68:71]
	v_mfma_f32_16x16x32_bf16 v[64:67], v[172:175], v[214:217], v[64:67]
	s_barrier
	s_mov_b32 m0, s16
	v_lshl_add_u64 v[188:189], s[74:75], 0, v[158:159]
	ds_read_b128 v[176:179], v191 offset:16384
	ds_read_b128 v[180:183], v191 offset:17408
	ds_read_b128 v[184:187], v191 offset:18432
	ds_read_b128 v[196:199], v191 offset:19456
	ds_read_b128 v[200:203], v191 offset:20480
	ds_read_b128 v[204:207], v191 offset:21504
	ds_read_b128 v[208:211], v191 offset:22528
	ds_read_b128 v[214:217], v191 offset:23552
	global_load_lds_dwordx4 v[188:189], off
	v_lshl_add_u64 v[218:219], s[74:75], 0, v[162:163]
	s_mov_b32 m0, s56
	v_lshl_add_u64 v[220:221], s[76:77], 0, v[158:159]
	global_load_lds_dwordx4 v[218:219], off
	s_mov_b32 m0, s63
	v_lshl_add_u64 v[222:223], s[72:73], 0, v[160:161]
	global_load_lds_dwordx4 v[220:221], off
	v_lshl_add_u64 v[220:221], s[76:77], 0, v[162:163]
	s_mov_b32 m0, s62
	s_nop 0
	global_load_lds_dwordx4 v[220:221], off
	v_lshl_add_u64 v[220:221], s[72:73], 0, v[156:157]
	s_mov_b32 m0, s68
	s_nop 0
	global_load_lds_dwordx4 v[220:221], off
	s_mov_b32 m0, s69
	s_nop 0
	global_load_lds_dwordx4 v[222:223], off
	s_waitcnt vmcnt(8)
	s_waitcnt lgkmcnt(0)
	s_barrier
; #define PG8_STAGE(bufoff, gbase, voff) do { _Pragma("unroll") for (int _i = 0; _i < 2; ++_i) \
;     __builtin_amdgcn_global_load_lds((const unsigned*)((const char*)(gbase) + (voff)[_i]), (PG8_LAS unsigned*)(lds + (bufoff) + ldsw + _i * 8192), 16, 0, 0); } while (0)
; #define PG8_LDA(dst, b, h) do { _Pragma("unroll") for (int m = 0; m < 4; ++m) _Pragma("unroll") for (int k = 0; k < 2; ++k) dst[m][k] = *(const PG8_LAS bf16x8*)(lds + PG8_SA(b, h) + aoff + m * 2048 + k * 1024); } while (0)
; #define PG8_LDB(dst, b, h) do { _Pragma("unroll") for (int n = 0; n < 2; ++n) _Pragma("unroll") for (int k = 0; k < 2; ++k) dst[n][k] = *(const PG8_LAS bf16x8*)(lds + PG8_SB(b, h) + boff + n * 2048 + k * 1024); } while (0)
; #define PG8_MMA(ai, bj, At, Bt) do { __builtin_amdgcn_s_setprio(1); _Pragma("unroll") for (int m = 0; m < 4; ++m) _Pragma("unroll") for (int n = 0; n < 2; ++n) _Pragma("unroll") for (int k = 0; k < 2; ++k) \
;     acc[ai][bj][m][n] = __builtin_amdgcn_mfma_f32_16x16x32_bf16(Bt[n][k], At[m][k], acc[ai][bj][m][n], 0, 0, 0); __builtin_amdgcn_s_setprio(0); } while (0)
; #define PG8_WAIT_V(n) asm volatile("s_waitcnt vmcnt(" #n ")" ::: "memory")
; #define PG8_WAIT_L(n) asm volatile("s_waitcnt lgkmcnt(" #n ")" ::: "memory")
; #define PG8_BAR __builtin_amdgcn_s_barrier()
; #define PG8_SCHED __builtin_amdgcn_sched_barrier(0)
; template <class Epi, class Sched>
; DI void gemm_phase(PG8_LAS unsigned char* lds, const Gemm g, const Sched& S, const Epi& E) {
;     ...
;       PG8_WAIT_V(8); PG8_WAIT_L(0); PG8_BAR; PG8_MMA(1, 0, At, B0); PG8_MMA(1, 1, At, B1); PG8_BAR; PG8_SCHED;
;       PG8_LDB(B0, 1, 0); PG8_LDB(B1, 1, 1); PG8_SCHED; PG8_LDA(At, 1, 0); PG8_STAGE(PG8_SA(0, 1), a2 + hstepA, voffA);
;       PG8_WAIT_V(8); PG8_WAIT_L(0); PG8_BAR; PG8_MMA(0, 0, At, B0); PG8_MMA(0, 1, At, B1); PG8_BAR; PG8_SCHED;
	s_waitcnt lgkmcnt(0)
	v_mfma_f32_16x16x32_bf16 v[60:63], v[128:131], v[176:179], v[60:63]
	v_mfma_f32_16x16x32_bf16 v[56:59], v[136:139], v[176:179], v[56:59]
	v_mfma_f32_16x16x32_bf16 v[44:47], v[128:131], v[184:187], v[44:47]
	v_mfma_f32_16x16x32_bf16 v[40:43], v[136:139], v[184:187], v[40:43]
	v_mfma_f32_16x16x32_bf16 v[28:31], v[128:131], v[200:203], v[28:31]
	v_mfma_f32_16x16x32_bf16 v[24:27], v[136:139], v[200:203], v[24:27]
	v_mfma_f32_16x16x32_bf16 v[12:15], v[128:131], v[208:211], v[12:15]
	v_mfma_f32_16x16x32_bf16 v[8:11], v[136:139], v[208:211], v[8:11]
	v_mfma_f32_16x16x32_bf16 v[60:63], v[132:135], v[180:183], v[60:63]
	v_mfma_f32_16x16x32_bf16 v[56:59], v[140:143], v[180:183], v[56:59]
	v_mfma_f32_16x16x32_bf16 v[44:47], v[132:135], v[196:199], v[44:47]
	v_mfma_f32_16x16x32_bf16 v[40:43], v[140:143], v[196:199], v[40:43]
	v_mfma_f32_16x16x32_bf16 v[28:31], v[132:135], v[204:207], v[28:31]
	v_mfma_f32_16x16x32_bf16 v[24:27], v[140:143], v[204:207], v[24:27]
	v_mfma_f32_16x16x32_bf16 v[12:15], v[132:135], v[214:217], v[12:15]
	v_mfma_f32_16x16x32_bf16 v[8:11], v[140:143], v[214:217], v[8:11]
	v_mfma_f32_16x16x32_bf16 v[52:55], v[144:147], v[176:179], v[52:55]
	v_mfma_f32_16x16x32_bf16 v[48:51], v[152:155], v[176:179], v[48:51]
	v_mfma_f32_16x16x32_bf16 v[36:39], v[144:147], v[184:187], v[36:39]
	v_mfma_f32_16x16x32_bf16 v[32:35], v[152:155], v[184:187], v[32:35]
	v_mfma_f32_16x16x32_bf16 v[20:23], v[144:147], v[200:203], v[20:23]
	v_mfma_f32_16x16x32_bf16 v[16:19], v[152:155], v[200:203], v[16:19]
	v_mfma_f32_16x16x32_bf16 v[4:7], v[144:147], v[208:211], v[4:7]
	v_mfma_f32_16x16x32_bf16 v[0:3], v[152:155], v[208:211], v[0:3]
	v_mfma_f32_16x16x32_bf16 v[52:55], v[148:151], v[180:183], v[52:55]
	v_mfma_f32_16x16x32_bf16 v[48:51], v[172:175], v[180:183], v[48:51]
	v_mfma_f32_16x16x32_bf16 v[36:39], v[148:151], v[196:199], v[36:39]
	v_mfma_f32_16x16x32_bf16 v[32:35], v[172:175], v[196:199], v[32:35]
	v_mfma_f32_16x16x32_bf16 v[20:23], v[148:151], v[204:207], v[20:23]
	v_mfma_f32_16x16x32_bf16 v[16:19], v[172:175], v[204:207], v[16:19]
	v_mfma_f32_16x16x32_bf16 v[4:7], v[148:151], v[214:217], v[4:7]
	v_mfma_f32_16x16x32_bf16 v[0:3], v[172:175], v[214:217], v[0:3]
	s_barrier
	ds_read_b128 v[128:131], v193
	ds_read_b128 v[132:135], v193 offset:1024
	ds_read_b128 v[136:139], v193 offset:2048
	ds_read_b128 v[140:143], v193 offset:3072
	ds_read_b128 v[144:147], v194
	ds_read_b128 v[148:151], v194 offset:1024
	ds_read_b128 v[152:155], v194 offset:2048
	ds_read_b128 v[172:175], v194 offset:3072
	s_mov_b32 m0, s79
	v_lshl_add_u64 v[224:225], s[70:71], 0, v[156:157]
	ds_read_b128 v[176:179], v191 offset:32768
	ds_read_b128 v[180:183], v191 offset:33792
	ds_read_b128 v[184:187], v191 offset:34816
	ds_read_b128 v[196:199], v191 offset:35840
	ds_read_b128 v[200:203], v191 offset:36864
	ds_read_b128 v[204:207], v191 offset:37888
	ds_read_b128 v[208:211], v191 offset:38912
	ds_read_b128 v[214:217], v191 offset:39936
	global_load_lds_dwordx4 v[224:225], off
	v_lshl_add_u64 v[224:225], s[70:71], 0, v[160:161]
	s_mov_b32 m0, s90
	s_nop 0
	global_load_lds_dwordx4 v[224:225], off
	s_waitcnt vmcnt(8)
	s_waitcnt lgkmcnt(0)
	s_barrier
	s_waitcnt lgkmcnt(0)
	v_mfma_f32_16x16x32_bf16 v[124:127], v[128:131], v[176:179], v[124:127]
	v_mfma_f32_16x16x32_bf16 v[120:123], v[136:139], v[176:179], v[120:123]
	v_mfma_f32_16x16x32_bf16 v[108:111], v[128:131], v[184:187], v[108:111]
	v_mfma_f32_16x16x32_bf16 v[104:107], v[136:139], v[184:187], v[104:107]
	v_mfma_f32_16x16x32_bf16 v[92:95], v[128:131], v[200:203], v[92:95]
	v_mfma_f32_16x16x32_bf16 v[88:91], v[136:139], v[200:203], v[88:91]
	v_mfma_f32_16x16x32_bf16 v[76:79], v[128:131], v[208:211], v[76:79]
	v_mfma_f32_16x16x32_bf16 v[72:75], v[136:139], v[208:211], v[72:75]
	v_mfma_f32_16x16x32_bf16 v[124:127], v[132:135], v[180:183], v[124:127]
	v_mfma_f32_16x16x32_bf16 v[120:123], v[140:143], v[180:183], v[120:123]
	v_mfma_f32_16x16x32_bf16 v[108:111], v[132:135], v[196:199], v[108:111]
	v_mfma_f32_16x16x32_bf16 v[104:107], v[140:143], v[196:199], v[104:107]
	v_mfma_f32_16x16x32_bf16 v[92:95], v[132:135], v[204:207], v[92:95]
	v_mfma_f32_16x16x32_bf16 v[88:91], v[140:143], v[204:207], v[88:91]
	v_mfma_f32_16x16x32_bf16 v[76:79], v[132:135], v[214:217], v[76:79]
	v_mfma_f32_16x16x32_bf16 v[72:75], v[140:143], v[214:217], v[72:75]
	v_mfma_f32_16x16x32_bf16 v[116:119], v[144:147], v[176:179], v[116:119]
	v_mfma_f32_16x16x32_bf16 v[112:115], v[152:155], v[176:179], v[112:115]
	v_mfma_f32_16x16x32_bf16 v[100:103], v[144:147], v[184:187], v[100:103]
	v_mfma_f32_16x16x32_bf16 v[96:99], v[152:155], v[184:187], v[96:99]
	v_mfma_f32_16x16x32_bf16 v[84:87], v[144:147], v[200:203], v[84:87]
	v_mfma_f32_16x16x32_bf16 v[80:83], v[152:155], v[200:203], v[80:83]
	v_mfma_f32_16x16x32_bf16 v[68:71], v[144:147], v[208:211], v[68:71]
	v_mfma_f32_16x16x32_bf16 v[64:67], v[152:155], v[208:211], v[64:67]
	v_mfma_f32_16x16x32_bf16 v[116:119], v[148:151], v[180:183], v[116:119]
	v_mfma_f32_16x16x32_bf16 v[112:115], v[172:175], v[180:183], v[112:115]
	v_mfma_f32_16x16x32_bf16 v[100:103], v[148:151], v[196:199], v[100:103]
	v_mfma_f32_16x16x32_bf16 v[96:99], v[172:175], v[196:199], v[96:99]
	v_mfma_f32_16x16x32_bf16 v[84:87], v[148:151], v[204:207], v[84:87]
	v_mfma_f32_16x16x32_bf16 v[80:83], v[172:175], v[204:207], v[80:83]
	v_mfma_f32_16x16x32_bf16 v[68:71], v[148:151], v[214:217], v[68:71]
	v_mfma_f32_16x16x32_bf16 v[64:67], v[172:175], v[214:217], v[64:67]
	s_barrier
; #define PG8_STAGE(bufoff, gbase, voff) do { _Pragma("unroll") for (int _i = 0; _i < 2; ++_i) \
;     __builtin_amdgcn_global_load_lds((const unsigned*)((const char*)(gbase) + (voff)[_i]), (PG8_LAS unsigned*)(lds + (bufoff) + ldsw + _i * 8192), 16, 0, 0); } while (0)
; #define PG8_LDA(dst, b, h) do { _Pragma("unroll") for (int m = 0; m < 4; ++m) _Pragma("unroll") for (int k = 0; k < 2; ++k) dst[m][k] = *(const PG8_LAS bf16x8*)(lds + PG8_SA(b, h) + aoff + m * 2048 + k * 1024); } while (0)
; #define PG8_MMA(ai, bj, At, Bt) do { __builtin_amdgcn_s_setprio(1); _Pragma("unroll") for (int m = 0; m < 4; ++m) _Pragma("unroll") for (int n = 0; n < 2; ++n) _Pragma("unroll") for (int k = 0; k < 2; ++k) \
;     acc[ai][bj][m][n] = __builtin_amdgcn_mfma_f32_16x16x32_bf16(Bt[n][k], At[m][k], acc[ai][bj][m][n], 0, 0, 0); __builtin_amdgcn_s_setprio(0); } while (0)
; #define PG8_WAIT_V(n) asm volatile("s_waitcnt vmcnt(" #n ")" ::: "memory")
; #define PG8_WAIT_L(n) asm volatile("s_waitcnt lgkmcnt(" #n ")" ::: "memory")
; #define PG8_BAR __builtin_amdgcn_s_barrier()
; #define PG8_SCHED __builtin_amdgcn_sched_barrier(0)
; template <class Epi, class Sched>
; DI void gemm_phase(PG8_LAS unsigned char* lds, const Gemm g, const Sched& S, const Epi& E) {
;     ...
;       PG8_LDA(At, 1, 1); PG8_STAGE(PG8_SB(1, 0), b3, voffB); PG8_STAGE(PG8_SB(1, 1), b3 + hstepB, voffB); PG8_STAGE(PG8_SA(1, 0), a3, voffA);
;       PG8_WAIT_V(8); PG8_WAIT_L(0); PG8_BAR; PG8_MMA(1, 0, At, B0); PG8_MMA(1, 1, At, B1); PG8_BAR; PG8_SCHED;
;     }
;     if (wr == 0) PG8_BAR;
	s_mov_b32 m0, vcc_lo
	v_lshl_add_u64 v[188:189], v[188:189], 0, s[28:29]
	ds_read_b128 v[176:179], v191 offset:49152
	ds_read_b128 v[180:183], v191 offset:50176
	ds_read_b128 v[184:187], v191 offset:51200
	ds_read_b128 v[196:199], v191 offset:52224
	ds_read_b128 v[200:203], v191 offset:53248
	ds_read_b128 v[204:207], v191 offset:54272
	ds_read_b128 v[208:211], v191 offset:55296
	ds_read_b128 v[214:217], v191 offset:56320
	global_load_lds_dwordx4 v[188:189], off
	v_lshl_add_u64 v[188:189], v[218:219], 0, s[28:29]
	s_mov_b32 m0, s33
	s_nop 0
	global_load_lds_dwordx4 v[188:189], off
	v_lshl_add_u64 v[188:189], s[64:65], 0, v[158:159]
	s_mov_b32 m0, vcc_hi
	s_nop 0
	global_load_lds_dwordx4 v[188:189], off
	v_lshl_add_u64 v[188:189], s[64:65], 0, v[162:163]
	s_mov_b32 m0, s17
	s_nop 0
	global_load_lds_dwordx4 v[188:189], off
	v_lshl_add_u64 v[188:189], v[220:221], 0, s[28:29]
	s_mov_b32 m0, s91
	s_nop 0
	global_load_lds_dwordx4 v[188:189], off
	v_lshl_add_u64 v[188:189], v[222:223], 0, s[28:29]
	s_mov_b32 m0, s92
	s_nop 0
	global_load_lds_dwordx4 v[188:189], off
	s_waitcnt vmcnt(8)
	s_waitcnt lgkmcnt(0)
	s_barrier
	s_waitcnt lgkmcnt(0)
	v_mfma_f32_16x16x32_bf16 v[60:63], v[128:131], v[176:179], v[60:63]
	v_mfma_f32_16x16x32_bf16 v[56:59], v[136:139], v[176:179], v[56:59]
	v_mfma_f32_16x16x32_bf16 v[44:47], v[128:131], v[184:187], v[44:47]
	v_mfma_f32_16x16x32_bf16 v[40:43], v[136:139], v[184:187], v[40:43]
	v_mfma_f32_16x16x32_bf16 v[28:31], v[128:131], v[200:203], v[28:31]
	v_mfma_f32_16x16x32_bf16 v[24:27], v[136:139], v[200:203], v[24:27]
	v_mfma_f32_16x16x32_bf16 v[12:15], v[128:131], v[208:211], v[12:15]
	v_mfma_f32_16x16x32_bf16 v[8:11], v[136:139], v[208:211], v[8:11]
	v_mfma_f32_16x16x32_bf16 v[60:63], v[132:135], v[180:183], v[60:63]
	v_mfma_f32_16x16x32_bf16 v[56:59], v[140:143], v[180:183], v[56:59]
	v_mfma_f32_16x16x32_bf16 v[44:47], v[132:135], v[196:199], v[44:47]
	v_mfma_f32_16x16x32_bf16 v[40:43], v[140:143], v[196:199], v[40:43]
	v_mfma_f32_16x16x32_bf16 v[28:31], v[132:135], v[204:207], v[28:31]
	v_mfma_f32_16x16x32_bf16 v[24:27], v[140:143], v[204:207], v[24:27]
	v_mfma_f32_16x16x32_bf16 v[12:15], v[132:135], v[214:217], v[12:15]
	v_mfma_f32_16x16x32_bf16 v[8:11], v[140:143], v[214:217], v[8:11]
	v_mfma_f32_16x16x32_bf16 v[52:55], v[144:147], v[176:179], v[52:55]
	v_mfma_f32_16x16x32_bf16 v[48:51], v[152:155], v[176:179], v[48:51]
	v_mfma_f32_16x16x32_bf16 v[36:39], v[144:147], v[184:187], v[36:39]
	v_mfma_f32_16x16x32_bf16 v[32:35], v[152:155], v[184:187], v[32:35]
	v_mfma_f32_16x16x32_bf16 v[20:23], v[144:147], v[200:203], v[20:23]
	v_mfma_f32_16x16x32_bf16 v[16:19], v[152:155], v[200:203], v[16:19]
	v_mfma_f32_16x16x32_bf16 v[4:7], v[144:147], v[208:211], v[4:7]
	v_mfma_f32_16x16x32_bf16 v[0:3], v[152:155], v[208:211], v[0:3]
	v_mfma_f32_16x16x32_bf16 v[52:55], v[148:151], v[180:183], v[52:55]
	v_mfma_f32_16x16x32_bf16 v[48:51], v[172:175], v[180:183], v[48:51]
	v_mfma_f32_16x16x32_bf16 v[36:39], v[148:151], v[196:199], v[36:39]
	v_mfma_f32_16x16x32_bf16 v[32:35], v[172:175], v[196:199], v[32:35]
	v_mfma_f32_16x16x32_bf16 v[20:23], v[148:151], v[204:207], v[20:23]
	v_mfma_f32_16x16x32_bf16 v[16:19], v[172:175], v[204:207], v[16:19]
	v_mfma_f32_16x16x32_bf16 v[4:7], v[148:151], v[214:217], v[4:7]
	v_mfma_f32_16x16x32_bf16 v[0:3], v[172:175], v[214:217], v[0:3]
	s_barrier
	s_andn2_b64 vcc, exec, s[44:45]
	s_mov_b64 s[64:65], -1
	s_mov_b64 s[44:45], 0
	s_mov_b64 s[70:71], 0x100
	s_cbranch_vccz .LBB0_984
	s_and_b64 vcc, exec, s[30:31]
	s_cbranch_vccz .LBB0_987
	s_barrier

; #define PG8_STAGE(bufoff, gbase, voff) do { _Pragma("unroll") for (int _i = 0; _i < 2; ++_i) \
;     __builtin_amdgcn_global_load_lds((const unsigned*)((const char*)(gbase) + (voff)[_i]), (PG8_LAS unsigned*)(lds + (bufoff) + ldsw + _i * 8192), 16, 0, 0); } while (0)
; #define PG8_LDA(dst, b, h) do { _Pragma("unroll") for (int m = 0; m < 4; ++m) _Pragma("unroll") for (int k = 0; k < 2; ++k) dst[m][k] = *(const PG8_LAS bf16x8*)(lds + PG8_SA(b, h) + aoff + m * 2048 + k * 1024); } while (0)
; #define PG8_LDB(dst, b, h) do { _Pragma("unroll") for (int n = 0; n < 2; ++n) _Pragma("unroll") for (int k = 0; k < 2; ++k) dst[n][k] = *(const PG8_LAS bf16x8*)(lds + PG8_SB(b, h) + boff + n * 2048 + k * 1024); } while (0)
; #define PG8_MMA(ai, bj, At, Bt) do { __builtin_amdgcn_s_setprio(1); _Pragma("unroll") for (int m = 0; m < 4; ++m) _Pragma("unroll") for (int n = 0; n < 2; ++n) _Pragma("unroll") for (int k = 0; k < 2; ++k) \
;     acc[ai][bj][m][n] = __builtin_amdgcn_mfma_f32_16x16x32_bf16(Bt[n][k], At[m][k], acc[ai][bj][m][n], 0, 0, 0); __builtin_amdgcn_s_setprio(0); } while (0)
; #define PG8_WAIT_V(n) asm volatile("s_waitcnt vmcnt(" #n ")" ::: "memory")
; #define PG8_WAIT_L(n) asm volatile("s_waitcnt lgkmcnt(" #n ")" ::: "memory")
; template <class Epi, class Sched>
; DI void gemm_phase(PG8_LAS unsigned char* lds, const Gemm g, const Sched& S, const Epi& E) {
;     ...
;     const char* nA = has_next ? (const char*)g.A + (size_t)nxt.pm * tstepA : cA; const char* nB = has_next ? (const char*)g.Bt + (size_t)nxt.pn * tstepB : cB;
; #pragma unroll 1
;     for (int t = 0; t < nt; t += 2) {
;       const bool last = (t == nt - 2);
;       const char* a1 = cA + (size_t)(t + 1) * kstep;
;       const char* a2 = last ? nA : cA + (size_t)(t + 2) * kstep; const char* b2 = last ? nB : cB + (size_t)(t + 2) * kstep;
;       const char* a3 = a2 + kstep; const char* b3 = b2 + kstep;
;       PG8_LDB(B0, 0, 0); PG8_LDB(B1, 0, 1); PG8_SCHED; PG8_LDA(At, 0, 0); PG8_STAGE(PG8_SA(1, 1), a1 + hstepA, voffA);
;       PG8_WAIT_V(8); PG8_WAIT_L(0); PG8_BAR; PG8_MMA(0, 0, At, B0); PG8_MMA(0, 1, At, B1); PG8_BAR; PG8_SCHED;
;       PG8_LDA(At, 0, 1); PG8_STAGE(PG8_SB(0, 0), b2, voffB); PG8_STAGE(PG8_SB(0, 1), b2 + hstepB, voffB); PG8_STAGE(PG8_SA(0, 0), a2, voffA);
;       PG8_WAIT_V(8); PG8_WAIT_L(0); PG8_BAR; PG8_MMA(1, 0, At, B0); PG8_MMA(1, 1, At, B1); PG8_BAR; PG8_SCHED;
.LBB0_1300:
	ds_read_b128 v[128:131], v156
	ds_read_b128 v[132:135], v156 offset:1024
	ds_read_b128 v[150:153], v156 offset:2048
	ds_read_b128 v[162:165], v156 offset:3072
	ds_read_b128 v[166:169], v157
	ds_read_b128 v[170:173], v157 offset:1024
	ds_read_b128 v[174:177], v157 offset:2048
	ds_read_b128 v[178:181], v157 offset:3072
	s_add_u32 s17, s62, 0xfffc0080
	s_addc_u32 s33, s63, -1
	s_cmp_eq_u32 s75, 12
	s_cselect_b32 s67, s39, s33
	s_cselect_b32 s66, s59, s17
	s_cselect_b32 s65, s37, s74
	s_cselect_b32 s64, s61, s73
	v_lshl_add_u64 v[210:211], s[62:63], 0, v[146:147]
	s_add_i32 m0, s53, 0xc000
	ds_read_b128 v[182:185], v158
	ds_read_b128 v[186:189], v158 offset:1024
	ds_read_b128 v[190:193], v158 offset:2048
	ds_read_b128 v[194:197], v158 offset:3072
	ds_read_b128 v[198:201], v158 offset:4096
	ds_read_b128 v[202:205], v158 offset:5120
	ds_read_b128 v[206:209], v158 offset:6144
	ds_read_b128 v[214:217], v158 offset:7168
	global_load_lds_dwordx4 v[210:211], off
	v_lshl_add_u64 v[210:211], s[62:63], 0, v[148:149]
	s_add_i32 m0, s53, 0xe000
	s_nop 0
	global_load_lds_dwordx4 v[210:211], off
	s_waitcnt vmcnt(8)
	s_waitcnt lgkmcnt(0)
	s_barrier
	s_waitcnt lgkmcnt(0)
	v_mfma_f32_16x16x32_bf16 v[124:127], v[128:131], v[182:185], v[124:127]
	v_mfma_f32_16x16x32_bf16 v[120:123], v[150:153], v[182:185], v[120:123]
	v_mfma_f32_16x16x32_bf16 v[108:111], v[128:131], v[190:193], v[108:111]
	v_mfma_f32_16x16x32_bf16 v[104:107], v[150:153], v[190:193], v[104:107]
	v_mfma_f32_16x16x32_bf16 v[92:95], v[128:131], v[198:201], v[92:95]
	v_mfma_f32_16x16x32_bf16 v[88:91], v[150:153], v[198:201], v[88:91]
	v_mfma_f32_16x16x32_bf16 v[76:79], v[128:131], v[206:209], v[76:79]
	v_mfma_f32_16x16x32_bf16 v[72:75], v[150:153], v[206:209], v[72:75]
	v_mfma_f32_16x16x32_bf16 v[124:127], v[132:135], v[186:189], v[124:127]
	v_mfma_f32_16x16x32_bf16 v[120:123], v[162:165], v[186:189], v[120:123]
	v_mfma_f32_16x16x32_bf16 v[108:111], v[132:135], v[194:197], v[108:111]
	v_mfma_f32_16x16x32_bf16 v[104:107], v[162:165], v[194:197], v[104:107]
	v_mfma_f32_16x16x32_bf16 v[92:95], v[132:135], v[202:205], v[92:95]
	v_mfma_f32_16x16x32_bf16 v[88:91], v[162:165], v[202:205], v[88:91]
	v_mfma_f32_16x16x32_bf16 v[76:79], v[132:135], v[214:217], v[76:79]
	v_mfma_f32_16x16x32_bf16 v[72:75], v[162:165], v[214:217], v[72:75]
	v_mfma_f32_16x16x32_bf16 v[116:119], v[166:169], v[182:185], v[116:119]
	v_mfma_f32_16x16x32_bf16 v[112:115], v[174:177], v[182:185], v[112:115]
	v_mfma_f32_16x16x32_bf16 v[100:103], v[166:169], v[190:193], v[100:103]
	v_mfma_f32_16x16x32_bf16 v[96:99], v[174:177], v[190:193], v[96:99]
	v_mfma_f32_16x16x32_bf16 v[84:87], v[166:169], v[198:201], v[84:87]
	v_mfma_f32_16x16x32_bf16 v[80:83], v[174:177], v[198:201], v[80:83]
	v_mfma_f32_16x16x32_bf16 v[68:71], v[166:169], v[206:209], v[68:71]
	v_mfma_f32_16x16x32_bf16 v[64:67], v[174:177], v[206:209], v[64:67]
	v_mfma_f32_16x16x32_bf16 v[116:119], v[170:173], v[186:189], v[116:119]
	v_mfma_f32_16x16x32_bf16 v[112:115], v[178:181], v[186:189], v[112:115]
	v_mfma_f32_16x16x32_bf16 v[100:103], v[170:173], v[194:197], v[100:103]
	v_mfma_f32_16x16x32_bf16 v[96:99], v[178:181], v[194:197], v[96:99]
	v_mfma_f32_16x16x32_bf16 v[84:87], v[170:173], v[202:205], v[84:87]
	v_mfma_f32_16x16x32_bf16 v[80:83], v[178:181], v[202:205], v[80:83]
	v_mfma_f32_16x16x32_bf16 v[68:71], v[170:173], v[214:217], v[68:71]
	v_mfma_f32_16x16x32_bf16 v[64:67], v[178:181], v[214:217], v[64:67]
	s_barrier
	s_add_i32 s17, s69, s16
	v_lshl_add_u64 v[210:211], s[64:65], 0, v[138:139]
	s_mov_b32 m0, s17
	ds_read_b128 v[182:185], v158 offset:16384
	ds_read_b128 v[186:189], v158 offset:17408
	ds_read_b128 v[190:193], v158 offset:18432
	ds_read_b128 v[194:197], v158 offset:19456
	ds_read_b128 v[198:201], v158 offset:20480
	ds_read_b128 v[202:205], v158 offset:21504
	ds_read_b128 v[206:209], v158 offset:22528
	ds_read_b128 v[214:217], v158 offset:23552
	global_load_lds_dwordx4 v[210:211], off
	s_add_i32 m0, s17, 0x2000
	s_add_u32 s56, s64, 0x40000
	v_lshl_add_u64 v[218:219], s[64:65], 0, v[142:143]
	s_addc_u32 s57, s65, 0
	s_add_i32 s17, s70, s16
	global_load_lds_dwordx4 v[218:219], off
	v_lshl_add_u64 v[220:221], s[56:57], 0, v[138:139]
	s_mov_b32 m0, s17
	v_lshl_add_u64 v[222:223], s[66:67], 0, v[140:141]
	global_load_lds_dwordx4 v[220:221], off
	v_lshl_add_u64 v[220:221], s[56:57], 0, v[142:143]
	s_add_i32 m0, s17, 0x2000
	s_nop 0
	global_load_lds_dwordx4 v[220:221], off
	v_lshl_add_u64 v[220:221], s[66:67], 0, v[136:137]
	s_mov_b32 m0, s53
	s_nop 0
	global_load_lds_dwordx4 v[220:221], off
	s_mov_b32 m0, s18
	s_nop 0
	global_load_lds_dwordx4 v[222:223], off
	s_waitcnt vmcnt(8)
	s_waitcnt lgkmcnt(0)
	s_barrier
; #define PG8_STAGE(bufoff, gbase, voff) do { _Pragma("unroll") for (int _i = 0; _i < 2; ++_i) \
;     __builtin_amdgcn_global_load_lds((const unsigned*)((const char*)(gbase) + (voff)[_i]), (PG8_LAS unsigned*)(lds + (bufoff) + ldsw + _i * 8192), 16, 0, 0); } while (0)
; #define PG8_LDA(dst, b, h) do { _Pragma("unroll") for (int m = 0; m < 4; ++m) _Pragma("unroll") for (int k = 0; k < 2; ++k) dst[m][k] = *(const PG8_LAS bf16x8*)(lds + PG8_SA(b, h) + aoff + m * 2048 + k * 1024); } while (0)
; #define PG8_LDB(dst, b, h) do { _Pragma("unroll") for (int n = 0; n < 2; ++n) _Pragma("unroll") for (int k = 0; k < 2; ++k) dst[n][k] = *(const PG8_LAS bf16x8*)(lds + PG8_SB(b, h) + boff + n * 2048 + k * 1024); } while (0)
; #define PG8_MMA(ai, bj, At, Bt) do { __builtin_amdgcn_s_setprio(1); _Pragma("unroll") for (int m = 0; m < 4; ++m) _Pragma("unroll") for (int n = 0; n < 2; ++n) _Pragma("unroll") for (int k = 0; k < 2; ++k) \
;     acc[ai][bj][m][n] = __builtin_amdgcn_mfma_f32_16x16x32_bf16(Bt[n][k], At[m][k], acc[ai][bj][m][n], 0, 0, 0); __builtin_amdgcn_s_setprio(0); } while (0)
; #define PG8_WAIT_V(n) asm volatile("s_waitcnt vmcnt(" #n ")" ::: "memory")
; #define PG8_WAIT_L(n) asm volatile("s_waitcnt lgkmcnt(" #n ")" ::: "memory")
; #define PG8_BAR __builtin_amdgcn_s_barrier()
; #define PG8_SCHED __builtin_amdgcn_sched_barrier(0)
; template <class Epi, class Sched>
; DI void gemm_phase(PG8_LAS unsigned char* lds, const Gemm g, const Sched& S, const Epi& E) {
;     ...
;       PG8_WAIT_V(8); PG8_WAIT_L(0); PG8_BAR; PG8_MMA(1, 0, At, B0); PG8_MMA(1, 1, At, B1); PG8_BAR; PG8_SCHED;
;       PG8_LDB(B0, 1, 0); PG8_LDB(B1, 1, 1); PG8_SCHED; PG8_LDA(At, 1, 0); PG8_STAGE(PG8_SA(0, 1), a2 + hstepA, voffA);
;       PG8_WAIT_V(8); PG8_WAIT_L(0); PG8_BAR; PG8_MMA(0, 0, At, B0); PG8_MMA(0, 1, At, B1); PG8_BAR; PG8_SCHED;
	s_waitcnt lgkmcnt(0)
	v_mfma_f32_16x16x32_bf16 v[60:63], v[128:131], v[182:185], v[60:63]
	v_mfma_f32_16x16x32_bf16 v[56:59], v[150:153], v[182:185], v[56:59]
	v_mfma_f32_16x16x32_bf16 v[44:47], v[128:131], v[190:193], v[44:47]
	v_mfma_f32_16x16x32_bf16 v[40:43], v[150:153], v[190:193], v[40:43]
	v_mfma_f32_16x16x32_bf16 v[28:31], v[128:131], v[198:201], v[28:31]
	v_mfma_f32_16x16x32_bf16 v[24:27], v[150:153], v[198:201], v[24:27]
	v_mfma_f32_16x16x32_bf16 v[12:15], v[128:131], v[206:209], v[12:15]
	v_mfma_f32_16x16x32_bf16 v[8:11], v[150:153], v[206:209], v[8:11]
	v_mfma_f32_16x16x32_bf16 v[60:63], v[132:135], v[186:189], v[60:63]
	v_mfma_f32_16x16x32_bf16 v[56:59], v[162:165], v[186:189], v[56:59]
	v_mfma_f32_16x16x32_bf16 v[44:47], v[132:135], v[194:197], v[44:47]
	v_mfma_f32_16x16x32_bf16 v[40:43], v[162:165], v[194:197], v[40:43]
	v_mfma_f32_16x16x32_bf16 v[28:31], v[132:135], v[202:205], v[28:31]
	v_mfma_f32_16x16x32_bf16 v[24:27], v[162:165], v[202:205], v[24:27]
	v_mfma_f32_16x16x32_bf16 v[12:15], v[132:135], v[214:217], v[12:15]
	v_mfma_f32_16x16x32_bf16 v[8:11], v[162:165], v[214:217], v[8:11]
	v_mfma_f32_16x16x32_bf16 v[52:55], v[166:169], v[182:185], v[52:55]
	v_mfma_f32_16x16x32_bf16 v[48:51], v[174:177], v[182:185], v[48:51]
	v_mfma_f32_16x16x32_bf16 v[36:39], v[166:169], v[190:193], v[36:39]
	v_mfma_f32_16x16x32_bf16 v[32:35], v[174:177], v[190:193], v[32:35]
	v_mfma_f32_16x16x32_bf16 v[20:23], v[166:169], v[198:201], v[20:23]
	v_mfma_f32_16x16x32_bf16 v[16:19], v[174:177], v[198:201], v[16:19]
	v_mfma_f32_16x16x32_bf16 v[4:7], v[166:169], v[206:209], v[4:7]
	v_mfma_f32_16x16x32_bf16 v[0:3], v[174:177], v[206:209], v[0:3]
	v_mfma_f32_16x16x32_bf16 v[52:55], v[170:173], v[186:189], v[52:55]
	v_mfma_f32_16x16x32_bf16 v[48:51], v[178:181], v[186:189], v[48:51]
	v_mfma_f32_16x16x32_bf16 v[36:39], v[170:173], v[194:197], v[36:39]
	v_mfma_f32_16x16x32_bf16 v[32:35], v[178:181], v[194:197], v[32:35]
	v_mfma_f32_16x16x32_bf16 v[20:23], v[170:173], v[202:205], v[20:23]
	v_mfma_f32_16x16x32_bf16 v[16:19], v[178:181], v[202:205], v[16:19]
	v_mfma_f32_16x16x32_bf16 v[4:7], v[170:173], v[214:217], v[4:7]
	v_mfma_f32_16x16x32_bf16 v[0:3], v[178:181], v[214:217], v[0:3]
	s_barrier
	s_mov_b32 s17, 0x18000
	s_addk_i32 s17, 0x110
	v_add_u32_e32 v161, s17, v155
	ds_read_b128 v[128:131], v161
	ds_read_b128 v[132:135], v161 offset:1024
	ds_read_b128 v[150:153], v161 offset:2048
	ds_read_b128 v[162:165], v161 offset:3072
	ds_read_b128 v[166:169], v160
	ds_read_b128 v[170:173], v160 offset:1024
	ds_read_b128 v[174:177], v160 offset:2048
	ds_read_b128 v[178:181], v160 offset:3072
	s_add_u32 s56, s66, 0x40000
	s_addc_u32 s57, s67, 0
	s_mov_b32 m0, s19
	v_lshl_add_u64 v[224:225], s[56:57], 0, v[136:137]
	ds_read_b128 v[182:185], v158 offset:32768
	ds_read_b128 v[186:189], v158 offset:33792
	ds_read_b128 v[190:193], v158 offset:34816
	ds_read_b128 v[194:197], v158 offset:35840
	ds_read_b128 v[198:201], v158 offset:36864
	ds_read_b128 v[202:205], v158 offset:37888
	ds_read_b128 v[206:209], v158 offset:38912
	ds_read_b128 v[214:217], v158 offset:39936
	global_load_lds_dwordx4 v[224:225], off
	v_lshl_add_u64 v[224:225], s[56:57], 0, v[140:141]
	s_mov_b32 m0, s54
	s_nop 0
	global_load_lds_dwordx4 v[224:225], off
	s_waitcnt vmcnt(8)
	s_waitcnt lgkmcnt(0)
	s_barrier
	s_waitcnt lgkmcnt(0)
	v_mfma_f32_16x16x32_bf16 v[124:127], v[128:131], v[182:185], v[124:127]
	v_mfma_f32_16x16x32_bf16 v[120:123], v[150:153], v[182:185], v[120:123]
	v_mfma_f32_16x16x32_bf16 v[108:111], v[128:131], v[190:193], v[108:111]
	v_mfma_f32_16x16x32_bf16 v[104:107], v[150:153], v[190:193], v[104:107]
	v_mfma_f32_16x16x32_bf16 v[92:95], v[128:131], v[198:201], v[92:95]
	v_mfma_f32_16x16x32_bf16 v[88:91], v[150:153], v[198:201], v[88:91]
	v_mfma_f32_16x16x32_bf16 v[76:79], v[128:131], v[206:209], v[76:79]
	v_mfma_f32_16x16x32_bf16 v[72:75], v[150:153], v[206:209], v[72:75]
	v_mfma_f32_16x16x32_bf16 v[124:127], v[132:135], v[186:189], v[124:127]
	v_mfma_f32_16x16x32_bf16 v[120:123], v[162:165], v[186:189], v[120:123]
	v_mfma_f32_16x16x32_bf16 v[108:111], v[132:135], v[194:197], v[108:111]
	v_mfma_f32_16x16x32_bf16 v[104:107], v[162:165], v[194:197], v[104:107]
	v_mfma_f32_16x16x32_bf16 v[92:95], v[132:135], v[202:205], v[92:95]
	v_mfma_f32_16x16x32_bf16 v[88:91], v[162:165], v[202:205], v[88:91]
	v_mfma_f32_16x16x32_bf16 v[76:79], v[132:135], v[214:217], v[76:79]
	v_mfma_f32_16x16x32_bf16 v[72:75], v[162:165], v[214:217], v[72:75]
	v_mfma_f32_16x16x32_bf16 v[116:119], v[166:169], v[182:185], v[116:119]
	v_mfma_f32_16x16x32_bf16 v[112:115], v[174:177], v[182:185], v[112:115]
	v_mfma_f32_16x16x32_bf16 v[100:103], v[166:169], v[190:193], v[100:103]
	v_mfma_f32_16x16x32_bf16 v[96:99], v[174:177], v[190:193], v[96:99]
	v_mfma_f32_16x16x32_bf16 v[84:87], v[166:169], v[198:201], v[84:87]
	v_mfma_f32_16x16x32_bf16 v[80:83], v[174:177], v[198:201], v[80:83]
	v_mfma_f32_16x16x32_bf16 v[68:71], v[166:169], v[206:209], v[68:71]
	v_mfma_f32_16x16x32_bf16 v[64:67], v[174:177], v[206:209], v[64:67]
	v_mfma_f32_16x16x32_bf16 v[116:119], v[170:173], v[186:189], v[116:119]
	v_mfma_f32_16x16x32_bf16 v[112:115], v[178:181], v[186:189], v[112:115]
	v_mfma_f32_16x16x32_bf16 v[100:103], v[170:173], v[194:197], v[100:103]
	v_mfma_f32_16x16x32_bf16 v[96:99], v[178:181], v[194:197], v[96:99]
	v_mfma_f32_16x16x32_bf16 v[84:87], v[170:173], v[202:205], v[84:87]
	v_mfma_f32_16x16x32_bf16 v[80:83], v[178:181], v[202:205], v[80:83]
	v_mfma_f32_16x16x32_bf16 v[68:71], v[170:173], v[214:217], v[68:71]
	v_mfma_f32_16x16x32_bf16 v[64:67], v[178:181], v[214:217], v[64:67]
	s_barrier
; #define PG8_STAGE(bufoff, gbase, voff) do { _Pragma("unroll") for (int _i = 0; _i < 2; ++_i) \
;     __builtin_amdgcn_global_load_lds((const unsigned*)((const char*)(gbase) + (voff)[_i]), (PG8_LAS unsigned*)(lds + (bufoff) + ldsw + _i * 8192), 16, 0, 0); } while (0)
; #define PG8_LDA(dst, b, h) do { _Pragma("unroll") for (int m = 0; m < 4; ++m) _Pragma("unroll") for (int k = 0; k < 2; ++k) dst[m][k] = *(const PG8_LAS bf16x8*)(lds + PG8_SA(b, h) + aoff + m * 2048 + k * 1024); } while (0)
; #define PG8_MMA(ai, bj, At, Bt) do { __builtin_amdgcn_s_setprio(1); _Pragma("unroll") for (int m = 0; m < 4; ++m) _Pragma("unroll") for (int n = 0; n < 2; ++n) _Pragma("unroll") for (int k = 0; k < 2; ++k) \
;     acc[ai][bj][m][n] = __builtin_amdgcn_mfma_f32_16x16x32_bf16(Bt[n][k], At[m][k], acc[ai][bj][m][n], 0, 0, 0); __builtin_amdgcn_s_setprio(0); } while (0)
; #define PG8_WAIT_V(n) asm volatile("s_waitcnt vmcnt(" #n ")" ::: "memory")
; #define PG8_WAIT_L(n) asm volatile("s_waitcnt lgkmcnt(" #n ")" ::: "memory")
; #define PG8_BAR __builtin_amdgcn_s_barrier()
; #define PG8_SCHED __builtin_amdgcn_sched_barrier(0)
;   DI void operator()(const f32x4 (&acc)[2][2][4][2], const Unit& u, int wr, int wc, int fr, int fq) const {
;     ...
;     RES_LD(0)
; template <class Epi, class Sched>
; DI void gemm_phase(PG8_LAS unsigned char* lds, const Gemm g, const Sched& S, const Epi& E) {
;     ...
;       PG8_LDA(At, 1, 1); PG8_STAGE(PG8_SB(1, 0), b3, voffB); PG8_STAGE(PG8_SB(1, 1), b3 + hstepB, voffB); PG8_STAGE(PG8_SA(1, 0), a3, voffA);
;       PG8_WAIT_V(8); PG8_WAIT_L(0); PG8_BAR; PG8_MMA(1, 0, At, B0); PG8_MMA(1, 1, At, B1); PG8_BAR; PG8_SCHED;
;     }
;     if (wr == 0) PG8_BAR;
;     E(acc, cur, wr, wc, fr, fq);
	s_add_i32 s17, s17, s16
	v_lshl_add_u64 v[210:211], v[210:211], 0, s[6:7]
	s_mov_b32 m0, s17
	ds_read_b128 v[182:185], v158 offset:49152
	ds_read_b128 v[186:189], v158 offset:50176
	ds_read_b128 v[190:193], v158 offset:51200
	ds_read_b128 v[194:197], v158 offset:52224
	ds_read_b128 v[198:201], v158 offset:53248
	ds_read_b128 v[202:205], v158 offset:54272
	ds_read_b128 v[206:209], v158 offset:55296
	ds_read_b128 v[214:217], v158 offset:56320
	global_load_lds_dwordx4 v[210:211], off
	s_add_i32 m0, s17, 0x2000
	s_add_u32 s56, s64, 0x40080
	v_lshl_add_u64 v[210:211], v[218:219], 0, s[6:7]
	s_addc_u32 s57, s65, 0
	s_add_i32 s17, s71, s16
	global_load_lds_dwordx4 v[210:211], off
	v_lshl_add_u64 v[210:211], s[56:57], 0, v[138:139]
	s_mov_b32 m0, s17
	s_nop 0
	global_load_lds_dwordx4 v[210:211], off
	v_lshl_add_u64 v[210:211], s[56:57], 0, v[142:143]
	s_add_i32 m0, s17, 0x2000
	s_nop 0
	global_load_lds_dwordx4 v[210:211], off
	v_lshl_add_u64 v[210:211], v[220:221], 0, s[6:7]
	s_mov_b32 m0, s5
	s_nop 0
	global_load_lds_dwordx4 v[210:211], off
	v_lshl_add_u64 v[210:211], v[222:223], 0, s[6:7]
	s_mov_b32 m0, s55
	s_nop 0
	global_load_lds_dwordx4 v[210:211], off
	s_waitcnt vmcnt(8)
	s_waitcnt lgkmcnt(0)
	s_barrier
	s_waitcnt lgkmcnt(0)
	v_mfma_f32_16x16x32_bf16 v[60:63], v[128:131], v[182:185], v[60:63]
	v_mfma_f32_16x16x32_bf16 v[56:59], v[150:153], v[182:185], v[56:59]
	v_mfma_f32_16x16x32_bf16 v[44:47], v[128:131], v[190:193], v[44:47]
	v_mfma_f32_16x16x32_bf16 v[40:43], v[150:153], v[190:193], v[40:43]
	v_mfma_f32_16x16x32_bf16 v[28:31], v[128:131], v[198:201], v[28:31]
	v_mfma_f32_16x16x32_bf16 v[24:27], v[150:153], v[198:201], v[24:27]
	v_mfma_f32_16x16x32_bf16 v[12:15], v[128:131], v[206:209], v[12:15]
	v_mfma_f32_16x16x32_bf16 v[8:11], v[150:153], v[206:209], v[8:11]
	v_mfma_f32_16x16x32_bf16 v[60:63], v[132:135], v[186:189], v[60:63]
	v_mfma_f32_16x16x32_bf16 v[56:59], v[162:165], v[186:189], v[56:59]
	v_mfma_f32_16x16x32_bf16 v[44:47], v[132:135], v[194:197], v[44:47]
	v_mfma_f32_16x16x32_bf16 v[40:43], v[162:165], v[194:197], v[40:43]
	v_mfma_f32_16x16x32_bf16 v[28:31], v[132:135], v[202:205], v[28:31]
	v_mfma_f32_16x16x32_bf16 v[24:27], v[162:165], v[202:205], v[24:27]
	v_mfma_f32_16x16x32_bf16 v[12:15], v[132:135], v[214:217], v[12:15]
	v_mfma_f32_16x16x32_bf16 v[8:11], v[162:165], v[214:217], v[8:11]
	v_mfma_f32_16x16x32_bf16 v[52:55], v[166:169], v[182:185], v[52:55]
	v_mfma_f32_16x16x32_bf16 v[48:51], v[174:177], v[182:185], v[48:51]
	v_mfma_f32_16x16x32_bf16 v[36:39], v[166:169], v[190:193], v[36:39]
	v_mfma_f32_16x16x32_bf16 v[32:35], v[174:177], v[190:193], v[32:35]
	v_mfma_f32_16x16x32_bf16 v[20:23], v[166:169], v[198:201], v[20:23]
	v_mfma_f32_16x16x32_bf16 v[16:19], v[174:177], v[198:201], v[16:19]
	v_mfma_f32_16x16x32_bf16 v[4:7], v[166:169], v[206:209], v[4:7]
	v_mfma_f32_16x16x32_bf16 v[0:3], v[174:177], v[206:209], v[0:3]
	v_mfma_f32_16x16x32_bf16 v[52:55], v[170:173], v[186:189], v[52:55]
	v_mfma_f32_16x16x32_bf16 v[48:51], v[178:181], v[186:189], v[48:51]
	v_mfma_f32_16x16x32_bf16 v[36:39], v[170:173], v[194:197], v[36:39]
	v_mfma_f32_16x16x32_bf16 v[32:35], v[178:181], v[194:197], v[32:35]
	v_mfma_f32_16x16x32_bf16 v[20:23], v[170:173], v[202:205], v[20:23]
	v_mfma_f32_16x16x32_bf16 v[16:19], v[178:181], v[202:205], v[16:19]
	v_mfma_f32_16x16x32_bf16 v[4:7], v[170:173], v[214:217], v[4:7]
	v_mfma_f32_16x16x32_bf16 v[0:3], v[178:181], v[214:217], v[0:3]
	s_barrier
	s_add_i32 s75, s75, 2
	s_add_u32 s62, s62, 0x100
	s_addc_u32 s63, s63, 0
	s_add_u32 s73, s73, 0x100
	s_addc_u32 s74, s74, 0
	s_cmp_gt_u32 s75, 13
	s_cbranch_scc0 .LBB0_1300
	v_lshl_add_u32 v152, s60, 8, v154
	v_ashrrev_i32_e32 v153, 31, v152
	s_lshl_b32 s56, s58, 8
	v_lshlrev_b64 v[128:129], 11, v[152:153]
	s_ashr_i32 s57, s56, 31
	v_lshl_add_u64 v[128:129], s[50:51], 0, v[128:129]
	v_lshl_add_u64 v[128:129], s[56:57], 1, v[128:129]
	v_lshl_add_u64 v[128:129], v[128:129], 0, s[10:11]
	v_lshl_add_u64 v[150:151], v[128:129], 0, v[144:145]
	s_mov_b32 s17, 0x8000
	v_add_co_u32_e32 v128, vcc, s17, v150
	global_load_dwordx4 v[164:167], v[150:151], off
	global_load_dwordx4 v[168:171], v[150:151], off offset:256
	v_addc_co_u32_e32 v129, vcc, 0, v151, vcc
	global_load_dwordx4 v[132:135], v[128:129], off
	s_nop 0
	global_load_dwordx4 v[128:131], v[128:129], off offset:256
	s_and_b64 vcc, exec, s[8:9]
	s_cbranch_vccz .LBB0_1303
	s_barrier

; #define PG8_STAGE(bufoff, gbase, voff) do { _Pragma("unroll") for (int _i = 0; _i < 2; ++_i) \
;     __builtin_amdgcn_global_load_lds((const unsigned*)((const char*)(gbase) + (voff)[_i]), (PG8_LAS unsigned*)(lds + (bufoff) + ldsw + _i * 8192), 16, 0, 0); } while (0)
; #define PG8_LDA(dst, b, h) do { _Pragma("unroll") for (int m = 0; m < 4; ++m) _Pragma("unroll") for (int k = 0; k < 2; ++k) dst[m][k] = *(const PG8_LAS bf16x8*)(lds + PG8_SA(b, h) + aoff + m * 2048 + k * 1024); } while (0)
; #define PG8_LDB(dst, b, h) do { _Pragma("unroll") for (int n = 0; n < 2; ++n) _Pragma("unroll") for (int k = 0; k < 2; ++k) dst[n][k] = *(const PG8_LAS bf16x8*)(lds + PG8_SB(b, h) + boff + n * 2048 + k * 1024); } while (0)
; #define PG8_MMA(ai, bj, At, Bt) do { __builtin_amdgcn_s_setprio(1); _Pragma("unroll") for (int m = 0; m < 4; ++m) _Pragma("unroll") for (int n = 0; n < 2; ++n) _Pragma("unroll") for (int k = 0; k < 2; ++k) \
;     acc[ai][bj][m][n] = __builtin_amdgcn_mfma_f32_16x16x32_bf16(Bt[n][k], At[m][k], acc[ai][bj][m][n], 0, 0, 0); __builtin_amdgcn_s_setprio(0); } while (0)
; #define PG8_WAIT_V(n) asm volatile("s_waitcnt vmcnt(" #n ")" ::: "memory")
; #define PG8_WAIT_L(n) asm volatile("s_waitcnt lgkmcnt(" #n ")" ::: "memory")
; template <class Epi, class Sched>
; DI void gemm_phase(PG8_LAS unsigned char* lds, const Gemm g, const Sched& S, const Epi& E) {
;     ...
;     const char* nA = has_next ? (const char*)g.A + (size_t)nxt.pm * tstepA : cA; const char* nB = has_next ? (const char*)g.Bt + (size_t)nxt.pn * tstepB : cB;
; #pragma unroll 1
;     for (int t = 0; t < nt; t += 2) {
;       const bool last = (t == nt - 2);
;       const char* a1 = cA + (size_t)(t + 1) * kstep;
;       const char* a2 = last ? nA : cA + (size_t)(t + 2) * kstep; const char* b2 = last ? nB : cB + (size_t)(t + 2) * kstep;
;       const char* a3 = a2 + kstep; const char* b3 = b2 + kstep;
;       PG8_LDB(B0, 0, 0); PG8_LDB(B1, 0, 1); PG8_SCHED; PG8_LDA(At, 0, 0); PG8_STAGE(PG8_SA(1, 1), a1 + hstepA, voffA);
;       PG8_WAIT_V(8); PG8_WAIT_L(0); PG8_BAR; PG8_MMA(0, 0, At, B0); PG8_MMA(0, 1, At, B1); PG8_BAR; PG8_SCHED;
;       PG8_LDA(At, 0, 1); PG8_STAGE(PG8_SB(0, 0), b2, voffB); PG8_STAGE(PG8_SB(0, 1), b2 + hstepB, voffB); PG8_STAGE(PG8_SA(0, 0), a2, voffA);
;       PG8_WAIT_V(8); PG8_WAIT_L(0); PG8_BAR; PG8_MMA(1, 0, At, B0); PG8_MMA(1, 1, At, B1); PG8_BAR; PG8_SCHED;
.LBB0_1384:
	ds_read_b128 v[144:147], v155
	ds_read_b128 v[156:159], v155 offset:1024
	ds_read_b128 v[174:177], v155 offset:2048
	ds_read_b128 v[178:181], v155 offset:3072
	ds_read_b128 v[182:185], v161
	ds_read_b128 v[186:189], v161 offset:1024
	ds_read_b128 v[190:193], v161 offset:2048
	ds_read_b128 v[194:197], v161 offset:3072
	s_add_u32 s30, s2, 0xfffc0080
	s_addc_u32 s31, s3, -1
	s_cmp_eq_u32 s55, 12
	s_cselect_b32 s35, s1, s31
	s_cselect_b32 s34, s23, s30
	s_cselect_b32 s31, s21, s54
	s_cselect_b32 s30, s49, s53
	v_lshl_add_u64 v[148:149], s[2:3], 0, v[140:141]
	s_add_i32 m0, s17, 0xc000
	ds_read_b128 v[198:201], v165
	ds_read_b128 v[202:205], v165 offset:1024
	ds_read_b128 v[206:209], v165 offset:2048
	ds_read_b128 v[214:217], v165 offset:3072
	ds_read_b128 v[218:221], v165 offset:4096
	ds_read_b128 v[222:225], v165 offset:5120
	ds_read_b128 v[226:229], v165 offset:6144
	ds_read_b128 v[230:233], v165 offset:7168
	global_load_lds_dwordx4 v[148:149], off
	v_lshl_add_u64 v[148:149], s[2:3], 0, v[142:143]
	s_add_i32 m0, s17, 0xe000
	s_nop 0
	global_load_lds_dwordx4 v[148:149], off
	s_waitcnt vmcnt(8)
	s_waitcnt lgkmcnt(0)
	s_barrier
	s_waitcnt lgkmcnt(0)
	v_mfma_f32_16x16x32_bf16 v[124:127], v[144:147], v[198:201], v[124:127]
	v_mfma_f32_16x16x32_bf16 v[120:123], v[174:177], v[198:201], v[120:123]
	v_mfma_f32_16x16x32_bf16 v[108:111], v[144:147], v[206:209], v[108:111]
	v_mfma_f32_16x16x32_bf16 v[104:107], v[174:177], v[206:209], v[104:107]
	v_mfma_f32_16x16x32_bf16 v[92:95], v[144:147], v[218:221], v[92:95]
	v_mfma_f32_16x16x32_bf16 v[88:91], v[174:177], v[218:221], v[88:91]
	v_mfma_f32_16x16x32_bf16 v[76:79], v[144:147], v[226:229], v[76:79]
	v_mfma_f32_16x16x32_bf16 v[72:75], v[174:177], v[226:229], v[72:75]
	v_mfma_f32_16x16x32_bf16 v[124:127], v[156:159], v[202:205], v[124:127]
	v_mfma_f32_16x16x32_bf16 v[120:123], v[178:181], v[202:205], v[120:123]
	v_mfma_f32_16x16x32_bf16 v[108:111], v[156:159], v[214:217], v[108:111]
	v_mfma_f32_16x16x32_bf16 v[104:107], v[178:181], v[214:217], v[104:107]
	v_mfma_f32_16x16x32_bf16 v[92:95], v[156:159], v[222:225], v[92:95]
	v_mfma_f32_16x16x32_bf16 v[88:91], v[178:181], v[222:225], v[88:91]
	v_mfma_f32_16x16x32_bf16 v[76:79], v[156:159], v[230:233], v[76:79]
	v_mfma_f32_16x16x32_bf16 v[72:75], v[178:181], v[230:233], v[72:75]
	v_mfma_f32_16x16x32_bf16 v[116:119], v[182:185], v[198:201], v[116:119]
	v_mfma_f32_16x16x32_bf16 v[112:115], v[190:193], v[198:201], v[112:115]
	v_mfma_f32_16x16x32_bf16 v[100:103], v[182:185], v[206:209], v[100:103]
	v_mfma_f32_16x16x32_bf16 v[96:99], v[190:193], v[206:209], v[96:99]
	v_mfma_f32_16x16x32_bf16 v[84:87], v[182:185], v[218:221], v[84:87]
	v_mfma_f32_16x16x32_bf16 v[80:83], v[190:193], v[218:221], v[80:83]
	v_mfma_f32_16x16x32_bf16 v[68:71], v[182:185], v[226:229], v[68:71]
	v_mfma_f32_16x16x32_bf16 v[64:67], v[190:193], v[226:229], v[64:67]
	v_mfma_f32_16x16x32_bf16 v[116:119], v[186:189], v[202:205], v[116:119]
	v_mfma_f32_16x16x32_bf16 v[112:115], v[194:197], v[202:205], v[112:115]
	v_mfma_f32_16x16x32_bf16 v[100:103], v[186:189], v[214:217], v[100:103]
	v_mfma_f32_16x16x32_bf16 v[96:99], v[194:197], v[214:217], v[96:99]
	v_mfma_f32_16x16x32_bf16 v[84:87], v[186:189], v[222:225], v[84:87]
	v_mfma_f32_16x16x32_bf16 v[80:83], v[194:197], v[222:225], v[80:83]
	v_mfma_f32_16x16x32_bf16 v[68:71], v[186:189], v[230:233], v[68:71]
	v_mfma_f32_16x16x32_bf16 v[64:67], v[194:197], v[230:233], v[64:67]
	s_barrier
	s_add_i32 s56, s37, s15
	v_lshl_add_u64 v[148:149], s[30:31], 0, v[132:133]
	s_mov_b32 m0, s56
	ds_read_b128 v[198:201], v165 offset:16384
	ds_read_b128 v[202:205], v165 offset:17408
	ds_read_b128 v[206:209], v165 offset:18432
	ds_read_b128 v[214:217], v165 offset:19456
	ds_read_b128 v[218:221], v165 offset:20480
	ds_read_b128 v[222:225], v165 offset:21504
	ds_read_b128 v[226:229], v165 offset:22528
	ds_read_b128 v[230:233], v165 offset:23552
	global_load_lds_dwordx4 v[148:149], off
	s_add_i32 m0, s56, 0x2000
	s_add_u32 s56, s30, 0x40000
	v_lshl_add_u64 v[152:153], s[30:31], 0, v[128:129]
	s_addc_u32 s57, s31, 0
	s_add_i32 s58, s38, s15
	global_load_lds_dwordx4 v[152:153], off
	v_lshl_add_u64 v[162:163], s[56:57], 0, v[132:133]
	s_mov_b32 m0, s58
	v_lshl_add_u64 v[166:167], s[34:35], 0, v[130:131]
	global_load_lds_dwordx4 v[162:163], off
	v_lshl_add_u64 v[162:163], s[56:57], 0, v[128:129]
	s_add_i32 m0, s58, 0x2000
	s_nop 0
	global_load_lds_dwordx4 v[162:163], off
	v_lshl_add_u64 v[162:163], s[34:35], 0, v[134:135]
	s_mov_b32 m0, s17
	s_nop 0
	global_load_lds_dwordx4 v[162:163], off
	s_mov_b32 m0, s4
	s_nop 0
	global_load_lds_dwordx4 v[166:167], off
	s_waitcnt vmcnt(8)
	s_waitcnt lgkmcnt(0)
	s_barrier
; #define PG8_STAGE(bufoff, gbase, voff) do { _Pragma("unroll") for (int _i = 0; _i < 2; ++_i) \
;     __builtin_amdgcn_global_load_lds((const unsigned*)((const char*)(gbase) + (voff)[_i]), (PG8_LAS unsigned*)(lds + (bufoff) + ldsw + _i * 8192), 16, 0, 0); } while (0)
; #define PG8_LDA(dst, b, h) do { _Pragma("unroll") for (int m = 0; m < 4; ++m) _Pragma("unroll") for (int k = 0; k < 2; ++k) dst[m][k] = *(const PG8_LAS bf16x8*)(lds + PG8_SA(b, h) + aoff + m * 2048 + k * 1024); } while (0)
; #define PG8_LDB(dst, b, h) do { _Pragma("unroll") for (int n = 0; n < 2; ++n) _Pragma("unroll") for (int k = 0; k < 2; ++k) dst[n][k] = *(const PG8_LAS bf16x8*)(lds + PG8_SB(b, h) + boff + n * 2048 + k * 1024); } while (0)
; #define PG8_MMA(ai, bj, At, Bt) do { __builtin_amdgcn_s_setprio(1); _Pragma("unroll") for (int m = 0; m < 4; ++m) _Pragma("unroll") for (int n = 0; n < 2; ++n) _Pragma("unroll") for (int k = 0; k < 2; ++k) \
;     acc[ai][bj][m][n] = __builtin_amdgcn_mfma_f32_16x16x32_bf16(Bt[n][k], At[m][k], acc[ai][bj][m][n], 0, 0, 0); __builtin_amdgcn_s_setprio(0); } while (0)
; #define PG8_WAIT_V(n) asm volatile("s_waitcnt vmcnt(" #n ")" ::: "memory")
; #define PG8_WAIT_L(n) asm volatile("s_waitcnt lgkmcnt(" #n ")" ::: "memory")
; #define PG8_BAR __builtin_amdgcn_s_barrier()
; #define PG8_SCHED __builtin_amdgcn_sched_barrier(0)
; template <class Epi, class Sched>
; DI void gemm_phase(PG8_LAS unsigned char* lds, const Gemm g, const Sched& S, const Epi& E) {
;     ...
;       PG8_WAIT_V(8); PG8_WAIT_L(0); PG8_BAR; PG8_MMA(1, 0, At, B0); PG8_MMA(1, 1, At, B1); PG8_BAR; PG8_SCHED;
;       PG8_LDB(B0, 1, 0); PG8_LDB(B1, 1, 1); PG8_SCHED; PG8_LDA(At, 1, 0); PG8_STAGE(PG8_SA(0, 1), a2 + hstepA, voffA);
;       PG8_WAIT_V(8); PG8_WAIT_L(0); PG8_BAR; PG8_MMA(0, 0, At, B0); PG8_MMA(0, 1, At, B1); PG8_BAR; PG8_SCHED;
	s_waitcnt lgkmcnt(0)
	v_mfma_f32_16x16x32_bf16 v[60:63], v[144:147], v[198:201], v[60:63]
	v_mfma_f32_16x16x32_bf16 v[56:59], v[174:177], v[198:201], v[56:59]
	v_mfma_f32_16x16x32_bf16 v[44:47], v[144:147], v[206:209], v[44:47]
	v_mfma_f32_16x16x32_bf16 v[40:43], v[174:177], v[206:209], v[40:43]
	v_mfma_f32_16x16x32_bf16 v[28:31], v[144:147], v[218:221], v[28:31]
	v_mfma_f32_16x16x32_bf16 v[24:27], v[174:177], v[218:221], v[24:27]
	v_mfma_f32_16x16x32_bf16 v[12:15], v[144:147], v[226:229], v[12:15]
	v_mfma_f32_16x16x32_bf16 v[8:11], v[174:177], v[226:229], v[8:11]
	v_mfma_f32_16x16x32_bf16 v[60:63], v[156:159], v[202:205], v[60:63]
	v_mfma_f32_16x16x32_bf16 v[56:59], v[178:181], v[202:205], v[56:59]
	v_mfma_f32_16x16x32_bf16 v[44:47], v[156:159], v[214:217], v[44:47]
	v_mfma_f32_16x16x32_bf16 v[40:43], v[178:181], v[214:217], v[40:43]
	v_mfma_f32_16x16x32_bf16 v[28:31], v[156:159], v[222:225], v[28:31]
	v_mfma_f32_16x16x32_bf16 v[24:27], v[178:181], v[222:225], v[24:27]
	v_mfma_f32_16x16x32_bf16 v[12:15], v[156:159], v[230:233], v[12:15]
	v_mfma_f32_16x16x32_bf16 v[8:11], v[178:181], v[230:233], v[8:11]
	v_mfma_f32_16x16x32_bf16 v[52:55], v[182:185], v[198:201], v[52:55]
	v_mfma_f32_16x16x32_bf16 v[48:51], v[190:193], v[198:201], v[48:51]
	v_mfma_f32_16x16x32_bf16 v[36:39], v[182:185], v[206:209], v[36:39]
	v_mfma_f32_16x16x32_bf16 v[32:35], v[190:193], v[206:209], v[32:35]
	v_mfma_f32_16x16x32_bf16 v[20:23], v[182:185], v[218:221], v[20:23]
	v_mfma_f32_16x16x32_bf16 v[16:19], v[190:193], v[218:221], v[16:19]
	v_mfma_f32_16x16x32_bf16 v[4:7], v[182:185], v[226:229], v[4:7]
	v_mfma_f32_16x16x32_bf16 v[0:3], v[190:193], v[226:229], v[0:3]
	v_mfma_f32_16x16x32_bf16 v[52:55], v[186:189], v[202:205], v[52:55]
	v_mfma_f32_16x16x32_bf16 v[48:51], v[194:197], v[202:205], v[48:51]
	v_mfma_f32_16x16x32_bf16 v[36:39], v[186:189], v[214:217], v[36:39]
	v_mfma_f32_16x16x32_bf16 v[32:35], v[194:197], v[214:217], v[32:35]
	v_mfma_f32_16x16x32_bf16 v[20:23], v[186:189], v[222:225], v[20:23]
	v_mfma_f32_16x16x32_bf16 v[16:19], v[194:197], v[222:225], v[16:19]
	v_mfma_f32_16x16x32_bf16 v[4:7], v[186:189], v[230:233], v[4:7]
	v_mfma_f32_16x16x32_bf16 v[0:3], v[194:197], v[230:233], v[0:3]
	s_barrier
	ds_read_b128 v[144:147], v171
	ds_read_b128 v[156:159], v171 offset:1024
	ds_read_b128 v[174:177], v171 offset:2048
	ds_read_b128 v[178:181], v171 offset:3072
	ds_read_b128 v[182:185], v173
	ds_read_b128 v[186:189], v173 offset:1024
	ds_read_b128 v[190:193], v173 offset:2048
	ds_read_b128 v[194:197], v173 offset:3072
	s_add_u32 s34, s34, 0x40000
	s_addc_u32 s35, s35, 0
	s_mov_b32 m0, s5
	v_lshl_add_u64 v[210:211], s[34:35], 0, v[134:135]
	ds_read_b128 v[198:201], v165 offset:32768
	ds_read_b128 v[202:205], v165 offset:33792
	ds_read_b128 v[206:209], v165 offset:34816
	ds_read_b128 v[214:217], v165 offset:35840
	ds_read_b128 v[218:221], v165 offset:36864
	ds_read_b128 v[222:225], v165 offset:37888
	ds_read_b128 v[226:229], v165 offset:38912
	ds_read_b128 v[230:233], v165 offset:39936
	global_load_lds_dwordx4 v[210:211], off
	v_lshl_add_u64 v[210:211], s[34:35], 0, v[130:131]
	s_mov_b32 m0, s19
	s_nop 0
	global_load_lds_dwordx4 v[210:211], off
	s_waitcnt vmcnt(8)
	s_waitcnt lgkmcnt(0)
	s_barrier
	s_waitcnt lgkmcnt(0)
	v_mfma_f32_16x16x32_bf16 v[124:127], v[144:147], v[198:201], v[124:127]
	v_mfma_f32_16x16x32_bf16 v[120:123], v[174:177], v[198:201], v[120:123]
	v_mfma_f32_16x16x32_bf16 v[108:111], v[144:147], v[206:209], v[108:111]
	v_mfma_f32_16x16x32_bf16 v[104:107], v[174:177], v[206:209], v[104:107]
	v_mfma_f32_16x16x32_bf16 v[92:95], v[144:147], v[218:221], v[92:95]
	v_mfma_f32_16x16x32_bf16 v[88:91], v[174:177], v[218:221], v[88:91]
	v_mfma_f32_16x16x32_bf16 v[76:79], v[144:147], v[226:229], v[76:79]
	v_mfma_f32_16x16x32_bf16 v[72:75], v[174:177], v[226:229], v[72:75]
	v_mfma_f32_16x16x32_bf16 v[124:127], v[156:159], v[202:205], v[124:127]
	v_mfma_f32_16x16x32_bf16 v[120:123], v[178:181], v[202:205], v[120:123]
	v_mfma_f32_16x16x32_bf16 v[108:111], v[156:159], v[214:217], v[108:111]
	v_mfma_f32_16x16x32_bf16 v[104:107], v[178:181], v[214:217], v[104:107]
	v_mfma_f32_16x16x32_bf16 v[92:95], v[156:159], v[222:225], v[92:95]
	v_mfma_f32_16x16x32_bf16 v[88:91], v[178:181], v[222:225], v[88:91]
	v_mfma_f32_16x16x32_bf16 v[76:79], v[156:159], v[230:233], v[76:79]
	v_mfma_f32_16x16x32_bf16 v[72:75], v[178:181], v[230:233], v[72:75]
	v_mfma_f32_16x16x32_bf16 v[116:119], v[182:185], v[198:201], v[116:119]
	v_mfma_f32_16x16x32_bf16 v[112:115], v[190:193], v[198:201], v[112:115]
	v_mfma_f32_16x16x32_bf16 v[100:103], v[182:185], v[206:209], v[100:103]
	v_mfma_f32_16x16x32_bf16 v[96:99], v[190:193], v[206:209], v[96:99]
	v_mfma_f32_16x16x32_bf16 v[84:87], v[182:185], v[218:221], v[84:87]
	v_mfma_f32_16x16x32_bf16 v[80:83], v[190:193], v[218:221], v[80:83]
	v_mfma_f32_16x16x32_bf16 v[68:71], v[182:185], v[226:229], v[68:71]
	v_mfma_f32_16x16x32_bf16 v[64:67], v[190:193], v[226:229], v[64:67]
	v_mfma_f32_16x16x32_bf16 v[116:119], v[186:189], v[202:205], v[116:119]
	v_mfma_f32_16x16x32_bf16 v[112:115], v[194:197], v[202:205], v[112:115]
	v_mfma_f32_16x16x32_bf16 v[100:103], v[186:189], v[214:217], v[100:103]
	v_mfma_f32_16x16x32_bf16 v[96:99], v[194:197], v[214:217], v[96:99]
	v_mfma_f32_16x16x32_bf16 v[84:87], v[186:189], v[222:225], v[84:87]
	v_mfma_f32_16x16x32_bf16 v[80:83], v[194:197], v[222:225], v[80:83]
	v_mfma_f32_16x16x32_bf16 v[68:71], v[186:189], v[230:233], v[68:71]
	v_mfma_f32_16x16x32_bf16 v[64:67], v[194:197], v[230:233], v[64:67]
	s_barrier
; #define PG8_STAGE(bufoff, gbase, voff) do { _Pragma("unroll") for (int _i = 0; _i < 2; ++_i) \
;     __builtin_amdgcn_global_load_lds((const unsigned*)((const char*)(gbase) + (voff)[_i]), (PG8_LAS unsigned*)(lds + (bufoff) + ldsw + _i * 8192), 16, 0, 0); } while (0)
; #define PG8_LDA(dst, b, h) do { _Pragma("unroll") for (int m = 0; m < 4; ++m) _Pragma("unroll") for (int k = 0; k < 2; ++k) dst[m][k] = *(const PG8_LAS bf16x8*)(lds + PG8_SA(b, h) + aoff + m * 2048 + k * 1024); } while (0)
; #define PG8_MMA(ai, bj, At, Bt) do { __builtin_amdgcn_s_setprio(1); _Pragma("unroll") for (int m = 0; m < 4; ++m) _Pragma("unroll") for (int n = 0; n < 2; ++n) _Pragma("unroll") for (int k = 0; k < 2; ++k) \
;     acc[ai][bj][m][n] = __builtin_amdgcn_mfma_f32_16x16x32_bf16(Bt[n][k], At[m][k], acc[ai][bj][m][n], 0, 0, 0); __builtin_amdgcn_s_setprio(0); } while (0)
; #define PG8_WAIT_V(n) asm volatile("s_waitcnt vmcnt(" #n ")" ::: "memory")
; #define PG8_WAIT_L(n) asm volatile("s_waitcnt lgkmcnt(" #n ")" ::: "memory")
; #define PG8_BAR __builtin_amdgcn_s_barrier()
; #define PG8_SCHED __builtin_amdgcn_sched_barrier(0)
; DI void rows_rstd(float (&rs)[2][4], const float* ps, const Unit& u, int wr, int fr, int fq, int p_lo, int p_hi, float inv_dim) {
;   f32x4 pv[2][4];
; #pragma unroll
;   for (int ai = 0; ai < 2; ++ai)
; #pragma unroll
;     for (int m = 0; m < 4; ++m) pv[ai][m] = *(const f32x4*)(ps + (size_t)(u.pm * BM + ai * HALF + wr * 64 + m * 16 + fr) * 16 + 4 * fq);
; template <class Epi, class Sched>
; DI void gemm_phase(PG8_LAS unsigned char* lds, const Gemm g, const Sched& S, const Epi& E) {
;     ...
;       PG8_LDA(At, 1, 1); PG8_STAGE(PG8_SB(1, 0), b3, voffB); PG8_STAGE(PG8_SB(1, 1), b3 + hstepB, voffB); PG8_STAGE(PG8_SA(1, 0), a3, voffA);
;       PG8_WAIT_V(8); PG8_WAIT_L(0); PG8_BAR; PG8_MMA(1, 0, At, B0); PG8_MMA(1, 1, At, B1); PG8_BAR; PG8_SCHED;
;     }
;     if (wr == 0) PG8_BAR;
;     E(acc, cur, wr, wc, fr, fq);
	s_add_i32 s34, s41, s15
	v_lshl_add_u64 v[148:149], v[148:149], 0, s[8:9]
	s_mov_b32 m0, s34
	ds_read_b128 v[198:201], v165 offset:49152
	ds_read_b128 v[202:205], v165 offset:50176
	ds_read_b128 v[206:209], v165 offset:51200
	ds_read_b128 v[214:217], v165 offset:52224
	ds_read_b128 v[218:221], v165 offset:53248
	ds_read_b128 v[222:225], v165 offset:54272
	ds_read_b128 v[226:229], v165 offset:55296
	ds_read_b128 v[230:233], v165 offset:56320
	global_load_lds_dwordx4 v[148:149], off
	s_add_i32 m0, s34, 0x2000
	s_add_u32 s30, s30, 0x40080
	v_lshl_add_u64 v[148:149], v[152:153], 0, s[8:9]
	s_addc_u32 s31, s31, 0
	s_add_i32 s34, s44, s15
	global_load_lds_dwordx4 v[148:149], off
	v_lshl_add_u64 v[148:149], s[30:31], 0, v[132:133]
	s_mov_b32 m0, s34
	s_nop 0
	global_load_lds_dwordx4 v[148:149], off
	v_lshl_add_u64 v[148:149], s[30:31], 0, v[128:129]
	s_add_i32 m0, s34, 0x2000
	s_nop 0
	global_load_lds_dwordx4 v[148:149], off
	v_lshl_add_u64 v[148:149], v[162:163], 0, s[8:9]
	s_mov_b32 m0, s33
	s_nop 0
	global_load_lds_dwordx4 v[148:149], off
	v_lshl_add_u64 v[148:149], v[166:167], 0, s[8:9]
	s_mov_b32 m0, s36
	s_nop 0
	global_load_lds_dwordx4 v[148:149], off
	s_waitcnt vmcnt(8)
	s_waitcnt lgkmcnt(0)
	s_barrier
	s_waitcnt lgkmcnt(0)
	v_mfma_f32_16x16x32_bf16 v[60:63], v[144:147], v[198:201], v[60:63]
	v_mfma_f32_16x16x32_bf16 v[56:59], v[174:177], v[198:201], v[56:59]
	v_mfma_f32_16x16x32_bf16 v[44:47], v[144:147], v[206:209], v[44:47]
	v_mfma_f32_16x16x32_bf16 v[40:43], v[174:177], v[206:209], v[40:43]
	v_mfma_f32_16x16x32_bf16 v[28:31], v[144:147], v[218:221], v[28:31]
	v_mfma_f32_16x16x32_bf16 v[24:27], v[174:177], v[218:221], v[24:27]
	v_mfma_f32_16x16x32_bf16 v[12:15], v[144:147], v[226:229], v[12:15]
	v_mfma_f32_16x16x32_bf16 v[8:11], v[174:177], v[226:229], v[8:11]
	v_mfma_f32_16x16x32_bf16 v[60:63], v[156:159], v[202:205], v[60:63]
	v_mfma_f32_16x16x32_bf16 v[56:59], v[178:181], v[202:205], v[56:59]
	v_mfma_f32_16x16x32_bf16 v[44:47], v[156:159], v[214:217], v[44:47]
	v_mfma_f32_16x16x32_bf16 v[40:43], v[178:181], v[214:217], v[40:43]
	v_mfma_f32_16x16x32_bf16 v[28:31], v[156:159], v[222:225], v[28:31]
	v_mfma_f32_16x16x32_bf16 v[24:27], v[178:181], v[222:225], v[24:27]
	v_mfma_f32_16x16x32_bf16 v[12:15], v[156:159], v[230:233], v[12:15]
	v_mfma_f32_16x16x32_bf16 v[8:11], v[178:181], v[230:233], v[8:11]
	v_mfma_f32_16x16x32_bf16 v[52:55], v[182:185], v[198:201], v[52:55]
	v_mfma_f32_16x16x32_bf16 v[48:51], v[190:193], v[198:201], v[48:51]
	v_mfma_f32_16x16x32_bf16 v[36:39], v[182:185], v[206:209], v[36:39]
	v_mfma_f32_16x16x32_bf16 v[32:35], v[190:193], v[206:209], v[32:35]
	v_mfma_f32_16x16x32_bf16 v[20:23], v[182:185], v[218:221], v[20:23]
	v_mfma_f32_16x16x32_bf16 v[16:19], v[190:193], v[218:221], v[16:19]
	v_mfma_f32_16x16x32_bf16 v[4:7], v[182:185], v[226:229], v[4:7]
	v_mfma_f32_16x16x32_bf16 v[0:3], v[190:193], v[226:229], v[0:3]
	v_mfma_f32_16x16x32_bf16 v[52:55], v[186:189], v[202:205], v[52:55]
	v_mfma_f32_16x16x32_bf16 v[48:51], v[194:197], v[202:205], v[48:51]
	v_mfma_f32_16x16x32_bf16 v[36:39], v[186:189], v[214:217], v[36:39]
	v_mfma_f32_16x16x32_bf16 v[32:35], v[194:197], v[214:217], v[32:35]
	v_mfma_f32_16x16x32_bf16 v[20:23], v[186:189], v[222:225], v[20:23]
	v_mfma_f32_16x16x32_bf16 v[16:19], v[194:197], v[222:225], v[16:19]
	v_mfma_f32_16x16x32_bf16 v[4:7], v[186:189], v[230:233], v[4:7]
	v_mfma_f32_16x16x32_bf16 v[0:3], v[194:197], v[230:233], v[0:3]
	s_barrier
	s_add_i32 s55, s55, 2
	s_add_u32 s2, s2, 0x100
	s_addc_u32 s3, s3, 0
	s_add_u32 s53, s53, 0x100
	s_addc_u32 s54, s54, 0
	s_cmp_gt_u32 s55, 13
	s_cbranch_scc0 .LBB0_1384
	v_lshl_add_u32 v166, s0, 8, v151
	v_or_b32_e32 v162, 16, v166
	v_ashrrev_i32_e32 v167, 31, v166
	v_ashrrev_i32_e32 v163, 31, v162
	v_or_b32_e32 v158, 32, v166
	v_lshlrev_b64 v[146:147], 6, v[166:167]
	v_lshlrev_b64 v[144:145], 6, v[162:163]
	v_ashrrev_i32_e32 v159, 31, v158
	v_lshl_add_u64 v[146:147], v[138:139], 0, v[146:147]
	v_or_b32_e32 v156, 48, v166
	v_lshl_add_u64 v[144:145], v[138:139], 0, v[144:145]
	global_load_dwordx4 v[174:177], v[146:147], off
	v_lshlrev_b64 v[146:147], 6, v[158:159]
	v_ashrrev_i32_e32 v157, 31, v156
	v_lshl_add_u64 v[146:147], v[138:139], 0, v[146:147]
	global_load_dwordx4 v[178:181], v[144:145], off
	global_load_dwordx4 v[182:185], v[146:147], off
	v_lshlrev_b64 v[144:145], 6, v[156:157]
	v_lshl_add_u64 v[144:145], v[138:139], 0, v[144:145]
	global_load_dwordx4 v[186:189], v[144:145], off
	v_add_u32_e32 v152, 0x80, v166
	v_ashrrev_i32_e32 v153, 31, v152
	v_lshlrev_b64 v[144:145], 6, v[152:153]
	v_add_u32_e32 v148, 0x90, v166
	v_lshl_add_u64 v[144:145], v[138:139], 0, v[144:145]
	v_ashrrev_i32_e32 v149, 31, v148
	global_load_dwordx4 v[190:193], v[144:145], off
	v_lshlrev_b64 v[144:145], 6, v[148:149]
	v_lshl_add_u64 v[144:145], v[138:139], 0, v[144:145]
	global_load_dwordx4 v[194:197], v[144:145], off
	v_add_u32_e32 v144, 0xb0, v166
	v_ashrrev_i32_e32 v145, 31, v144
	v_lshlrev_b64 v[146:147], 6, v[144:145]
	v_lshl_add_u64 v[146:147], v[138:139], 0, v[146:147]
	global_load_dwordx4 v[198:201], v[146:147], off
	v_and_b32_e32 v147, 64, v169
	v_add_u32_e32 v146, 0xa0, v166
	v_add_u32_e32 v150, 64, v147
	v_ashrrev_i32_e32 v147, 31, v146
	v_lshlrev_b64 v[202:203], 6, v[146:147]
	v_lshl_add_u64 v[202:203], v[138:139], 0, v[202:203]
	global_load_dwordx4 v[202:205], v[202:203], off
	s_and_b64 vcc, exec, s[10:11]
	s_cbranch_vccz .LBB0_1387
	s_barrier

; #define PG8_STAGE(bufoff, gbase, voff) do { _Pragma("unroll") for (int _i = 0; _i < 2; ++_i) \
;     __builtin_amdgcn_global_load_lds((const unsigned*)((const char*)(gbase) + (voff)[_i]), (PG8_LAS unsigned*)(lds + (bufoff) + ldsw + _i * 8192), 16, 0, 0); } while (0)
; #define PG8_LDA(dst, b, h) do { _Pragma("unroll") for (int m = 0; m < 4; ++m) _Pragma("unroll") for (int k = 0; k < 2; ++k) dst[m][k] = *(const PG8_LAS bf16x8*)(lds + PG8_SA(b, h) + aoff + m * 2048 + k * 1024); } while (0)
; #define PG8_LDB(dst, b, h) do { _Pragma("unroll") for (int n = 0; n < 2; ++n) _Pragma("unroll") for (int k = 0; k < 2; ++k) dst[n][k] = *(const PG8_LAS bf16x8*)(lds + PG8_SB(b, h) + boff + n * 2048 + k * 1024); } while (0)
; #define PG8_MMA(ai, bj, At, Bt) do { __builtin_amdgcn_s_setprio(1); _Pragma("unroll") for (int m = 0; m < 4; ++m) _Pragma("unroll") for (int n = 0; n < 2; ++n) _Pragma("unroll") for (int k = 0; k < 2; ++k) \
;     acc[ai][bj][m][n] = __builtin_amdgcn_mfma_f32_16x16x32_bf16(Bt[n][k], At[m][k], acc[ai][bj][m][n], 0, 0, 0); __builtin_amdgcn_s_setprio(0); } while (0)
; #define PG8_WAIT_V(n) asm volatile("s_waitcnt vmcnt(" #n ")" ::: "memory")
; #define PG8_WAIT_L(n) asm volatile("s_waitcnt lgkmcnt(" #n ")" ::: "memory")
; template <class Epi, class Sched>
; DI void gemm_phase(PG8_LAS unsigned char* lds, const Gemm g, const Sched& S, const Epi& E) {
;     ...
;     const char* nA = has_next ? (const char*)g.A + (size_t)nxt.pm * tstepA : cA; const char* nB = has_next ? (const char*)g.Bt + (size_t)nxt.pn * tstepB : cB;
; #pragma unroll 1
;     for (int t = 0; t < nt; t += 2) {
;       const bool last = (t == nt - 2);
;       const char* a1 = cA + (size_t)(t + 1) * kstep;
;       const char* a2 = last ? nA : cA + (size_t)(t + 2) * kstep; const char* b2 = last ? nB : cB + (size_t)(t + 2) * kstep;
;       const char* a3 = a2 + kstep; const char* b3 = b2 + kstep;
;       PG8_LDB(B0, 0, 0); PG8_LDB(B1, 0, 1); PG8_SCHED; PG8_LDA(At, 0, 0); PG8_STAGE(PG8_SA(1, 1), a1 + hstepA, voffA);
;       PG8_WAIT_V(8); PG8_WAIT_L(0); PG8_BAR; PG8_MMA(0, 0, At, B0); PG8_MMA(0, 1, At, B1); PG8_BAR; PG8_SCHED;
;       PG8_LDA(At, 0, 1); PG8_STAGE(PG8_SB(0, 0), b2, voffB); PG8_STAGE(PG8_SB(0, 1), b2 + hstepB, voffB); PG8_STAGE(PG8_SA(0, 0), a2, voffA);
;       PG8_WAIT_V(8); PG8_WAIT_L(0); PG8_BAR; PG8_MMA(1, 0, At, B0); PG8_MMA(1, 1, At, B1); PG8_BAR; PG8_SCHED;
.LBB0_1456:
	ds_read_b128 v[150:153], v145
	ds_read_b128 v[154:157], v145 offset:1024
	ds_read_b128 v[158:161], v145 offset:2048
	ds_read_b128 v[162:165], v145 offset:3072
	ds_read_b128 v[166:169], v146
	ds_read_b128 v[170:173], v146 offset:1024
	ds_read_b128 v[174:177], v146 offset:2048
	ds_read_b128 v[178:181], v146 offset:3072
	s_add_u32 s14, s12, 0x100
	s_addc_u32 s15, s13, 0
	s_cmp_eq_u32 s60, 40
	s_cselect_b32 s19, s9, s15
	s_cselect_b32 s18, s8, s14
	s_cselect_b32 s17, s11, s59
	s_cselect_b32 s16, s10, s58
	s_mov_b32 m0, s49
	v_lshl_add_u64 v[142:143], s[12:13], 0, v[138:139]
	ds_read_b128 v[182:185], v147
	ds_read_b128 v[186:189], v147 offset:1024
	ds_read_b128 v[190:193], v147 offset:2048
	ds_read_b128 v[194:197], v147 offset:3072
	ds_read_b128 v[198:201], v147 offset:4096
	ds_read_b128 v[202:205], v147 offset:5120
	ds_read_b128 v[206:209], v147 offset:6144
	ds_read_b128 v[210:213], v147 offset:7168
	global_load_lds_dwordx4 v[142:143], off
	v_lshl_add_u64 v[142:143], s[12:13], 0, v[140:141]
	s_mov_b32 m0, s52
	s_nop 0
	global_load_lds_dwordx4 v[142:143], off
	s_waitcnt vmcnt(8)
	s_waitcnt lgkmcnt(0)
	s_barrier
	s_waitcnt lgkmcnt(0)
	v_mfma_f32_16x16x32_bf16 v[124:127], v[150:153], v[182:185], v[124:127]
	v_mfma_f32_16x16x32_bf16 v[120:123], v[158:161], v[182:185], v[120:123]
	v_mfma_f32_16x16x32_bf16 v[108:111], v[150:153], v[190:193], v[108:111]
	v_mfma_f32_16x16x32_bf16 v[104:107], v[158:161], v[190:193], v[104:107]
	v_mfma_f32_16x16x32_bf16 v[92:95], v[150:153], v[198:201], v[92:95]
	v_mfma_f32_16x16x32_bf16 v[88:91], v[158:161], v[198:201], v[88:91]
	v_mfma_f32_16x16x32_bf16 v[76:79], v[150:153], v[206:209], v[76:79]
	v_mfma_f32_16x16x32_bf16 v[72:75], v[158:161], v[206:209], v[72:75]
	v_mfma_f32_16x16x32_bf16 v[124:127], v[154:157], v[186:189], v[124:127]
	v_mfma_f32_16x16x32_bf16 v[120:123], v[162:165], v[186:189], v[120:123]
	v_mfma_f32_16x16x32_bf16 v[108:111], v[154:157], v[194:197], v[108:111]
	v_mfma_f32_16x16x32_bf16 v[104:107], v[162:165], v[194:197], v[104:107]
	v_mfma_f32_16x16x32_bf16 v[92:95], v[154:157], v[202:205], v[92:95]
	v_mfma_f32_16x16x32_bf16 v[88:91], v[162:165], v[202:205], v[88:91]
	v_mfma_f32_16x16x32_bf16 v[76:79], v[154:157], v[210:213], v[76:79]
	v_mfma_f32_16x16x32_bf16 v[72:75], v[162:165], v[210:213], v[72:75]
	v_mfma_f32_16x16x32_bf16 v[116:119], v[166:169], v[182:185], v[116:119]
	v_mfma_f32_16x16x32_bf16 v[112:115], v[174:177], v[182:185], v[112:115]
	v_mfma_f32_16x16x32_bf16 v[100:103], v[166:169], v[190:193], v[100:103]
	v_mfma_f32_16x16x32_bf16 v[96:99], v[174:177], v[190:193], v[96:99]
	v_mfma_f32_16x16x32_bf16 v[84:87], v[166:169], v[198:201], v[84:87]
	v_mfma_f32_16x16x32_bf16 v[80:83], v[174:177], v[198:201], v[80:83]
	v_mfma_f32_16x16x32_bf16 v[68:71], v[166:169], v[206:209], v[68:71]
	v_mfma_f32_16x16x32_bf16 v[64:67], v[174:177], v[206:209], v[64:67]
	v_mfma_f32_16x16x32_bf16 v[116:119], v[170:173], v[186:189], v[116:119]
	v_mfma_f32_16x16x32_bf16 v[112:115], v[178:181], v[186:189], v[112:115]
	v_mfma_f32_16x16x32_bf16 v[100:103], v[170:173], v[194:197], v[100:103]
	v_mfma_f32_16x16x32_bf16 v[96:99], v[178:181], v[194:197], v[96:99]
	v_mfma_f32_16x16x32_bf16 v[84:87], v[170:173], v[202:205], v[84:87]
	v_mfma_f32_16x16x32_bf16 v[80:83], v[178:181], v[202:205], v[80:83]
	v_mfma_f32_16x16x32_bf16 v[68:71], v[170:173], v[210:213], v[68:71]
	v_mfma_f32_16x16x32_bf16 v[64:67], v[178:181], v[210:213], v[64:67]
	s_barrier
	s_add_i32 s12, s33, s20
	v_lshl_add_u64 v[142:143], s[16:17], 0, v[132:133]
	s_mov_b32 m0, s12
	ds_read_b128 v[182:185], v147 offset:16384
	ds_read_b128 v[186:189], v147 offset:17408
	ds_read_b128 v[190:193], v147 offset:18432
	ds_read_b128 v[194:197], v147 offset:19456
	ds_read_b128 v[198:201], v147 offset:20480
	ds_read_b128 v[202:205], v147 offset:21504
	ds_read_b128 v[206:209], v147 offset:22528
	ds_read_b128 v[210:213], v147 offset:23552
	global_load_lds_dwordx4 v[142:143], off
	s_add_i32 m0, s12, 0x2000
	s_add_u32 s12, s16, 0xb0000
	v_lshl_add_u64 v[214:215], s[16:17], 0, v[128:129]
	s_addc_u32 s13, s17, 0
	s_add_i32 s61, s34, s20
	global_load_lds_dwordx4 v[214:215], off
	v_lshl_add_u64 v[216:217], s[12:13], 0, v[132:133]
	s_mov_b32 m0, s61
	v_lshl_add_u64 v[218:219], s[18:19], 0, v[130:131]
	global_load_lds_dwordx4 v[216:217], off
	v_lshl_add_u64 v[216:217], s[12:13], 0, v[128:129]
	s_add_i32 m0, s61, 0x2000
	s_nop 0
	global_load_lds_dwordx4 v[216:217], off
	v_lshl_add_u64 v[216:217], s[18:19], 0, v[134:135]
	s_mov_b32 m0, s22
	s_nop 0
	global_load_lds_dwordx4 v[216:217], off
	s_mov_b32 m0, s23
	s_nop 0
	global_load_lds_dwordx4 v[218:219], off
	s_waitcnt vmcnt(8)
	s_waitcnt lgkmcnt(0)
	s_barrier
; #define PG8_STAGE(bufoff, gbase, voff) do { _Pragma("unroll") for (int _i = 0; _i < 2; ++_i) \
;     __builtin_amdgcn_global_load_lds((const unsigned*)((const char*)(gbase) + (voff)[_i]), (PG8_LAS unsigned*)(lds + (bufoff) + ldsw + _i * 8192), 16, 0, 0); } while (0)
; #define PG8_LDA(dst, b, h) do { _Pragma("unroll") for (int m = 0; m < 4; ++m) _Pragma("unroll") for (int k = 0; k < 2; ++k) dst[m][k] = *(const PG8_LAS bf16x8*)(lds + PG8_SA(b, h) + aoff + m * 2048 + k * 1024); } while (0)
; #define PG8_LDB(dst, b, h) do { _Pragma("unroll") for (int n = 0; n < 2; ++n) _Pragma("unroll") for (int k = 0; k < 2; ++k) dst[n][k] = *(const PG8_LAS bf16x8*)(lds + PG8_SB(b, h) + boff + n * 2048 + k * 1024); } while (0)
; #define PG8_MMA(ai, bj, At, Bt) do { __builtin_amdgcn_s_setprio(1); _Pragma("unroll") for (int m = 0; m < 4; ++m) _Pragma("unroll") for (int n = 0; n < 2; ++n) _Pragma("unroll") for (int k = 0; k < 2; ++k) \
;     acc[ai][bj][m][n] = __builtin_amdgcn_mfma_f32_16x16x32_bf16(Bt[n][k], At[m][k], acc[ai][bj][m][n], 0, 0, 0); __builtin_amdgcn_s_setprio(0); } while (0)
; #define PG8_WAIT_V(n) asm volatile("s_waitcnt vmcnt(" #n ")" ::: "memory")
; #define PG8_WAIT_L(n) asm volatile("s_waitcnt lgkmcnt(" #n ")" ::: "memory")
; template <class Epi, class Sched>
; DI void gemm_phase(PG8_LAS unsigned char* lds, const Gemm g, const Sched& S, const Epi& E) {
;     ...
;       PG8_LDB(B0, 0, 0); PG8_LDB(B1, 0, 1); PG8_SCHED; PG8_LDA(At, 0, 0); PG8_STAGE(PG8_SA(1, 1), a1 + hstepA, voffA);
;       PG8_WAIT_V(8); PG8_WAIT_L(0); PG8_BAR; PG8_MMA(0, 0, At, B0); PG8_MMA(0, 1, At, B1); PG8_BAR; PG8_SCHED;
;       PG8_LDA(At, 0, 1); PG8_STAGE(PG8_SB(0, 0), b2, voffB); PG8_STAGE(PG8_SB(0, 1), b2 + hstepB, voffB); PG8_STAGE(PG8_SA(0, 0), a2, voffA);
;       PG8_WAIT_V(8); PG8_WAIT_L(0); PG8_BAR; PG8_MMA(1, 0, At, B0); PG8_MMA(1, 1, At, B1); PG8_BAR; PG8_SCHED;
;       PG8_LDB(B0, 1, 0); PG8_LDB(B1, 1, 1); PG8_SCHED; PG8_LDA(At, 1, 0); PG8_STAGE(PG8_SA(0, 1), a2 + hstepA, voffA);
;       PG8_WAIT_V(8); PG8_WAIT_L(0); PG8_BAR; PG8_MMA(0, 0, At, B0); PG8_MMA(0, 1, At, B1); PG8_BAR; PG8_SCHED;
;       PG8_LDA(At, 1, 1); PG8_STAGE(PG8_SB(1, 0), b3, voffB); PG8_STAGE(PG8_SB(1, 1), b3 + hstepB, voffB); PG8_STAGE(PG8_SA(1, 0), a3, voffA);
;       PG8_WAIT_V(8); PG8_WAIT_L(0); PG8_BAR; PG8_MMA(1, 0, At, B0); PG8_MMA(1, 1, At, B1); PG8_BAR; PG8_SCHED;
	s_waitcnt lgkmcnt(0)
	v_mfma_f32_16x16x32_bf16 v[60:63], v[150:153], v[182:185], v[60:63]
	v_mfma_f32_16x16x32_bf16 v[56:59], v[158:161], v[182:185], v[56:59]
	v_mfma_f32_16x16x32_bf16 v[44:47], v[150:153], v[190:193], v[44:47]
	v_mfma_f32_16x16x32_bf16 v[40:43], v[158:161], v[190:193], v[40:43]
	v_mfma_f32_16x16x32_bf16 v[28:31], v[150:153], v[198:201], v[28:31]
	v_mfma_f32_16x16x32_bf16 v[24:27], v[158:161], v[198:201], v[24:27]
	v_mfma_f32_16x16x32_bf16 v[16:19], v[150:153], v[206:209], v[16:19]
	v_mfma_f32_16x16x32_bf16 v[8:11], v[158:161], v[206:209], v[8:11]
	v_mfma_f32_16x16x32_bf16 v[60:63], v[154:157], v[186:189], v[60:63]
	v_mfma_f32_16x16x32_bf16 v[56:59], v[162:165], v[186:189], v[56:59]
	v_mfma_f32_16x16x32_bf16 v[44:47], v[154:157], v[194:197], v[44:47]
	v_mfma_f32_16x16x32_bf16 v[40:43], v[162:165], v[194:197], v[40:43]
	v_mfma_f32_16x16x32_bf16 v[28:31], v[154:157], v[202:205], v[28:31]
	v_mfma_f32_16x16x32_bf16 v[24:27], v[162:165], v[202:205], v[24:27]
	v_mfma_f32_16x16x32_bf16 v[16:19], v[154:157], v[210:213], v[16:19]
	v_mfma_f32_16x16x32_bf16 v[8:11], v[162:165], v[210:213], v[8:11]
	v_mfma_f32_16x16x32_bf16 v[52:55], v[166:169], v[182:185], v[52:55]
	v_mfma_f32_16x16x32_bf16 v[48:51], v[174:177], v[182:185], v[48:51]
	v_mfma_f32_16x16x32_bf16 v[36:39], v[166:169], v[190:193], v[36:39]
	v_mfma_f32_16x16x32_bf16 v[32:35], v[174:177], v[190:193], v[32:35]
	v_mfma_f32_16x16x32_bf16 v[20:23], v[166:169], v[198:201], v[20:23]
	v_mfma_f32_16x16x32_bf16 v[12:15], v[174:177], v[198:201], v[12:15]
	v_mfma_f32_16x16x32_bf16 v[4:7], v[166:169], v[206:209], v[4:7]
	v_mfma_f32_16x16x32_bf16 v[0:3], v[174:177], v[206:209], v[0:3]
	v_mfma_f32_16x16x32_bf16 v[52:55], v[170:173], v[186:189], v[52:55]
	v_mfma_f32_16x16x32_bf16 v[48:51], v[178:181], v[186:189], v[48:51]
	v_mfma_f32_16x16x32_bf16 v[36:39], v[170:173], v[194:197], v[36:39]
	v_mfma_f32_16x16x32_bf16 v[32:35], v[178:181], v[194:197], v[32:35]
	v_mfma_f32_16x16x32_bf16 v[20:23], v[170:173], v[202:205], v[20:23]
	v_mfma_f32_16x16x32_bf16 v[12:15], v[178:181], v[202:205], v[12:15]
	v_mfma_f32_16x16x32_bf16 v[4:7], v[170:173], v[210:213], v[4:7]
	v_mfma_f32_16x16x32_bf16 v[0:3], v[178:181], v[210:213], v[0:3]
	s_barrier
	s_add_i32 s61, s30, 0x110
	v_add_u32_e32 v149, s61, v144
	ds_read_b128 v[150:153], v149
	ds_read_b128 v[154:157], v149 offset:1024
	ds_read_b128 v[158:161], v149 offset:2048
	ds_read_b128 v[162:165], v149 offset:3072
	ds_read_b128 v[166:169], v148
	ds_read_b128 v[170:173], v148 offset:1024
	ds_read_b128 v[174:177], v148 offset:2048
	ds_read_b128 v[178:181], v148 offset:3072
	s_add_u32 s12, s18, 0xb0000
	s_addc_u32 s13, s19, 0
	s_mov_b32 m0, s24
	v_lshl_add_u64 v[220:221], s[12:13], 0, v[134:135]
	ds_read_b128 v[182:185], v147 offset:32768
	ds_read_b128 v[186:189], v147 offset:33792
	ds_read_b128 v[190:193], v147 offset:34816
	ds_read_b128 v[194:197], v147 offset:35840
	ds_read_b128 v[198:201], v147 offset:36864
	ds_read_b128 v[202:205], v147 offset:37888
	ds_read_b128 v[206:209], v147 offset:38912
	ds_read_b128 v[210:213], v147 offset:39936
	global_load_lds_dwordx4 v[220:221], off
	v_lshl_add_u64 v[220:221], s[12:13], 0, v[130:131]
	s_mov_b32 m0, s25
	s_nop 0
	global_load_lds_dwordx4 v[220:221], off
	s_waitcnt vmcnt(8)
	s_waitcnt lgkmcnt(0)
	s_barrier
	s_waitcnt lgkmcnt(0)
	v_mfma_f32_16x16x32_bf16 v[124:127], v[150:153], v[182:185], v[124:127]
	v_mfma_f32_16x16x32_bf16 v[120:123], v[158:161], v[182:185], v[120:123]
	v_mfma_f32_16x16x32_bf16 v[108:111], v[150:153], v[190:193], v[108:111]
	v_mfma_f32_16x16x32_bf16 v[104:107], v[158:161], v[190:193], v[104:107]
	v_mfma_f32_16x16x32_bf16 v[92:95], v[150:153], v[198:201], v[92:95]
	v_mfma_f32_16x16x32_bf16 v[88:91], v[158:161], v[198:201], v[88:91]
	v_mfma_f32_16x16x32_bf16 v[76:79], v[150:153], v[206:209], v[76:79]
	v_mfma_f32_16x16x32_bf16 v[72:75], v[158:161], v[206:209], v[72:75]
	v_mfma_f32_16x16x32_bf16 v[124:127], v[154:157], v[186:189], v[124:127]
	v_mfma_f32_16x16x32_bf16 v[120:123], v[162:165], v[186:189], v[120:123]
	v_mfma_f32_16x16x32_bf16 v[108:111], v[154:157], v[194:197], v[108:111]
	v_mfma_f32_16x16x32_bf16 v[104:107], v[162:165], v[194:197], v[104:107]
	v_mfma_f32_16x16x32_bf16 v[92:95], v[154:157], v[202:205], v[92:95]
	v_mfma_f32_16x16x32_bf16 v[88:91], v[162:165], v[202:205], v[88:91]
	v_mfma_f32_16x16x32_bf16 v[76:79], v[154:157], v[210:213], v[76:79]
	v_mfma_f32_16x16x32_bf16 v[72:75], v[162:165], v[210:213], v[72:75]
	v_mfma_f32_16x16x32_bf16 v[116:119], v[166:169], v[182:185], v[116:119]
	v_mfma_f32_16x16x32_bf16 v[112:115], v[174:177], v[182:185], v[112:115]
	v_mfma_f32_16x16x32_bf16 v[100:103], v[166:169], v[190:193], v[100:103]
	v_mfma_f32_16x16x32_bf16 v[96:99], v[174:177], v[190:193], v[96:99]
	v_mfma_f32_16x16x32_bf16 v[84:87], v[166:169], v[198:201], v[84:87]
	v_mfma_f32_16x16x32_bf16 v[80:83], v[174:177], v[198:201], v[80:83]
	v_mfma_f32_16x16x32_bf16 v[68:71], v[166:169], v[206:209], v[68:71]
	v_mfma_f32_16x16x32_bf16 v[64:67], v[174:177], v[206:209], v[64:67]
	v_mfma_f32_16x16x32_bf16 v[116:119], v[170:173], v[186:189], v[116:119]
	v_mfma_f32_16x16x32_bf16 v[112:115], v[178:181], v[186:189], v[112:115]
	v_mfma_f32_16x16x32_bf16 v[100:103], v[170:173], v[194:197], v[100:103]
	v_mfma_f32_16x16x32_bf16 v[96:99], v[178:181], v[194:197], v[96:99]
	v_mfma_f32_16x16x32_bf16 v[84:87], v[170:173], v[202:205], v[84:87]
	v_mfma_f32_16x16x32_bf16 v[80:83], v[178:181], v[202:205], v[80:83]
	v_mfma_f32_16x16x32_bf16 v[68:71], v[170:173], v[210:213], v[68:71]
	v_mfma_f32_16x16x32_bf16 v[64:67], v[178:181], v[210:213], v[64:67]
	s_barrier
; #define PG8_STAGE(bufoff, gbase, voff) do { _Pragma("unroll") for (int _i = 0; _i < 2; ++_i) \
;     __builtin_amdgcn_global_load_lds((const unsigned*)((const char*)(gbase) + (voff)[_i]), (PG8_LAS unsigned*)(lds + (bufoff) + ldsw + _i * 8192), 16, 0, 0); } while (0)
; #define PG8_LDA(dst, b, h) do { _Pragma("unroll") for (int m = 0; m < 4; ++m) _Pragma("unroll") for (int k = 0; k < 2; ++k) dst[m][k] = *(const PG8_LAS bf16x8*)(lds + PG8_SA(b, h) + aoff + m * 2048 + k * 1024); } while (0)
; #define PG8_MMA(ai, bj, At, Bt) do { __builtin_amdgcn_s_setprio(1); _Pragma("unroll") for (int m = 0; m < 4; ++m) _Pragma("unroll") for (int n = 0; n < 2; ++n) _Pragma("unroll") for (int k = 0; k < 2; ++k) \
;     acc[ai][bj][m][n] = __builtin_amdgcn_mfma_f32_16x16x32_bf16(Bt[n][k], At[m][k], acc[ai][bj][m][n], 0, 0, 0); __builtin_amdgcn_s_setprio(0); } while (0)
; #define PG8_WAIT_V(n) asm volatile("s_waitcnt vmcnt(" #n ")" ::: "memory")
; #define PG8_WAIT_L(n) asm volatile("s_waitcnt lgkmcnt(" #n ")" ::: "memory")
; #define PG8_BAR __builtin_amdgcn_s_barrier()
; #define PG8_SCHED __builtin_amdgcn_sched_barrier(0)
;   DI void operator()(const f32x4 (&acc)[2][2][4][2], const Unit& u, int wr, int wc, int fr, int fq) const {
;     ...
;     RES_LD(0)
; template <class Epi, class Sched>
; DI void gemm_phase(PG8_LAS unsigned char* lds, const Gemm g, const Sched& S, const Epi& E) {
;     ...
;       PG8_LDA(At, 1, 1); PG8_STAGE(PG8_SB(1, 0), b3, voffB); PG8_STAGE(PG8_SB(1, 1), b3 + hstepB, voffB); PG8_STAGE(PG8_SA(1, 0), a3, voffA);
;       PG8_WAIT_V(8); PG8_WAIT_L(0); PG8_BAR; PG8_MMA(1, 0, At, B0); PG8_MMA(1, 1, At, B1); PG8_BAR; PG8_SCHED;
;     }
;     if (wr == 0) PG8_BAR;
	s_add_i32 s12, s61, s20
	v_lshl_add_u64 v[142:143], v[142:143], 0, s[4:5]
	s_mov_b32 m0, s12
	ds_read_b128 v[182:185], v147 offset:49152
	ds_read_b128 v[186:189], v147 offset:50176
	ds_read_b128 v[190:193], v147 offset:51200
	ds_read_b128 v[194:197], v147 offset:52224
	ds_read_b128 v[198:201], v147 offset:53248
	ds_read_b128 v[202:205], v147 offset:54272
	ds_read_b128 v[206:209], v147 offset:55296
	ds_read_b128 v[210:213], v147 offset:56320
	global_load_lds_dwordx4 v[142:143], off
	s_add_i32 m0, s12, 0x2000
	s_add_u32 s12, s16, 0xb0080
	v_lshl_add_u64 v[142:143], v[214:215], 0, s[4:5]
	s_addc_u32 s13, s17, 0
	s_add_i32 s16, s53, s20
	global_load_lds_dwordx4 v[142:143], off
	v_lshl_add_u64 v[142:143], s[12:13], 0, v[132:133]
	s_mov_b32 m0, s16
	s_nop 0
	global_load_lds_dwordx4 v[142:143], off
	v_lshl_add_u64 v[142:143], s[12:13], 0, v[128:129]
	s_add_i32 m0, s16, 0x2000
	s_nop 0
	global_load_lds_dwordx4 v[142:143], off
	v_lshl_add_u64 v[142:143], v[216:217], 0, s[4:5]
	s_mov_b32 m0, s28
	s_nop 0
	global_load_lds_dwordx4 v[142:143], off
	v_lshl_add_u64 v[142:143], v[218:219], 0, s[4:5]
	s_mov_b32 m0, s29
	s_nop 0
	global_load_lds_dwordx4 v[142:143], off
	s_waitcnt vmcnt(8)
	s_waitcnt lgkmcnt(0)
	s_barrier
	s_waitcnt lgkmcnt(0)
	v_mfma_f32_16x16x32_bf16 v[60:63], v[150:153], v[182:185], v[60:63]
	v_mfma_f32_16x16x32_bf16 v[56:59], v[158:161], v[182:185], v[56:59]
	v_mfma_f32_16x16x32_bf16 v[44:47], v[150:153], v[190:193], v[44:47]
	v_mfma_f32_16x16x32_bf16 v[40:43], v[158:161], v[190:193], v[40:43]
	v_mfma_f32_16x16x32_bf16 v[28:31], v[150:153], v[198:201], v[28:31]
	v_mfma_f32_16x16x32_bf16 v[24:27], v[158:161], v[198:201], v[24:27]
	v_mfma_f32_16x16x32_bf16 v[16:19], v[150:153], v[206:209], v[16:19]
	v_mfma_f32_16x16x32_bf16 v[8:11], v[158:161], v[206:209], v[8:11]
	v_mfma_f32_16x16x32_bf16 v[60:63], v[154:157], v[186:189], v[60:63]
	v_mfma_f32_16x16x32_bf16 v[56:59], v[162:165], v[186:189], v[56:59]
	v_mfma_f32_16x16x32_bf16 v[44:47], v[154:157], v[194:197], v[44:47]
	v_mfma_f32_16x16x32_bf16 v[40:43], v[162:165], v[194:197], v[40:43]
	v_mfma_f32_16x16x32_bf16 v[28:31], v[154:157], v[202:205], v[28:31]
	v_mfma_f32_16x16x32_bf16 v[24:27], v[162:165], v[202:205], v[24:27]
	v_mfma_f32_16x16x32_bf16 v[16:19], v[154:157], v[210:213], v[16:19]
	v_mfma_f32_16x16x32_bf16 v[8:11], v[162:165], v[210:213], v[8:11]
	v_mfma_f32_16x16x32_bf16 v[52:55], v[166:169], v[182:185], v[52:55]
	v_mfma_f32_16x16x32_bf16 v[48:51], v[174:177], v[182:185], v[48:51]
	v_mfma_f32_16x16x32_bf16 v[36:39], v[166:169], v[190:193], v[36:39]
	v_mfma_f32_16x16x32_bf16 v[32:35], v[174:177], v[190:193], v[32:35]
	v_mfma_f32_16x16x32_bf16 v[20:23], v[166:169], v[198:201], v[20:23]
	v_mfma_f32_16x16x32_bf16 v[12:15], v[174:177], v[198:201], v[12:15]
	v_mfma_f32_16x16x32_bf16 v[4:7], v[166:169], v[206:209], v[4:7]
	v_mfma_f32_16x16x32_bf16 v[0:3], v[174:177], v[206:209], v[0:3]
	v_mfma_f32_16x16x32_bf16 v[52:55], v[170:173], v[186:189], v[52:55]
	v_mfma_f32_16x16x32_bf16 v[48:51], v[178:181], v[186:189], v[48:51]
	v_mfma_f32_16x16x32_bf16 v[36:39], v[170:173], v[194:197], v[36:39]
	v_mfma_f32_16x16x32_bf16 v[32:35], v[178:181], v[194:197], v[32:35]
	v_mfma_f32_16x16x32_bf16 v[20:23], v[170:173], v[202:205], v[20:23]
	v_mfma_f32_16x16x32_bf16 v[12:15], v[178:181], v[202:205], v[12:15]
	v_mfma_f32_16x16x32_bf16 v[4:7], v[170:173], v[210:213], v[4:7]
	v_mfma_f32_16x16x32_bf16 v[0:3], v[178:181], v[210:213], v[0:3]
	s_barrier
	s_add_i32 s60, s60, 2
	s_add_u32 s58, s58, 0x100
	s_addc_u32 s59, s59, 0
	s_cmp_gt_u32 s60, 41
	s_mov_b64 s[12:13], s[14:15]
	s_cbranch_scc0 .LBB0_1456
	v_lshl_add_u32 v142, s57, 8, v137
	v_ashrrev_i32_e32 v143, 31, v142
	s_lshl_b32 s12, s56, 8
	v_lshlrev_b64 v[142:143], 10, v[142:143]
	s_ashr_i32 s13, s12, 31
	v_lshl_add_u64 v[166:167], v[142:143], 0, s[12:13]
	v_or_b32_e32 v166, v166, v136
	v_lshl_add_u64 v[142:143], v[166:167], 1, s[50:51]
	v_add_co_u32_e32 v162, vcc, s31, v142
	global_load_dwordx4 v[150:153], v[142:143], off
	global_load_dwordx4 v[154:157], v[142:143], off offset:256
	v_addc_co_u32_e32 v163, vcc, 0, v143, vcc
	global_load_dwordx4 v[158:161], v[162:163], off
	s_nop 0
	global_load_dwordx4 v[162:165], v[162:163], off offset:256
	s_and_b64 vcc, exec, s[6:7]
	s_cbranch_vccz .LBB0_1459
	s_barrier
